# V loop trimmed too: one-pair-ahead index bpermute, merged waits, slice offset folded into the per-unit VGPR offset, out base folded
# baseline (speedup 1.0000x reference)
; DEV void sort_lists(int lane, int& myi0, int& myi1, float& myg0, float& myg1) {
; #pragma unroll
;     for (int k = 2; k <= 128; k <<= 1) {
; #pragma unroll
;       for (int j = k >> 1; j >= 1; j >>= 1) {
;         if (j == 64) {
;           const bool sw_ = myi1 < myi0;
;           const int ti = sw_ ? myi1 : myi0, tj = sw_ ? myi0 : myi1; const float tg = sw_ ? myg1 : myg0, th = sw_ ? myg0 : myg1;
;           myi0 = ti; myi1 = tj; myg0 = tg; myg1 = th;
;         } else {
;           const bool lower = (lane & j) == 0;
;           {
;             const bool up = (k == 128) ? true : ((k == 64) ? true : ((lane & k) == 0));
;             const int oi = __shfl_xor(myi0, j); const float og = __shfl_xor(myg0, j);
;             const bool take = (lower == up) ? (oi < myi0) : (oi > myi0);
;             myi0 = take ? oi : myi0; myg0 = take ? og : myg0;
;           }
;           {
;             const bool up = (k == 128) ? true : ((k == 64) ? false : ((lane & k) == 0));
;             const int oi = __shfl_xor(myi1, j); const float og = __shfl_xor(myg1, j);
;             const bool take = (lower == up) ? (oi < myi1) : (oi > myi1);
;             myi1 = take ? oi : myi1; myg1 = take ? og : myg1;
;           }
;         }
;       }
;     }
; }
; DEV void peer_gather(const Params& P, int l, int m0, const int* idxs, const float* gs) {
;     ...
;   int ni0 = idxs[(wid * 16) * 128 + lane], ni1 = idxs[(wid * 16) * 128 + 64 + lane];
;   float ng0 = gs[(wid * 16) * 128 + lane], ng1 = gs[(wid * 16) * 128 + 64 + lane];
.Lpg0_p0:
	v_readlane_b32 s82, v231, 26
	v_readlane_b32 s83, v231, 27
	s_nop 4
	s_lshl_b32 s98, s2, 2
	s_add_u32 s98, s98, s33
	s_add_u32 s98, s98, 0
	s_lshl_b32 s98, s98, 9
	v_add_u32_e32 v116, s98, v234
	global_load_dword v241, v116, s[82:83]
	global_load_dword v242, v116, s[82:83] offset:256
	s_lshl_b32 s98, s2, 2
	s_add_u32 s98, s98, s33
	s_add_u32 s98, s98, 1
	s_lshl_b32 s98, s98, 9
	v_add_u32_e32 v117, s98, v234
	global_load_dword v243, v117, s[82:83]
	global_load_dword v244, v117, s[82:83] offset:256
	s_lshl_b32 s98, s2, 2
	s_add_u32 s98, s98, s33
	s_add_u32 s98, s98, 2
	s_lshl_b32 s98, s98, 9
	v_add_u32_e32 v118, s98, v234
	global_load_dword v245, v118, s[82:83]
	global_load_dword v246, v118, s[82:83] offset:256
	s_lshl_b32 s98, s2, 2
	s_add_u32 s98, s98, s33
	s_add_u32 s98, s98, 3
	s_lshl_b32 s98, s98, 9
	v_add_u32_e32 v119, s98, v234
	global_load_dword v247, v119, s[82:83]
	global_load_dword v248, v119, s[82:83] offset:256
	s_waitcnt vmcnt(0)
	v_or_b32_e32 v116, 64, v233
	v_lshl_or_b32 v241, v241, 7, v233
	v_lshl_or_b32 v242, v242, 7, v116
	v_lshl_or_b32 v243, v243, 7, v233
	v_lshl_or_b32 v244, v244, 7, v116
	v_lshl_or_b32 v245, v245, 7, v233
	v_lshl_or_b32 v246, v246, 7, v116
	v_lshl_or_b32 v247, v247, 7, v233
	v_lshl_or_b32 v248, v248, 7, v116
	v_xor_b32_e32 v116, 4, v234
	ds_bpermute_b32 v0, v116, v241
	ds_bpermute_b32 v1, v116, v243
	ds_bpermute_b32 v2, v116, v245
	ds_bpermute_b32 v3, v116, v247
	ds_bpermute_b32 v4, v116, v242
	ds_bpermute_b32 v5, v116, v244
	ds_bpermute_b32 v6, v116, v246
	ds_bpermute_b32 v7, v116, v248
	s_waitcnt lgkmcnt(0)
	s_mov_b32 s88, 0x99999999
	s_mov_b32 s89, 0x99999999
	v_min_u32_e32 v104, v241, v0
	v_max_u32_e32 v105, v241, v0
	v_cndmask_b32_e64 v241, v105, v104, s[88:89]
	v_min_u32_e32 v106, v243, v1
	v_max_u32_e32 v107, v243, v1
	v_cndmask_b32_e64 v243, v107, v106, s[88:89]
	v_min_u32_e32 v104, v245, v2
	v_max_u32_e32 v105, v245, v2
	v_cndmask_b32_e64 v245, v105, v104, s[88:89]
	v_min_u32_e32 v106, v247, v3
	v_max_u32_e32 v107, v247, v3
	v_cndmask_b32_e64 v247, v107, v106, s[88:89]
	v_min_u32_e32 v104, v242, v4
	v_max_u32_e32 v105, v242, v4
	v_cndmask_b32_e64 v242, v105, v104, s[88:89]
	v_min_u32_e32 v106, v244, v5
	v_max_u32_e32 v107, v244, v5
	v_cndmask_b32_e64 v244, v107, v106, s[88:89]
	v_min_u32_e32 v104, v246, v6
	v_max_u32_e32 v105, v246, v6
	v_cndmask_b32_e64 v246, v105, v104, s[88:89]
	v_min_u32_e32 v106, v248, v7
	v_max_u32_e32 v107, v248, v7
	v_cndmask_b32_e64 v248, v107, v106, s[88:89]
	v_xor_b32_e32 v116, 8, v234
	ds_bpermute_b32 v0, v116, v241
	ds_bpermute_b32 v1, v116, v243
	ds_bpermute_b32 v2, v116, v245
	ds_bpermute_b32 v3, v116, v247
	ds_bpermute_b32 v4, v116, v242
	ds_bpermute_b32 v5, v116, v244
	ds_bpermute_b32 v6, v116, v246
	ds_bpermute_b32 v7, v116, v248
	s_waitcnt lgkmcnt(0)
	s_mov_b32 s88, 0xc3c3c3c3
	s_mov_b32 s89, 0xc3c3c3c3
	v_min_u32_e32 v104, v241, v0
	v_max_u32_e32 v105, v241, v0
	v_cndmask_b32_e64 v241, v105, v104, s[88:89]
	v_min_u32_e32 v106, v243, v1
	v_max_u32_e32 v107, v243, v1
	v_cndmask_b32_e64 v243, v107, v106, s[88:89]
	v_min_u32_e32 v104, v245, v2
	v_max_u32_e32 v105, v245, v2
	v_cndmask_b32_e64 v245, v105, v104, s[88:89]
	v_min_u32_e32 v106, v247, v3
	v_max_u32_e32 v107, v247, v3
	v_cndmask_b32_e64 v247, v107, v106, s[88:89]
	v_min_u32_e32 v104, v242, v4
	v_max_u32_e32 v105, v242, v4
	v_cndmask_b32_e64 v242, v105, v104, s[88:89]
	v_min_u32_e32 v106, v244, v5
	v_max_u32_e32 v107, v244, v5
	v_cndmask_b32_e64 v244, v107, v106, s[88:89]
	v_min_u32_e32 v104, v246, v6
	v_max_u32_e32 v105, v246, v6
	v_cndmask_b32_e64 v246, v105, v104, s[88:89]
	v_min_u32_e32 v106, v248, v7
	v_max_u32_e32 v107, v248, v7
	v_cndmask_b32_e64 v248, v107, v106, s[88:89]
	v_xor_b32_e32 v116, 4, v234
	ds_bpermute_b32 v0, v116, v241
	ds_bpermute_b32 v1, v116, v243
	ds_bpermute_b32 v2, v116, v245
	ds_bpermute_b32 v3, v116, v247
	ds_bpermute_b32 v4, v116, v242
	ds_bpermute_b32 v5, v116, v244
	ds_bpermute_b32 v6, v116, v246
	ds_bpermute_b32 v7, v116, v248
	s_waitcnt lgkmcnt(0)
	s_mov_b32 s88, 0xa5a5a5a5
	s_mov_b32 s89, 0xa5a5a5a5
	v_min_u32_e32 v104, v241, v0
	v_max_u32_e32 v105, v241, v0
	v_cndmask_b32_e64 v241, v105, v104, s[88:89]
	v_min_u32_e32 v106, v243, v1
	v_max_u32_e32 v107, v243, v1
	v_cndmask_b32_e64 v243, v107, v106, s[88:89]
	v_min_u32_e32 v104, v245, v2
	v_max_u32_e32 v105, v245, v2
	v_cndmask_b32_e64 v245, v105, v104, s[88:89]
	v_min_u32_e32 v106, v247, v3
	v_max_u32_e32 v107, v247, v3
	v_cndmask_b32_e64 v247, v107, v106, s[88:89]
	v_min_u32_e32 v104, v242, v4
	v_max_u32_e32 v105, v242, v4
	v_cndmask_b32_e64 v242, v105, v104, s[88:89]
	v_min_u32_e32 v106, v244, v5
	v_max_u32_e32 v107, v244, v5
	v_cndmask_b32_e64 v244, v107, v106, s[88:89]
	v_min_u32_e32 v104, v246, v6
	v_max_u32_e32 v105, v246, v6
	v_cndmask_b32_e64 v246, v105, v104, s[88:89]
	v_min_u32_e32 v106, v248, v7
	v_max_u32_e32 v107, v248, v7
	v_cndmask_b32_e64 v248, v107, v106, s[88:89]
	v_xor_b32_e32 v116, 16, v234
	ds_bpermute_b32 v0, v116, v241
	ds_bpermute_b32 v1, v116, v243
	ds_bpermute_b32 v2, v116, v245
	ds_bpermute_b32 v3, v116, v247
	ds_bpermute_b32 v4, v116, v242
	ds_bpermute_b32 v5, v116, v244
	ds_bpermute_b32 v6, v116, v246
	ds_bpermute_b32 v7, v116, v248
	s_waitcnt lgkmcnt(0)
; DEV void sort_lists(int lane, int& myi0, int& myi1, float& myg0, float& myg1) {
; #pragma unroll
;     for (int k = 2; k <= 128; k <<= 1) {
; #pragma unroll
;       for (int j = k >> 1; j >= 1; j >>= 1) {
;         if (j == 64) {
;           const bool sw_ = myi1 < myi0;
;           const int ti = sw_ ? myi1 : myi0, tj = sw_ ? myi0 : myi1; const float tg = sw_ ? myg1 : myg0, th = sw_ ? myg0 : myg1;
;           myi0 = ti; myi1 = tj; myg0 = tg; myg1 = th;
;         } else {
;           const bool lower = (lane & j) == 0;
;           {
;             const bool up = (k == 128) ? true : ((k == 64) ? true : ((lane & k) == 0));
;             const int oi = __shfl_xor(myi0, j); const float og = __shfl_xor(myg0, j);
;             const bool take = (lower == up) ? (oi < myi0) : (oi > myi0);
;             myi0 = take ? oi : myi0; myg0 = take ? og : myg0;
;           }
;           {
;             const bool up = (k == 128) ? true : ((k == 64) ? false : ((lane & k) == 0));
;             const int oi = __shfl_xor(myi1, j); const float og = __shfl_xor(myg1, j);
;             const bool take = (lower == up) ? (oi < myi1) : (oi > myi1);
;             myi1 = take ? oi : myi1; myg1 = take ? og : myg1;
;           }
;         }
;       }
;     }
; }
	s_mov_b32 s88, 0xf00ff00f
	s_mov_b32 s89, 0xf00ff00f
	v_min_u32_e32 v104, v241, v0
	v_max_u32_e32 v105, v241, v0
	v_cndmask_b32_e64 v241, v105, v104, s[88:89]
	v_min_u32_e32 v106, v243, v1
	v_max_u32_e32 v107, v243, v1
	v_cndmask_b32_e64 v243, v107, v106, s[88:89]
	v_min_u32_e32 v104, v245, v2
	v_max_u32_e32 v105, v245, v2
	v_cndmask_b32_e64 v245, v105, v104, s[88:89]
	v_min_u32_e32 v106, v247, v3
	v_max_u32_e32 v107, v247, v3
	v_cndmask_b32_e64 v247, v107, v106, s[88:89]
	v_min_u32_e32 v104, v242, v4
	v_max_u32_e32 v105, v242, v4
	v_cndmask_b32_e64 v242, v105, v104, s[88:89]
	v_min_u32_e32 v106, v244, v5
	v_max_u32_e32 v107, v244, v5
	v_cndmask_b32_e64 v244, v107, v106, s[88:89]
	v_min_u32_e32 v104, v246, v6
	v_max_u32_e32 v105, v246, v6
	v_cndmask_b32_e64 v246, v105, v104, s[88:89]
	v_min_u32_e32 v106, v248, v7
	v_max_u32_e32 v107, v248, v7
	v_cndmask_b32_e64 v248, v107, v106, s[88:89]
	v_xor_b32_e32 v116, 8, v234
	ds_bpermute_b32 v0, v116, v241
	ds_bpermute_b32 v1, v116, v243
	ds_bpermute_b32 v2, v116, v245
	ds_bpermute_b32 v3, v116, v247
	ds_bpermute_b32 v4, v116, v242
	ds_bpermute_b32 v5, v116, v244
	ds_bpermute_b32 v6, v116, v246
	ds_bpermute_b32 v7, v116, v248
	s_waitcnt lgkmcnt(0)
	s_mov_b32 s88, 0xcc33cc33
	s_mov_b32 s89, 0xcc33cc33
	v_min_u32_e32 v104, v241, v0
	v_max_u32_e32 v105, v241, v0
	v_cndmask_b32_e64 v241, v105, v104, s[88:89]
	v_min_u32_e32 v106, v243, v1
	v_max_u32_e32 v107, v243, v1
	v_cndmask_b32_e64 v243, v107, v106, s[88:89]
	v_min_u32_e32 v104, v245, v2
	v_max_u32_e32 v105, v245, v2
	v_cndmask_b32_e64 v245, v105, v104, s[88:89]
	v_min_u32_e32 v106, v247, v3
	v_max_u32_e32 v107, v247, v3
	v_cndmask_b32_e64 v247, v107, v106, s[88:89]
	v_min_u32_e32 v104, v242, v4
	v_max_u32_e32 v105, v242, v4
	v_cndmask_b32_e64 v242, v105, v104, s[88:89]
	v_min_u32_e32 v106, v244, v5
	v_max_u32_e32 v107, v244, v5
	v_cndmask_b32_e64 v244, v107, v106, s[88:89]
	v_min_u32_e32 v104, v246, v6
	v_max_u32_e32 v105, v246, v6
	v_cndmask_b32_e64 v246, v105, v104, s[88:89]
	v_min_u32_e32 v106, v248, v7
	v_max_u32_e32 v107, v248, v7
	v_cndmask_b32_e64 v248, v107, v106, s[88:89]
	v_xor_b32_e32 v116, 4, v234
	ds_bpermute_b32 v0, v116, v241
	ds_bpermute_b32 v1, v116, v243
	ds_bpermute_b32 v2, v116, v245
	ds_bpermute_b32 v3, v116, v247
	ds_bpermute_b32 v4, v116, v242
	ds_bpermute_b32 v5, v116, v244
	ds_bpermute_b32 v6, v116, v246
	ds_bpermute_b32 v7, v116, v248
	s_waitcnt lgkmcnt(0)
	s_mov_b32 s88, 0xaa55aa55
	s_mov_b32 s89, 0xaa55aa55
	v_min_u32_e32 v104, v241, v0
	v_max_u32_e32 v105, v241, v0
	v_cndmask_b32_e64 v241, v105, v104, s[88:89]
	v_min_u32_e32 v106, v243, v1
	v_max_u32_e32 v107, v243, v1
	v_cndmask_b32_e64 v243, v107, v106, s[88:89]
	v_min_u32_e32 v104, v245, v2
	v_max_u32_e32 v105, v245, v2
	v_cndmask_b32_e64 v245, v105, v104, s[88:89]
	v_min_u32_e32 v106, v247, v3
	v_max_u32_e32 v107, v247, v3
	v_cndmask_b32_e64 v247, v107, v106, s[88:89]
	v_min_u32_e32 v104, v242, v4
	v_max_u32_e32 v105, v242, v4
	v_cndmask_b32_e64 v242, v105, v104, s[88:89]
	v_min_u32_e32 v106, v244, v5
	v_max_u32_e32 v107, v244, v5
	v_cndmask_b32_e64 v244, v107, v106, s[88:89]
	v_min_u32_e32 v104, v246, v6
	v_max_u32_e32 v105, v246, v6
	v_cndmask_b32_e64 v246, v105, v104, s[88:89]
	v_min_u32_e32 v106, v248, v7
	v_max_u32_e32 v107, v248, v7
	v_cndmask_b32_e64 v248, v107, v106, s[88:89]
	v_xor_b32_e32 v116, 32, v234
	ds_bpermute_b32 v0, v116, v241
	ds_bpermute_b32 v1, v116, v243
	ds_bpermute_b32 v2, v116, v245
	ds_bpermute_b32 v3, v116, v247
	ds_bpermute_b32 v4, v116, v242
	ds_bpermute_b32 v5, v116, v244
	ds_bpermute_b32 v6, v116, v246
	ds_bpermute_b32 v7, v116, v248
	s_waitcnt lgkmcnt(0)
	s_mov_b32 s88, 0xff0000ff
	s_mov_b32 s89, 0xff0000ff
	v_min_u32_e32 v104, v241, v0
	v_max_u32_e32 v105, v241, v0
	v_cndmask_b32_e64 v241, v105, v104, s[88:89]
	v_min_u32_e32 v106, v243, v1
	v_max_u32_e32 v107, v243, v1
	v_cndmask_b32_e64 v243, v107, v106, s[88:89]
	v_min_u32_e32 v104, v245, v2
	v_max_u32_e32 v105, v245, v2
	v_cndmask_b32_e64 v245, v105, v104, s[88:89]
	v_min_u32_e32 v106, v247, v3
	v_max_u32_e32 v107, v247, v3
	v_cndmask_b32_e64 v247, v107, v106, s[88:89]
	v_min_u32_e32 v104, v242, v4
	v_max_u32_e32 v105, v242, v4
	v_cndmask_b32_e64 v242, v105, v104, s[88:89]
	v_min_u32_e32 v106, v244, v5
	v_max_u32_e32 v107, v244, v5
	v_cndmask_b32_e64 v244, v107, v106, s[88:89]
	v_min_u32_e32 v104, v246, v6
	v_max_u32_e32 v105, v246, v6
	v_cndmask_b32_e64 v246, v105, v104, s[88:89]
	v_min_u32_e32 v106, v248, v7
	v_max_u32_e32 v107, v248, v7
	v_cndmask_b32_e64 v248, v107, v106, s[88:89]
	v_xor_b32_e32 v116, 16, v234
	ds_bpermute_b32 v0, v116, v241
	ds_bpermute_b32 v1, v116, v243
	ds_bpermute_b32 v2, v116, v245
	ds_bpermute_b32 v3, v116, v247
	ds_bpermute_b32 v4, v116, v242
	ds_bpermute_b32 v5, v116, v244
	ds_bpermute_b32 v6, v116, v246
	ds_bpermute_b32 v7, v116, v248
	s_waitcnt lgkmcnt(0)
	s_mov_b32 s88, 0xf0f00f0f
	s_mov_b32 s89, 0xf0f00f0f
	v_min_u32_e32 v104, v241, v0
	v_max_u32_e32 v105, v241, v0
	v_cndmask_b32_e64 v241, v105, v104, s[88:89]
	v_min_u32_e32 v106, v243, v1
	v_max_u32_e32 v107, v243, v1
	v_cndmask_b32_e64 v243, v107, v106, s[88:89]
	v_min_u32_e32 v104, v245, v2
	v_max_u32_e32 v105, v245, v2
	v_cndmask_b32_e64 v245, v105, v104, s[88:89]
	v_min_u32_e32 v106, v247, v3
	v_max_u32_e32 v107, v247, v3
	v_cndmask_b32_e64 v247, v107, v106, s[88:89]
	v_min_u32_e32 v104, v242, v4
	v_max_u32_e32 v105, v242, v4
	v_cndmask_b32_e64 v242, v105, v104, s[88:89]
	v_min_u32_e32 v106, v244, v5
	v_max_u32_e32 v107, v244, v5
	v_cndmask_b32_e64 v244, v107, v106, s[88:89]
	v_min_u32_e32 v104, v246, v6
	v_max_u32_e32 v105, v246, v6
	v_cndmask_b32_e64 v246, v105, v104, s[88:89]
	v_min_u32_e32 v106, v248, v7
	v_max_u32_e32 v107, v248, v7
	v_cndmask_b32_e64 v248, v107, v106, s[88:89]
	v_xor_b32_e32 v116, 8, v234
	ds_bpermute_b32 v0, v116, v241
	ds_bpermute_b32 v1, v116, v243
	ds_bpermute_b32 v2, v116, v245
	ds_bpermute_b32 v3, v116, v247
	ds_bpermute_b32 v4, v116, v242
	ds_bpermute_b32 v5, v116, v244
	ds_bpermute_b32 v6, v116, v246
	ds_bpermute_b32 v7, v116, v248
	s_waitcnt lgkmcnt(0)
; DEV void sort_lists(int lane, int& myi0, int& myi1, float& myg0, float& myg1) {
; #pragma unroll
;     for (int k = 2; k <= 128; k <<= 1) {
; #pragma unroll
;       for (int j = k >> 1; j >= 1; j >>= 1) {
;         if (j == 64) {
;           const bool sw_ = myi1 < myi0;
;           const int ti = sw_ ? myi1 : myi0, tj = sw_ ? myi0 : myi1; const float tg = sw_ ? myg1 : myg0, th = sw_ ? myg0 : myg1;
;           myi0 = ti; myi1 = tj; myg0 = tg; myg1 = th;
;         } else {
;           const bool lower = (lane & j) == 0;
;           {
;             const bool up = (k == 128) ? true : ((k == 64) ? true : ((lane & k) == 0));
;             const int oi = __shfl_xor(myi0, j); const float og = __shfl_xor(myg0, j);
;             const bool take = (lower == up) ? (oi < myi0) : (oi > myi0);
;             myi0 = take ? oi : myi0; myg0 = take ? og : myg0;
;           }
;           {
;             const bool up = (k == 128) ? true : ((k == 64) ? false : ((lane & k) == 0));
;             const int oi = __shfl_xor(myi1, j); const float og = __shfl_xor(myg1, j);
;             const bool take = (lower == up) ? (oi < myi1) : (oi > myi1);
;             myi1 = take ? oi : myi1; myg1 = take ? og : myg1;
;           }
;         }
;       }
;     }
; }
	s_mov_b32 s88, 0xcccc3333
	s_mov_b32 s89, 0xcccc3333
	v_min_u32_e32 v104, v241, v0
	v_max_u32_e32 v105, v241, v0
	v_cndmask_b32_e64 v241, v105, v104, s[88:89]
	v_min_u32_e32 v106, v243, v1
	v_max_u32_e32 v107, v243, v1
	v_cndmask_b32_e64 v243, v107, v106, s[88:89]
	v_min_u32_e32 v104, v245, v2
	v_max_u32_e32 v105, v245, v2
	v_cndmask_b32_e64 v245, v105, v104, s[88:89]
	v_min_u32_e32 v106, v247, v3
	v_max_u32_e32 v107, v247, v3
	v_cndmask_b32_e64 v247, v107, v106, s[88:89]
	v_min_u32_e32 v104, v242, v4
	v_max_u32_e32 v105, v242, v4
	v_cndmask_b32_e64 v242, v105, v104, s[88:89]
	v_min_u32_e32 v106, v244, v5
	v_max_u32_e32 v107, v244, v5
	v_cndmask_b32_e64 v244, v107, v106, s[88:89]
	v_min_u32_e32 v104, v246, v6
	v_max_u32_e32 v105, v246, v6
	v_cndmask_b32_e64 v246, v105, v104, s[88:89]
	v_min_u32_e32 v106, v248, v7
	v_max_u32_e32 v107, v248, v7
	v_cndmask_b32_e64 v248, v107, v106, s[88:89]
	v_xor_b32_e32 v116, 4, v234
	ds_bpermute_b32 v0, v116, v241
	ds_bpermute_b32 v1, v116, v243
	ds_bpermute_b32 v2, v116, v245
	ds_bpermute_b32 v3, v116, v247
	ds_bpermute_b32 v4, v116, v242
	ds_bpermute_b32 v5, v116, v244
	ds_bpermute_b32 v6, v116, v246
	ds_bpermute_b32 v7, v116, v248
	s_waitcnt lgkmcnt(0)
	s_mov_b32 s88, 0xaaaa5555
	s_mov_b32 s89, 0xaaaa5555
	v_min_u32_e32 v104, v241, v0
	v_max_u32_e32 v105, v241, v0
	v_cndmask_b32_e64 v241, v105, v104, s[88:89]
	v_min_u32_e32 v106, v243, v1
	v_max_u32_e32 v107, v243, v1
	v_cndmask_b32_e64 v243, v107, v106, s[88:89]
	v_min_u32_e32 v104, v245, v2
	v_max_u32_e32 v105, v245, v2
	v_cndmask_b32_e64 v245, v105, v104, s[88:89]
	v_min_u32_e32 v106, v247, v3
	v_max_u32_e32 v107, v247, v3
	v_cndmask_b32_e64 v247, v107, v106, s[88:89]
	v_min_u32_e32 v104, v242, v4
	v_max_u32_e32 v105, v242, v4
	v_cndmask_b32_e64 v242, v105, v104, s[88:89]
	v_min_u32_e32 v106, v244, v5
	v_max_u32_e32 v107, v244, v5
	v_cndmask_b32_e64 v244, v107, v106, s[88:89]
	v_min_u32_e32 v104, v246, v6
	v_max_u32_e32 v105, v246, v6
	v_cndmask_b32_e64 v246, v105, v104, s[88:89]
	v_min_u32_e32 v106, v248, v7
	v_max_u32_e32 v107, v248, v7
	v_cndmask_b32_e64 v248, v107, v106, s[88:89]
	v_xor_b32_e32 v116, 64, v234
	ds_bpermute_b32 v0, v116, v241
	ds_bpermute_b32 v1, v116, v243
	ds_bpermute_b32 v2, v116, v245
	ds_bpermute_b32 v3, v116, v247
	ds_bpermute_b32 v4, v116, v242
	ds_bpermute_b32 v5, v116, v244
	ds_bpermute_b32 v6, v116, v246
	ds_bpermute_b32 v7, v116, v248
	s_waitcnt lgkmcnt(0)
	s_mov_b32 s88, 0xffff
	s_mov_b32 s89, 0xffff0000
	v_min_u32_e32 v104, v241, v0
	v_max_u32_e32 v105, v241, v0
	v_cndmask_b32_e64 v241, v105, v104, s[88:89]
	v_min_u32_e32 v106, v243, v1
	v_max_u32_e32 v107, v243, v1
	v_cndmask_b32_e64 v243, v107, v106, s[88:89]
	v_min_u32_e32 v104, v245, v2
	v_max_u32_e32 v105, v245, v2
	v_cndmask_b32_e64 v245, v105, v104, s[88:89]
	v_min_u32_e32 v106, v247, v3
	v_max_u32_e32 v107, v247, v3
	v_cndmask_b32_e64 v247, v107, v106, s[88:89]
	v_min_u32_e32 v104, v242, v4
	v_max_u32_e32 v105, v242, v4
	v_cndmask_b32_e64 v242, v105, v104, s[88:89]
	v_min_u32_e32 v106, v244, v5
	v_max_u32_e32 v107, v244, v5
	v_cndmask_b32_e64 v244, v107, v106, s[88:89]
	v_min_u32_e32 v104, v246, v6
	v_max_u32_e32 v105, v246, v6
	v_cndmask_b32_e64 v246, v105, v104, s[88:89]
	v_min_u32_e32 v106, v248, v7
	v_max_u32_e32 v107, v248, v7
	v_cndmask_b32_e64 v248, v107, v106, s[88:89]
	v_xor_b32_e32 v116, 32, v234
	ds_bpermute_b32 v0, v116, v241
	ds_bpermute_b32 v1, v116, v243
	ds_bpermute_b32 v2, v116, v245
	ds_bpermute_b32 v3, v116, v247
	ds_bpermute_b32 v4, v116, v242
	ds_bpermute_b32 v5, v116, v244
	ds_bpermute_b32 v6, v116, v246
	ds_bpermute_b32 v7, v116, v248
	s_waitcnt lgkmcnt(0)
	s_mov_b32 s88, 0xff00ff
	s_mov_b32 s89, 0xff00ff00
	v_min_u32_e32 v104, v241, v0
	v_max_u32_e32 v105, v241, v0
	v_cndmask_b32_e64 v241, v105, v104, s[88:89]
	v_min_u32_e32 v106, v243, v1
	v_max_u32_e32 v107, v243, v1
	v_cndmask_b32_e64 v243, v107, v106, s[88:89]
	v_min_u32_e32 v104, v245, v2
	v_max_u32_e32 v105, v245, v2
	v_cndmask_b32_e64 v245, v105, v104, s[88:89]
	v_min_u32_e32 v106, v247, v3
	v_max_u32_e32 v107, v247, v3
	v_cndmask_b32_e64 v247, v107, v106, s[88:89]
	v_min_u32_e32 v104, v242, v4
	v_max_u32_e32 v105, v242, v4
	v_cndmask_b32_e64 v242, v105, v104, s[88:89]
	v_min_u32_e32 v106, v244, v5
	v_max_u32_e32 v107, v244, v5
	v_cndmask_b32_e64 v244, v107, v106, s[88:89]
	v_min_u32_e32 v104, v246, v6
	v_max_u32_e32 v105, v246, v6
	v_cndmask_b32_e64 v246, v105, v104, s[88:89]
	v_min_u32_e32 v106, v248, v7
	v_max_u32_e32 v107, v248, v7
	v_cndmask_b32_e64 v248, v107, v106, s[88:89]
	v_xor_b32_e32 v116, 16, v234
	ds_bpermute_b32 v0, v116, v241
	ds_bpermute_b32 v1, v116, v243
	ds_bpermute_b32 v2, v116, v245
	ds_bpermute_b32 v3, v116, v247
	ds_bpermute_b32 v4, v116, v242
	ds_bpermute_b32 v5, v116, v244
	ds_bpermute_b32 v6, v116, v246
	ds_bpermute_b32 v7, v116, v248
	s_waitcnt lgkmcnt(0)
	s_mov_b32 s88, 0xf0f0f0f
	s_mov_b32 s89, 0xf0f0f0f0
	v_min_u32_e32 v104, v241, v0
	v_max_u32_e32 v105, v241, v0
	v_cndmask_b32_e64 v241, v105, v104, s[88:89]
	v_min_u32_e32 v106, v243, v1
	v_max_u32_e32 v107, v243, v1
	v_cndmask_b32_e64 v243, v107, v106, s[88:89]
	v_min_u32_e32 v104, v245, v2
	v_max_u32_e32 v105, v245, v2
	v_cndmask_b32_e64 v245, v105, v104, s[88:89]
	v_min_u32_e32 v106, v247, v3
	v_max_u32_e32 v107, v247, v3
	v_cndmask_b32_e64 v247, v107, v106, s[88:89]
	v_min_u32_e32 v104, v242, v4
	v_max_u32_e32 v105, v242, v4
	v_cndmask_b32_e64 v242, v105, v104, s[88:89]
	v_min_u32_e32 v106, v244, v5
	v_max_u32_e32 v107, v244, v5
	v_cndmask_b32_e64 v244, v107, v106, s[88:89]
	v_min_u32_e32 v104, v246, v6
	v_max_u32_e32 v105, v246, v6
	v_cndmask_b32_e64 v246, v105, v104, s[88:89]
	v_min_u32_e32 v106, v248, v7
	v_max_u32_e32 v107, v248, v7
	v_cndmask_b32_e64 v248, v107, v106, s[88:89]
	v_xor_b32_e32 v116, 8, v234
	ds_bpermute_b32 v0, v116, v241
	ds_bpermute_b32 v1, v116, v243
	ds_bpermute_b32 v2, v116, v245
	ds_bpermute_b32 v3, v116, v247
	ds_bpermute_b32 v4, v116, v242
	ds_bpermute_b32 v5, v116, v244
	ds_bpermute_b32 v6, v116, v246
	ds_bpermute_b32 v7, v116, v248
	s_waitcnt lgkmcnt(0)
; DEV void sort_lists(int lane, int& myi0, int& myi1, float& myg0, float& myg1) {
; #pragma unroll
;     for (int k = 2; k <= 128; k <<= 1) {
; #pragma unroll
;       for (int j = k >> 1; j >= 1; j >>= 1) {
;         if (j == 64) {
;           const bool sw_ = myi1 < myi0;
;           const int ti = sw_ ? myi1 : myi0, tj = sw_ ? myi0 : myi1; const float tg = sw_ ? myg1 : myg0, th = sw_ ? myg0 : myg1;
;           myi0 = ti; myi1 = tj; myg0 = tg; myg1 = th;
;         } else {
;           const bool lower = (lane & j) == 0;
;           {
;             const bool up = (k == 128) ? true : ((k == 64) ? true : ((lane & k) == 0));
;             const int oi = __shfl_xor(myi0, j); const float og = __shfl_xor(myg0, j);
;             const bool take = (lower == up) ? (oi < myi0) : (oi > myi0);
;             myi0 = take ? oi : myi0; myg0 = take ? og : myg0;
;           }
;           {
;             const bool up = (k == 128) ? true : ((k == 64) ? false : ((lane & k) == 0));
;             const int oi = __shfl_xor(myi1, j); const float og = __shfl_xor(myg1, j);
;             const bool take = (lower == up) ? (oi < myi1) : (oi > myi1);
;             myi1 = take ? oi : myi1; myg1 = take ? og : myg1;
;           }
;         }
;       }
;     }
; }
	s_mov_b32 s88, 0x33333333
	s_mov_b32 s89, 0xcccccccc
	v_min_u32_e32 v104, v241, v0
	v_max_u32_e32 v105, v241, v0
	v_cndmask_b32_e64 v241, v105, v104, s[88:89]
	v_min_u32_e32 v106, v243, v1
	v_max_u32_e32 v107, v243, v1
	v_cndmask_b32_e64 v243, v107, v106, s[88:89]
	v_min_u32_e32 v104, v245, v2
	v_max_u32_e32 v105, v245, v2
	v_cndmask_b32_e64 v245, v105, v104, s[88:89]
	v_min_u32_e32 v106, v247, v3
	v_max_u32_e32 v107, v247, v3
	v_cndmask_b32_e64 v247, v107, v106, s[88:89]
	v_min_u32_e32 v104, v242, v4
	v_max_u32_e32 v105, v242, v4
	v_cndmask_b32_e64 v242, v105, v104, s[88:89]
	v_min_u32_e32 v106, v244, v5
	v_max_u32_e32 v107, v244, v5
	v_cndmask_b32_e64 v244, v107, v106, s[88:89]
	v_min_u32_e32 v104, v246, v6
	v_max_u32_e32 v105, v246, v6
	v_cndmask_b32_e64 v246, v105, v104, s[88:89]
	v_min_u32_e32 v106, v248, v7
	v_max_u32_e32 v107, v248, v7
	v_cndmask_b32_e64 v248, v107, v106, s[88:89]
	v_xor_b32_e32 v116, 4, v234
	ds_bpermute_b32 v0, v116, v241
	ds_bpermute_b32 v1, v116, v243
	ds_bpermute_b32 v2, v116, v245
	ds_bpermute_b32 v3, v116, v247
	ds_bpermute_b32 v4, v116, v242
	ds_bpermute_b32 v5, v116, v244
	ds_bpermute_b32 v6, v116, v246
	ds_bpermute_b32 v7, v116, v248
	s_waitcnt lgkmcnt(0)
	s_mov_b32 s88, 0x55555555
	s_mov_b32 s89, 0xaaaaaaaa
	v_min_u32_e32 v104, v241, v0
	v_max_u32_e32 v105, v241, v0
	v_cndmask_b32_e64 v241, v105, v104, s[88:89]
	v_min_u32_e32 v106, v243, v1
	v_max_u32_e32 v107, v243, v1
	v_cndmask_b32_e64 v243, v107, v106, s[88:89]
	v_min_u32_e32 v104, v245, v2
	v_max_u32_e32 v105, v245, v2
	v_cndmask_b32_e64 v245, v105, v104, s[88:89]
	v_min_u32_e32 v106, v247, v3
	v_max_u32_e32 v107, v247, v3
	v_cndmask_b32_e64 v247, v107, v106, s[88:89]
	v_min_u32_e32 v104, v242, v4
	v_max_u32_e32 v105, v242, v4
	v_cndmask_b32_e64 v242, v105, v104, s[88:89]
	v_min_u32_e32 v106, v244, v5
	v_max_u32_e32 v107, v244, v5
	v_cndmask_b32_e64 v244, v107, v106, s[88:89]
	v_min_u32_e32 v104, v246, v6
	v_max_u32_e32 v105, v246, v6
	v_cndmask_b32_e64 v246, v105, v104, s[88:89]
	v_min_u32_e32 v106, v248, v7
	v_max_u32_e32 v107, v248, v7
	v_cndmask_b32_e64 v248, v107, v106, s[88:89]
	v_xor_b32_e32 v116, 128, v234
	ds_bpermute_b32 v0, v116, v241
	ds_bpermute_b32 v1, v116, v243
	ds_bpermute_b32 v2, v116, v245
	ds_bpermute_b32 v3, v116, v247
	ds_bpermute_b32 v4, v116, v242
	ds_bpermute_b32 v5, v116, v244
	ds_bpermute_b32 v6, v116, v246
	ds_bpermute_b32 v7, v116, v248
	s_waitcnt lgkmcnt(0)
	s_mov_b32 s88, 0xffffffff
	s_mov_b32 s89, 0x0
	v_min_u32_e32 v104, v241, v0
	v_max_u32_e32 v105, v241, v0
	v_cndmask_b32_e64 v241, v105, v104, s[88:89]
	v_min_u32_e32 v106, v243, v1
	v_max_u32_e32 v107, v243, v1
	v_cndmask_b32_e64 v243, v107, v106, s[88:89]
	v_min_u32_e32 v104, v245, v2
	v_max_u32_e32 v105, v245, v2
	v_cndmask_b32_e64 v245, v105, v104, s[88:89]
	v_min_u32_e32 v106, v247, v3
	v_max_u32_e32 v107, v247, v3
	v_cndmask_b32_e64 v247, v107, v106, s[88:89]
	s_mov_b32 s88, 0x0
	s_mov_b32 s89, 0xffffffff
	v_min_u32_e32 v104, v242, v4
	v_max_u32_e32 v105, v242, v4
	v_cndmask_b32_e64 v242, v105, v104, s[88:89]
	v_min_u32_e32 v106, v244, v5
	v_max_u32_e32 v107, v244, v5
	v_cndmask_b32_e64 v244, v107, v106, s[88:89]
	v_min_u32_e32 v104, v246, v6
	v_max_u32_e32 v105, v246, v6
	v_cndmask_b32_e64 v246, v105, v104, s[88:89]
	v_min_u32_e32 v106, v248, v7
	v_max_u32_e32 v107, v248, v7
	v_cndmask_b32_e64 v248, v107, v106, s[88:89]
	v_xor_b32_e32 v116, 64, v234
	ds_bpermute_b32 v0, v116, v241
	ds_bpermute_b32 v1, v116, v243
	ds_bpermute_b32 v2, v116, v245
	ds_bpermute_b32 v3, v116, v247
	ds_bpermute_b32 v4, v116, v242
	ds_bpermute_b32 v5, v116, v244
	ds_bpermute_b32 v6, v116, v246
	ds_bpermute_b32 v7, v116, v248
	s_waitcnt lgkmcnt(0)
	s_mov_b32 s88, 0xffff
	s_mov_b32 s89, 0xffff
	v_min_u32_e32 v104, v241, v0
	v_max_u32_e32 v105, v241, v0
	v_cndmask_b32_e64 v241, v105, v104, s[88:89]
	v_min_u32_e32 v106, v243, v1
	v_max_u32_e32 v107, v243, v1
	v_cndmask_b32_e64 v243, v107, v106, s[88:89]
	v_min_u32_e32 v104, v245, v2
	v_max_u32_e32 v105, v245, v2
	v_cndmask_b32_e64 v245, v105, v104, s[88:89]
	v_min_u32_e32 v106, v247, v3
	v_max_u32_e32 v107, v247, v3
	v_cndmask_b32_e64 v247, v107, v106, s[88:89]
	s_mov_b32 s88, 0xffff0000
	s_mov_b32 s89, 0xffff0000
	v_min_u32_e32 v104, v242, v4
	v_max_u32_e32 v105, v242, v4
	v_cndmask_b32_e64 v242, v105, v104, s[88:89]
	v_min_u32_e32 v106, v244, v5
	v_max_u32_e32 v107, v244, v5
	v_cndmask_b32_e64 v244, v107, v106, s[88:89]
	v_min_u32_e32 v104, v246, v6
	v_max_u32_e32 v105, v246, v6
	v_cndmask_b32_e64 v246, v105, v104, s[88:89]
	v_min_u32_e32 v106, v248, v7
	v_max_u32_e32 v107, v248, v7
	v_cndmask_b32_e64 v248, v107, v106, s[88:89]
	v_xor_b32_e32 v116, 32, v234
	ds_bpermute_b32 v0, v116, v241
	ds_bpermute_b32 v1, v116, v243
	ds_bpermute_b32 v2, v116, v245
	ds_bpermute_b32 v3, v116, v247
	ds_bpermute_b32 v4, v116, v242
	ds_bpermute_b32 v5, v116, v244
	ds_bpermute_b32 v6, v116, v246
	ds_bpermute_b32 v7, v116, v248
	s_waitcnt lgkmcnt(0)
	s_mov_b32 s88, 0xff00ff
	s_mov_b32 s89, 0xff00ff
	v_min_u32_e32 v104, v241, v0
	v_max_u32_e32 v105, v241, v0
	v_cndmask_b32_e64 v241, v105, v104, s[88:89]
	v_min_u32_e32 v106, v243, v1
	v_max_u32_e32 v107, v243, v1
	v_cndmask_b32_e64 v243, v107, v106, s[88:89]
	v_min_u32_e32 v104, v245, v2
	v_max_u32_e32 v105, v245, v2
	v_cndmask_b32_e64 v245, v105, v104, s[88:89]
	v_min_u32_e32 v106, v247, v3
	v_max_u32_e32 v107, v247, v3
	v_cndmask_b32_e64 v247, v107, v106, s[88:89]
	s_mov_b32 s88, 0xff00ff00
	s_mov_b32 s89, 0xff00ff00
	v_min_u32_e32 v104, v242, v4
	v_max_u32_e32 v105, v242, v4
	v_cndmask_b32_e64 v242, v105, v104, s[88:89]
	v_min_u32_e32 v106, v244, v5
	v_max_u32_e32 v107, v244, v5
	v_cndmask_b32_e64 v244, v107, v106, s[88:89]
	v_min_u32_e32 v104, v246, v6
	v_max_u32_e32 v105, v246, v6
	v_cndmask_b32_e64 v246, v105, v104, s[88:89]
	v_min_u32_e32 v106, v248, v7
	v_max_u32_e32 v107, v248, v7
	v_cndmask_b32_e64 v248, v107, v106, s[88:89]
	v_xor_b32_e32 v116, 16, v234
	ds_bpermute_b32 v0, v116, v241
	ds_bpermute_b32 v1, v116, v243
	ds_bpermute_b32 v2, v116, v245
	ds_bpermute_b32 v3, v116, v247
	ds_bpermute_b32 v4, v116, v242
	ds_bpermute_b32 v5, v116, v244
	ds_bpermute_b32 v6, v116, v246
	ds_bpermute_b32 v7, v116, v248
	s_waitcnt lgkmcnt(0)
; DEV void sort_lists(int lane, int& myi0, int& myi1, float& myg0, float& myg1) {
; #pragma unroll
;     for (int k = 2; k <= 128; k <<= 1) {
; #pragma unroll
;       for (int j = k >> 1; j >= 1; j >>= 1) {
;         if (j == 64) {
;           const bool sw_ = myi1 < myi0;
;           const int ti = sw_ ? myi1 : myi0, tj = sw_ ? myi0 : myi1; const float tg = sw_ ? myg1 : myg0, th = sw_ ? myg0 : myg1;
;           myi0 = ti; myi1 = tj; myg0 = tg; myg1 = th;
;         } else {
;           const bool lower = (lane & j) == 0;
;           {
;             const bool up = (k == 128) ? true : ((k == 64) ? true : ((lane & k) == 0));
;             const int oi = __shfl_xor(myi0, j); const float og = __shfl_xor(myg0, j);
;             const bool take = (lower == up) ? (oi < myi0) : (oi > myi0);
;             myi0 = take ? oi : myi0; myg0 = take ? og : myg0;
;           }
;           {
;             const bool up = (k == 128) ? true : ((k == 64) ? false : ((lane & k) == 0));
;             const int oi = __shfl_xor(myi1, j); const float og = __shfl_xor(myg1, j);
;             const bool take = (lower == up) ? (oi < myi1) : (oi > myi1);
;             myi1 = take ? oi : myi1; myg1 = take ? og : myg1;
;           }
;         }
;       }
;     }
; }
	s_mov_b32 s88, 0xf0f0f0f
	s_mov_b32 s89, 0xf0f0f0f
	v_min_u32_e32 v104, v241, v0
	v_max_u32_e32 v105, v241, v0
	v_cndmask_b32_e64 v241, v105, v104, s[88:89]
	v_min_u32_e32 v106, v243, v1
	v_max_u32_e32 v107, v243, v1
	v_cndmask_b32_e64 v243, v107, v106, s[88:89]
	v_min_u32_e32 v104, v245, v2
	v_max_u32_e32 v105, v245, v2
	v_cndmask_b32_e64 v245, v105, v104, s[88:89]
	v_min_u32_e32 v106, v247, v3
	v_max_u32_e32 v107, v247, v3
	v_cndmask_b32_e64 v247, v107, v106, s[88:89]
	s_mov_b32 s88, 0xf0f0f0f0
	s_mov_b32 s89, 0xf0f0f0f0
	v_min_u32_e32 v104, v242, v4
	v_max_u32_e32 v105, v242, v4
	v_cndmask_b32_e64 v242, v105, v104, s[88:89]
	v_min_u32_e32 v106, v244, v5
	v_max_u32_e32 v107, v244, v5
	v_cndmask_b32_e64 v244, v107, v106, s[88:89]
	v_min_u32_e32 v104, v246, v6
	v_max_u32_e32 v105, v246, v6
	v_cndmask_b32_e64 v246, v105, v104, s[88:89]
	v_min_u32_e32 v106, v248, v7
	v_max_u32_e32 v107, v248, v7
	v_cndmask_b32_e64 v248, v107, v106, s[88:89]
	v_xor_b32_e32 v116, 8, v234
	ds_bpermute_b32 v0, v116, v241
	ds_bpermute_b32 v1, v116, v243
	ds_bpermute_b32 v2, v116, v245
	ds_bpermute_b32 v3, v116, v247
	ds_bpermute_b32 v4, v116, v242
	ds_bpermute_b32 v5, v116, v244
	ds_bpermute_b32 v6, v116, v246
	ds_bpermute_b32 v7, v116, v248
	s_waitcnt lgkmcnt(0)
	s_mov_b32 s88, 0x33333333
	s_mov_b32 s89, 0x33333333
	v_min_u32_e32 v104, v241, v0
	v_max_u32_e32 v105, v241, v0
	v_cndmask_b32_e64 v241, v105, v104, s[88:89]
	v_min_u32_e32 v106, v243, v1
	v_max_u32_e32 v107, v243, v1
	v_cndmask_b32_e64 v243, v107, v106, s[88:89]
	v_min_u32_e32 v104, v245, v2
	v_max_u32_e32 v105, v245, v2
	v_cndmask_b32_e64 v245, v105, v104, s[88:89]
	v_min_u32_e32 v106, v247, v3
	v_max_u32_e32 v107, v247, v3
	v_cndmask_b32_e64 v247, v107, v106, s[88:89]
	s_mov_b32 s88, 0xcccccccc
	s_mov_b32 s89, 0xcccccccc
	v_min_u32_e32 v104, v242, v4
	v_max_u32_e32 v105, v242, v4
	v_cndmask_b32_e64 v242, v105, v104, s[88:89]
	v_min_u32_e32 v106, v244, v5
	v_max_u32_e32 v107, v244, v5
	v_cndmask_b32_e64 v244, v107, v106, s[88:89]
	v_min_u32_e32 v104, v246, v6
	v_max_u32_e32 v105, v246, v6
	v_cndmask_b32_e64 v246, v105, v104, s[88:89]
	v_min_u32_e32 v106, v248, v7
	v_max_u32_e32 v107, v248, v7
	v_cndmask_b32_e64 v248, v107, v106, s[88:89]
	v_xor_b32_e32 v116, 4, v234
	ds_bpermute_b32 v0, v116, v241
	ds_bpermute_b32 v1, v116, v243
	ds_bpermute_b32 v2, v116, v245
	ds_bpermute_b32 v3, v116, v247
	ds_bpermute_b32 v4, v116, v242
	ds_bpermute_b32 v5, v116, v244
	ds_bpermute_b32 v6, v116, v246
	ds_bpermute_b32 v7, v116, v248
	s_waitcnt lgkmcnt(0)
	s_mov_b32 s88, 0x55555555
	s_mov_b32 s89, 0x55555555
	v_min_u32_e32 v104, v241, v0
	v_max_u32_e32 v105, v241, v0
	v_cndmask_b32_e64 v241, v105, v104, s[88:89]
	v_min_u32_e32 v106, v243, v1
	v_max_u32_e32 v107, v243, v1
	v_cndmask_b32_e64 v243, v107, v106, s[88:89]
	v_min_u32_e32 v104, v245, v2
	v_max_u32_e32 v105, v245, v2
	v_cndmask_b32_e64 v245, v105, v104, s[88:89]
	v_min_u32_e32 v106, v247, v3
	v_max_u32_e32 v107, v247, v3
	v_cndmask_b32_e64 v247, v107, v106, s[88:89]
	s_mov_b32 s88, 0xaaaaaaaa
	s_mov_b32 s89, 0xaaaaaaaa
	v_min_u32_e32 v104, v242, v4
	v_max_u32_e32 v105, v242, v4
	v_cndmask_b32_e64 v242, v105, v104, s[88:89]
	v_min_u32_e32 v106, v244, v5
	v_max_u32_e32 v107, v244, v5
	v_cndmask_b32_e64 v244, v107, v106, s[88:89]
	v_min_u32_e32 v104, v246, v6
	v_max_u32_e32 v105, v246, v6
	v_cndmask_b32_e64 v246, v105, v104, s[88:89]
	v_min_u32_e32 v106, v248, v7
	v_max_u32_e32 v107, v248, v7
	v_cndmask_b32_e64 v248, v107, v106, s[88:89]
	v_min_u32_e32 v104, v241, v242
	v_max_u32_e32 v242, v241, v242
	v_mov_b32_e32 v241, v104
	v_min_u32_e32 v106, v243, v244
	v_max_u32_e32 v244, v243, v244
	v_mov_b32_e32 v243, v106
	v_min_u32_e32 v104, v245, v246
	v_max_u32_e32 v246, v245, v246
	v_mov_b32_e32 v245, v104
	v_min_u32_e32 v106, v247, v248
	v_max_u32_e32 v248, v247, v248
	v_mov_b32_e32 v247, v106
	v_xor_b32_e32 v116, 128, v234
	ds_bpermute_b32 v0, v116, v241
	ds_bpermute_b32 v1, v116, v243
	ds_bpermute_b32 v2, v116, v245
	ds_bpermute_b32 v3, v116, v247
	ds_bpermute_b32 v4, v116, v242
	ds_bpermute_b32 v5, v116, v244
	ds_bpermute_b32 v6, v116, v246
	ds_bpermute_b32 v7, v116, v248
	s_waitcnt lgkmcnt(0)
	s_mov_b32 s88, 0xffffffff
	s_mov_b32 s89, 0x0
	v_min_u32_e32 v104, v241, v0
	v_max_u32_e32 v105, v241, v0
	v_cndmask_b32_e64 v241, v105, v104, s[88:89]
	v_min_u32_e32 v106, v243, v1
	v_max_u32_e32 v107, v243, v1
	v_cndmask_b32_e64 v243, v107, v106, s[88:89]
	v_min_u32_e32 v104, v245, v2
	v_max_u32_e32 v105, v245, v2
	v_cndmask_b32_e64 v245, v105, v104, s[88:89]
	v_min_u32_e32 v106, v247, v3
	v_max_u32_e32 v107, v247, v3
	v_cndmask_b32_e64 v247, v107, v106, s[88:89]
	v_min_u32_e32 v104, v242, v4
	v_max_u32_e32 v105, v242, v4
	v_cndmask_b32_e64 v242, v105, v104, s[88:89]
	v_min_u32_e32 v106, v244, v5
	v_max_u32_e32 v107, v244, v5
	v_cndmask_b32_e64 v244, v107, v106, s[88:89]
	v_min_u32_e32 v104, v246, v6
	v_max_u32_e32 v105, v246, v6
	v_cndmask_b32_e64 v246, v105, v104, s[88:89]
	v_min_u32_e32 v106, v248, v7
	v_max_u32_e32 v107, v248, v7
	v_cndmask_b32_e64 v248, v107, v106, s[88:89]
	v_xor_b32_e32 v116, 64, v234
	ds_bpermute_b32 v0, v116, v241
	ds_bpermute_b32 v1, v116, v243
	ds_bpermute_b32 v2, v116, v245
	ds_bpermute_b32 v3, v116, v247
	ds_bpermute_b32 v4, v116, v242
	ds_bpermute_b32 v5, v116, v244
	ds_bpermute_b32 v6, v116, v246
	ds_bpermute_b32 v7, v116, v248
	s_waitcnt lgkmcnt(0)
; DEV void sort_lists(int lane, int& myi0, int& myi1, float& myg0, float& myg1) {
; #pragma unroll
;     for (int k = 2; k <= 128; k <<= 1) {
; #pragma unroll
;       for (int j = k >> 1; j >= 1; j >>= 1) {
;         if (j == 64) {
;           const bool sw_ = myi1 < myi0;
;           const int ti = sw_ ? myi1 : myi0, tj = sw_ ? myi0 : myi1; const float tg = sw_ ? myg1 : myg0, th = sw_ ? myg0 : myg1;
;           myi0 = ti; myi1 = tj; myg0 = tg; myg1 = th;
;         } else {
;           const bool lower = (lane & j) == 0;
;           {
;             const bool up = (k == 128) ? true : ((k == 64) ? true : ((lane & k) == 0));
;             const int oi = __shfl_xor(myi0, j); const float og = __shfl_xor(myg0, j);
;             const bool take = (lower == up) ? (oi < myi0) : (oi > myi0);
;             myi0 = take ? oi : myi0; myg0 = take ? og : myg0;
;           }
;           {
;             const bool up = (k == 128) ? true : ((k == 64) ? false : ((lane & k) == 0));
;             const int oi = __shfl_xor(myi1, j); const float og = __shfl_xor(myg1, j);
;             const bool take = (lower == up) ? (oi < myi1) : (oi > myi1);
;             myi1 = take ? oi : myi1; myg1 = take ? og : myg1;
;           }
;         }
;       }
;     }
; }
	s_mov_b32 s88, 0xffff
	s_mov_b32 s89, 0xffff
	v_min_u32_e32 v104, v241, v0
	v_max_u32_e32 v105, v241, v0
	v_cndmask_b32_e64 v241, v105, v104, s[88:89]
	v_min_u32_e32 v106, v243, v1
	v_max_u32_e32 v107, v243, v1
	v_cndmask_b32_e64 v243, v107, v106, s[88:89]
	v_min_u32_e32 v104, v245, v2
	v_max_u32_e32 v105, v245, v2
	v_cndmask_b32_e64 v245, v105, v104, s[88:89]
	v_min_u32_e32 v106, v247, v3
	v_max_u32_e32 v107, v247, v3
	v_cndmask_b32_e64 v247, v107, v106, s[88:89]
	v_min_u32_e32 v104, v242, v4
	v_max_u32_e32 v105, v242, v4
	v_cndmask_b32_e64 v242, v105, v104, s[88:89]
	v_min_u32_e32 v106, v244, v5
	v_max_u32_e32 v107, v244, v5
	v_cndmask_b32_e64 v244, v107, v106, s[88:89]
	v_min_u32_e32 v104, v246, v6
	v_max_u32_e32 v105, v246, v6
	v_cndmask_b32_e64 v246, v105, v104, s[88:89]
	v_min_u32_e32 v106, v248, v7
	v_max_u32_e32 v107, v248, v7
	v_cndmask_b32_e64 v248, v107, v106, s[88:89]
	v_xor_b32_e32 v116, 32, v234
	ds_bpermute_b32 v0, v116, v241
	ds_bpermute_b32 v1, v116, v243
	ds_bpermute_b32 v2, v116, v245
	ds_bpermute_b32 v3, v116, v247
	ds_bpermute_b32 v4, v116, v242
	ds_bpermute_b32 v5, v116, v244
	ds_bpermute_b32 v6, v116, v246
	ds_bpermute_b32 v7, v116, v248
	s_waitcnt lgkmcnt(0)
	s_mov_b32 s88, 0xff00ff
	s_mov_b32 s89, 0xff00ff
	v_min_u32_e32 v104, v241, v0
	v_max_u32_e32 v105, v241, v0
	v_cndmask_b32_e64 v241, v105, v104, s[88:89]
	v_min_u32_e32 v106, v243, v1
	v_max_u32_e32 v107, v243, v1
	v_cndmask_b32_e64 v243, v107, v106, s[88:89]
	v_min_u32_e32 v104, v245, v2
	v_max_u32_e32 v105, v245, v2
	v_cndmask_b32_e64 v245, v105, v104, s[88:89]
	v_min_u32_e32 v106, v247, v3
	v_max_u32_e32 v107, v247, v3
	v_cndmask_b32_e64 v247, v107, v106, s[88:89]
	v_min_u32_e32 v104, v242, v4
	v_max_u32_e32 v105, v242, v4
	v_cndmask_b32_e64 v242, v105, v104, s[88:89]
	v_min_u32_e32 v106, v244, v5
	v_max_u32_e32 v107, v244, v5
	v_cndmask_b32_e64 v244, v107, v106, s[88:89]
	v_min_u32_e32 v104, v246, v6
	v_max_u32_e32 v105, v246, v6
	v_cndmask_b32_e64 v246, v105, v104, s[88:89]
	v_min_u32_e32 v106, v248, v7
	v_max_u32_e32 v107, v248, v7
	v_cndmask_b32_e64 v248, v107, v106, s[88:89]
	v_xor_b32_e32 v116, 16, v234
	ds_bpermute_b32 v0, v116, v241
	ds_bpermute_b32 v1, v116, v243
	ds_bpermute_b32 v2, v116, v245
	ds_bpermute_b32 v3, v116, v247
	ds_bpermute_b32 v4, v116, v242
	ds_bpermute_b32 v5, v116, v244
	ds_bpermute_b32 v6, v116, v246
	ds_bpermute_b32 v7, v116, v248
	s_waitcnt lgkmcnt(0)
	s_mov_b32 s88, 0xf0f0f0f
	s_mov_b32 s89, 0xf0f0f0f
	v_min_u32_e32 v104, v241, v0
	v_max_u32_e32 v105, v241, v0
	v_cndmask_b32_e64 v241, v105, v104, s[88:89]
	v_min_u32_e32 v106, v243, v1
	v_max_u32_e32 v107, v243, v1
	v_cndmask_b32_e64 v243, v107, v106, s[88:89]
	v_min_u32_e32 v104, v245, v2
	v_max_u32_e32 v105, v245, v2
	v_cndmask_b32_e64 v245, v105, v104, s[88:89]
	v_min_u32_e32 v106, v247, v3
	v_max_u32_e32 v107, v247, v3
	v_cndmask_b32_e64 v247, v107, v106, s[88:89]
	v_min_u32_e32 v104, v242, v4
	v_max_u32_e32 v105, v242, v4
	v_cndmask_b32_e64 v242, v105, v104, s[88:89]
	v_min_u32_e32 v106, v244, v5
	v_max_u32_e32 v107, v244, v5
	v_cndmask_b32_e64 v244, v107, v106, s[88:89]
	v_min_u32_e32 v104, v246, v6
	v_max_u32_e32 v105, v246, v6
	v_cndmask_b32_e64 v246, v105, v104, s[88:89]
	v_min_u32_e32 v106, v248, v7
	v_max_u32_e32 v107, v248, v7
	v_cndmask_b32_e64 v248, v107, v106, s[88:89]
	v_xor_b32_e32 v116, 8, v234
	ds_bpermute_b32 v0, v116, v241
	ds_bpermute_b32 v1, v116, v243
	ds_bpermute_b32 v2, v116, v245
	ds_bpermute_b32 v3, v116, v247
	ds_bpermute_b32 v4, v116, v242
	ds_bpermute_b32 v5, v116, v244
	ds_bpermute_b32 v6, v116, v246
	ds_bpermute_b32 v7, v116, v248
	s_waitcnt lgkmcnt(0)
	s_mov_b32 s88, 0x33333333
	s_mov_b32 s89, 0x33333333
	v_min_u32_e32 v104, v241, v0
	v_max_u32_e32 v105, v241, v0
	v_cndmask_b32_e64 v241, v105, v104, s[88:89]
	v_min_u32_e32 v106, v243, v1
	v_max_u32_e32 v107, v243, v1
	v_cndmask_b32_e64 v243, v107, v106, s[88:89]
	v_min_u32_e32 v104, v245, v2
	v_max_u32_e32 v105, v245, v2
	v_cndmask_b32_e64 v245, v105, v104, s[88:89]
	v_min_u32_e32 v106, v247, v3
	v_max_u32_e32 v107, v247, v3
	v_cndmask_b32_e64 v247, v107, v106, s[88:89]
	v_min_u32_e32 v104, v242, v4
	v_max_u32_e32 v105, v242, v4
	v_cndmask_b32_e64 v242, v105, v104, s[88:89]
	v_min_u32_e32 v106, v244, v5
	v_max_u32_e32 v107, v244, v5
	v_cndmask_b32_e64 v244, v107, v106, s[88:89]
	v_min_u32_e32 v104, v246, v6
	v_max_u32_e32 v105, v246, v6
	v_cndmask_b32_e64 v246, v105, v104, s[88:89]
	v_min_u32_e32 v106, v248, v7
	v_max_u32_e32 v107, v248, v7
	v_cndmask_b32_e64 v248, v107, v106, s[88:89]
	v_xor_b32_e32 v116, 4, v234
	ds_bpermute_b32 v0, v116, v241
	ds_bpermute_b32 v1, v116, v243
	ds_bpermute_b32 v2, v116, v245
	ds_bpermute_b32 v3, v116, v247
	ds_bpermute_b32 v4, v116, v242
	ds_bpermute_b32 v5, v116, v244
	ds_bpermute_b32 v6, v116, v246
	ds_bpermute_b32 v7, v116, v248
	s_waitcnt lgkmcnt(0)
	s_mov_b32 s88, 0x55555555
	s_mov_b32 s89, 0x55555555
	v_min_u32_e32 v104, v241, v0
	v_max_u32_e32 v105, v241, v0
	v_cndmask_b32_e64 v241, v105, v104, s[88:89]
	v_min_u32_e32 v106, v243, v1
	v_max_u32_e32 v107, v243, v1
	v_cndmask_b32_e64 v243, v107, v106, s[88:89]
	v_min_u32_e32 v104, v245, v2
	v_max_u32_e32 v105, v245, v2
	v_cndmask_b32_e64 v245, v105, v104, s[88:89]
	v_min_u32_e32 v106, v247, v3
	v_max_u32_e32 v107, v247, v3
	v_cndmask_b32_e64 v247, v107, v106, s[88:89]
	v_min_u32_e32 v104, v242, v4
	v_max_u32_e32 v105, v242, v4
	v_cndmask_b32_e64 v242, v105, v104, s[88:89]
	v_min_u32_e32 v106, v244, v5
	v_max_u32_e32 v107, v244, v5
	v_cndmask_b32_e64 v244, v107, v106, s[88:89]
	v_min_u32_e32 v104, v246, v6
	v_max_u32_e32 v105, v246, v6
	v_cndmask_b32_e64 v246, v105, v104, s[88:89]
	v_min_u32_e32 v106, v248, v7
	v_max_u32_e32 v107, v248, v7
	v_cndmask_b32_e64 v248, v107, v106, s[88:89]
	v_mov_b32_e32 v117, 0
	s_lshl_b32 s98, s2, 11
	s_add_u32 s98, s98, s101
	v_add_u32_e32 v116, s98, v234
	ds_write_b32 v116, v241 offset:0
	ds_write_b32 v116, v242 offset:256
	ds_write_b32 v116, v243 offset:512
	ds_write_b32 v116, v244 offset:768
	ds_write_b32 v116, v245 offset:1024
	ds_write_b32 v116, v246 offset:1280
	ds_write_b32 v116, v247 offset:1536
	ds_write_b32 v116, v248 offset:1792
	v_add_u32_e32 v118, 0x10000, v116
	ds_write_b32 v118, v117 offset:0
	ds_write_b32 v118, v117 offset:256
	ds_write_b32 v118, v117 offset:512
	ds_write_b32 v118, v117 offset:768
	ds_write_b32 v118, v117 offset:1024
	ds_write_b32 v118, v117 offset:1280
	ds_write_b32 v118, v117 offset:1536
	ds_write_b32 v118, v117 offset:1792
	s_add_u32 s2, s2, 1
	s_cmp_lt_u32 s2, 4
	s_cbranch_scc1 .Lpg0_p0
; #define PG_ISSUE(BUF, TAB, e0_) do { const int isrc_ = ((e0_) < 64) ? myi0 : myi1; \
;       _Pragma("unroll") for (int e = 0; e < 8; ++e) { const int idx_ = __builtin_amdgcn_readlane(isrc_, ((e0_) + e) & 63); \
;         BUF[e] = *(const u32x4*)((TAB) + (size_t)idx_ * 1024 + lane * 16); } } while (0)
; DEV void peer_gather(const Params& P, int l, int m0, const int* idxs, const float* gs) {
;     ...
;     PG_ISSUE(b0, U, 0);
; #pragma nounroll
;     for (int e0 = 0; e0 < 128; e0 += 16) {
;       PG_ISSUE(b1, U, e0 + 8);
;       PG_U8(b0, 0, e0);
;       if (e0 + 16 < 128) PG_ISSUE(b0, U, e0 + 16); else PG_ISSUE(b0, V, 0);
;       PG_U8(b1, 0, e0 + 8);
	s_waitcnt lgkmcnt(0)
	v_lshrrev_b32_e32 v248, 3, v233
	v_readfirstlane_b32 s82, v128
	v_readfirstlane_b32 s83, v129
	s_nop 4
	v_readfirstlane_b32 s80, v124
	v_readfirstlane_b32 s81, v125
	s_nop 4
	s_mov_b32 s2, 0xffffff80
	s_mov_b32 s86, 0xcccccccc
	s_mov_b32 s87, 0xcccccccc
	s_mov_b32 s88, 0xaaaaaaaa
	s_mov_b32 s89, 0xaaaaaaaa
	s_mov_b32 s90, 0xf0f0f0f0
	s_mov_b32 s91, 0xf0f0f0f0
	s_lshl_b32 vcc_lo, s3, 11
	s_add_u32 s82, s82, vcc_lo
	s_addc_u32 s83, s83, 0
	v_add_u32_e32 v246, s101, v234
	v_add_u32_e32 v247, 0x10000, v246
	s_mov_b32 s100, 0
	s_mov_b32 s98, 0
	s_mov_b32 s99, 0
	s_lshl3_add_u32 vcc_lo, s98, s99
	v_lshl_add_u32 v119, vcc_lo, 8, v236
	global_load_dwordx4 v[80:83], v119, s[82:83]
	global_load_dwordx4 v[84:87], v119, s[82:83] offset:16
	v_lshl_add_u32 v116, s98, 9, v246
	ds_read_b32 v134, v116
	ds_read_b32 v135, v116 offset:256
	v_lshl_or_b32 v240, s99, 21, v235
	s_waitcnt lgkmcnt(0)
	ds_bpermute_b32 v142, v249, v134
	ds_bpermute_b32 v143, v250, v134
	s_waitcnt lgkmcnt(0)
	v_and_or_b32 v142, v142, s2, v240
	v_and_or_b32 v143, v143, s2, v240
	global_load_dwordx4 v[0:3], v142, s[80:81]
	global_load_dwordx4 v[4:7], v143, s[80:81]
	ds_bpermute_b32 v142, v251, v134
	ds_bpermute_b32 v143, v252, v134
	s_waitcnt lgkmcnt(0)
	v_and_or_b32 v142, v142, s2, v240
	v_and_or_b32 v143, v143, s2, v240
	global_load_dwordx4 v[8:11], v142, s[80:81]
	global_load_dwordx4 v[12:15], v143, s[80:81]
	ds_bpermute_b32 v142, v253, v134
	ds_bpermute_b32 v143, v254, v134
	s_waitcnt lgkmcnt(0)
	v_and_or_b32 v142, v142, s2, v240
	v_and_or_b32 v143, v143, s2, v240
	global_load_dwordx4 v[16:19], v142, s[80:81]
	global_load_dwordx4 v[20:23], v143, s[80:81]
	ds_bpermute_b32 v142, v255, v134
	ds_bpermute_b32 v143, v153, v134
	s_waitcnt lgkmcnt(0)
	v_and_or_b32 v142, v142, s2, v240
	v_and_or_b32 v143, v143, s2, v240
	global_load_dwordx4 v[24:27], v142, s[80:81]
	global_load_dwordx4 v[28:31], v143, s[80:81]
	ds_bpermute_b32 v142, v249, v135
	ds_bpermute_b32 v143, v250, v135
	s_waitcnt lgkmcnt(0)
	v_and_or_b32 v142, v142, s2, v240
	v_and_or_b32 v143, v143, s2, v240
	global_load_dwordx4 v[32:35], v142, s[80:81]
	global_load_dwordx4 v[36:39], v143, s[80:81]
	ds_bpermute_b32 v142, v251, v135
	ds_bpermute_b32 v143, v252, v135
	s_waitcnt lgkmcnt(0)
	v_and_or_b32 v142, v142, s2, v240
	v_and_or_b32 v143, v143, s2, v240
	global_load_dwordx4 v[40:43], v142, s[80:81]
	global_load_dwordx4 v[44:47], v143, s[80:81]
	ds_bpermute_b32 v142, v253, v135
	ds_bpermute_b32 v143, v254, v135
	s_waitcnt lgkmcnt(0)
	v_and_or_b32 v142, v142, s2, v240
	v_and_or_b32 v143, v143, s2, v240
	global_load_dwordx4 v[48:51], v142, s[80:81]
	global_load_dwordx4 v[52:55], v143, s[80:81]
	ds_bpermute_b32 v142, v255, v135
	ds_bpermute_b32 v143, v153, v135
	s_waitcnt lgkmcnt(0)
	v_and_or_b32 v142, v142, s2, v240
	v_and_or_b32 v143, v143, s2, v240
	global_load_dwordx4 v[56:59], v142, s[80:81]
	global_load_dwordx4 v[60:63], v143, s[80:81]
	s_mov_b32 s92, 1
	v_lshl_add_u32 v116, s92, 9, v246
	ds_read_b32 v134, v116
	ds_read_b32 v135, v116 offset:256
.Lpg0_uloop:
	s_and_b32 s98, s100, 15
	s_add_u32 s92, s100, 1
	s_min_u32 s92, s92, 127
	s_lshr_b32 s93, s92, 4
	s_and_b32 s92, s92, 15
	s_waitcnt lgkmcnt(0)
	ds_bpermute_b32 v142, v249, v134
	ds_bpermute_b32 v143, v250, v134
	s_waitcnt vmcnt(16)
	v_mov_b32_e32 v64, v80
	v_mov_b32_e32 v65, v81
	v_mov_b32_e32 v66, v82
	v_mov_b32_e32 v67, v83
	v_mov_b32_e32 v68, v84
	v_mov_b32_e32 v69, v85
	v_mov_b32_e32 v70, v86
	v_mov_b32_e32 v71, v87
	s_lshl3_add_u32 vcc_lo, s92, s93
	v_lshl_add_u32 v119, vcc_lo, 8, v236
	global_load_dwordx4 v[80:83], v119, s[82:83]
	global_load_dwordx4 v[84:87], v119, s[82:83] offset:16
	v_lshl_or_b32 v240, s93, 21, v235
	s_waitcnt vmcnt(16) lgkmcnt(0)
	ds_bpermute_b32 v244, v251, v134
	ds_bpermute_b32 v245, v252, v134
	v_cvt_scalef32_pk_bf16_fp8 v104, v0, 1.0
	v_cvt_scalef32_pk_bf16_fp8 v106, v4, 1.0
	v_cvt_scalef32_pk_bf16_fp8 v105, v0, 1.0 op_sel:[1,0,0]
	v_cvt_scalef32_pk_bf16_fp8 v107, v4, 1.0 op_sel:[1,0,0]
	v_cvt_scalef32_pk_bf16_fp8 v108, v1, 1.0
	v_cvt_scalef32_pk_bf16_fp8 v109, v1, 1.0 op_sel:[1,0,0]
	v_mfma_f32_4x4x4_16b_bf16 v[72:75], v[104:105], v[64:65], 0
	v_cvt_scalef32_pk_bf16_fp8 v110, v5, 1.0
	v_cvt_scalef32_pk_bf16_fp8 v111, v5, 1.0 op_sel:[1,0,0]
	v_mfma_f32_4x4x4_16b_bf16 v[76:79], v[106:107], v[64:65], 0
	v_cvt_scalef32_pk_bf16_fp8 v104, v2, 1.0
	v_cvt_scalef32_pk_bf16_fp8 v105, v2, 1.0 op_sel:[1,0,0]
	v_mfma_f32_4x4x4_16b_bf16 v[72:75], v[108:109], v[66:67], v[72:75]
	v_cvt_scalef32_pk_bf16_fp8 v106, v6, 1.0
	v_cvt_scalef32_pk_bf16_fp8 v107, v6, 1.0 op_sel:[1,0,0]
	v_mfma_f32_4x4x4_16b_bf16 v[76:79], v[110:111], v[66:67], v[76:79]
	v_cvt_scalef32_pk_bf16_fp8 v108, v3, 1.0
	v_cvt_scalef32_pk_bf16_fp8 v109, v3, 1.0 op_sel:[1,0,0]
	v_mfma_f32_4x4x4_16b_bf16 v[72:75], v[104:105], v[68:69], v[72:75]
	v_cvt_scalef32_pk_bf16_fp8 v110, v7, 1.0
	v_cvt_scalef32_pk_bf16_fp8 v111, v7, 1.0 op_sel:[1,0,0]
	v_mfma_f32_4x4x4_16b_bf16 v[76:79], v[106:107], v[68:69], v[76:79]
	v_and_or_b32 v142, v142, s2, v240
	v_and_or_b32 v143, v143, s2, v240
	global_load_dwordx4 v[0:3], v142, s[80:81]
	global_load_dwordx4 v[4:7], v143, s[80:81]
	s_waitcnt vmcnt(16) lgkmcnt(0)
; #define PG_ISSUE(BUF, TAB, e0_) do { const int isrc_ = ((e0_) < 64) ? myi0 : myi1; \
;       _Pragma("unroll") for (int e = 0; e < 8; ++e) { const int idx_ = __builtin_amdgcn_readlane(isrc_, ((e0_) + e) & 63); \
;         BUF[e] = *(const u32x4*)((TAB) + (size_t)idx_ * 1024 + lane * 16); } } while (0)
; DEV void peer_gather(const Params& P, int l, int m0, const int* idxs, const float* gs) {
;     ...
;     for (int e0 = 0; e0 < 128; e0 += 16) {
;       PG_ISSUE(b1, U, e0 + 8);
;       PG_U8(b0, 0, e0);
;       if (e0 + 16 < 128) PG_ISSUE(b0, U, e0 + 16); else PG_ISSUE(b0, V, 0);
;       PG_U8(b1, 0, e0 + 8);
	ds_bpermute_b32 v142, v253, v134
	ds_bpermute_b32 v143, v254, v134
	v_cvt_scalef32_pk_bf16_fp8 v104, v8, 1.0
	v_cvt_scalef32_pk_bf16_fp8 v105, v8, 1.0 op_sel:[1,0,0]
	v_mfma_f32_4x4x4_16b_bf16 v[72:75], v[108:109], v[70:71], v[72:75]
	v_cvt_scalef32_pk_bf16_fp8 v106, v12, 1.0
	v_cvt_scalef32_pk_bf16_fp8 v107, v12, 1.0 op_sel:[1,0,0]
	v_mfma_f32_4x4x4_16b_bf16 v[76:79], v[110:111], v[70:71], v[76:79]
	v_cvt_scalef32_pk_bf16_fp8 v108, v9, 1.0
	v_cvt_scalef32_pk_bf16_fp8 v110, v13, 1.0
	v_cvt_scalef32_pk_bf16_fp8 v109, v9, 1.0 op_sel:[1,0,0]
	v_cvt_scalef32_pk_bf16_fp8 v111, v13, 1.0 op_sel:[1,0,0]
	v_cndmask_b32_e64 v148, v72, v73, s[88:89]
	v_cndmask_b32_e64 v149, v74, v75, s[88:89]
	v_cndmask_b32_e64 v88, v148, v149, s[86:87]
	v_mfma_f32_4x4x4_16b_bf16 v[72:75], v[104:105], v[64:65], 0
	v_cndmask_b32_e64 v150, v76, v77, s[88:89]
	v_cndmask_b32_e64 v151, v78, v79, s[88:89]
	v_cndmask_b32_e64 v89, v150, v151, s[86:87]
	v_mfma_f32_4x4x4_16b_bf16 v[76:79], v[106:107], v[64:65], 0
	v_cvt_scalef32_pk_bf16_fp8 v104, v10, 1.0
	v_cvt_scalef32_pk_bf16_fp8 v105, v10, 1.0 op_sel:[1,0,0]
	v_mfma_f32_4x4x4_16b_bf16 v[72:75], v[108:109], v[66:67], v[72:75]
	v_cvt_scalef32_pk_bf16_fp8 v106, v14, 1.0
	v_cvt_scalef32_pk_bf16_fp8 v107, v14, 1.0 op_sel:[1,0,0]
	v_mfma_f32_4x4x4_16b_bf16 v[76:79], v[110:111], v[66:67], v[76:79]
	v_cvt_scalef32_pk_bf16_fp8 v108, v11, 1.0
	v_cvt_scalef32_pk_bf16_fp8 v109, v11, 1.0 op_sel:[1,0,0]
	v_mfma_f32_4x4x4_16b_bf16 v[72:75], v[104:105], v[68:69], v[72:75]
	v_cvt_scalef32_pk_bf16_fp8 v110, v15, 1.0
	v_cvt_scalef32_pk_bf16_fp8 v111, v15, 1.0 op_sel:[1,0,0]
	v_mfma_f32_4x4x4_16b_bf16 v[76:79], v[106:107], v[68:69], v[76:79]
	v_and_or_b32 v244, v244, s2, v240
	v_and_or_b32 v245, v245, s2, v240
	global_load_dwordx4 v[8:11], v244, s[80:81]
	global_load_dwordx4 v[12:15], v245, s[80:81]
	s_waitcnt vmcnt(16) lgkmcnt(0)
	ds_bpermute_b32 v244, v255, v134
	ds_bpermute_b32 v245, v153, v134
	v_cvt_scalef32_pk_bf16_fp8 v104, v16, 1.0
	v_cvt_scalef32_pk_bf16_fp8 v105, v16, 1.0 op_sel:[1,0,0]
	v_mfma_f32_4x4x4_16b_bf16 v[72:75], v[108:109], v[70:71], v[72:75]
	v_cvt_scalef32_pk_bf16_fp8 v106, v20, 1.0
	v_cvt_scalef32_pk_bf16_fp8 v107, v20, 1.0 op_sel:[1,0,0]
	v_mfma_f32_4x4x4_16b_bf16 v[76:79], v[110:111], v[70:71], v[76:79]
	v_cvt_scalef32_pk_bf16_fp8 v108, v17, 1.0
	v_cvt_scalef32_pk_bf16_fp8 v110, v21, 1.0
	v_cvt_scalef32_pk_bf16_fp8 v109, v17, 1.0 op_sel:[1,0,0]
	v_cvt_scalef32_pk_bf16_fp8 v111, v21, 1.0 op_sel:[1,0,0]
	v_cndmask_b32_e64 v148, v72, v73, s[88:89]
	v_cndmask_b32_e64 v149, v74, v75, s[88:89]
	v_cndmask_b32_e64 v90, v148, v149, s[86:87]
	v_mfma_f32_4x4x4_16b_bf16 v[72:75], v[104:105], v[64:65], 0
	v_cndmask_b32_e64 v150, v76, v77, s[88:89]
	v_cndmask_b32_e64 v151, v78, v79, s[88:89]
	v_cndmask_b32_e64 v91, v150, v151, s[86:87]
	v_mfma_f32_4x4x4_16b_bf16 v[76:79], v[106:107], v[64:65], 0
	v_cvt_scalef32_pk_bf16_fp8 v104, v18, 1.0
	v_cvt_scalef32_pk_bf16_fp8 v105, v18, 1.0 op_sel:[1,0,0]
	v_mfma_f32_4x4x4_16b_bf16 v[72:75], v[108:109], v[66:67], v[72:75]
	v_cvt_scalef32_pk_bf16_fp8 v106, v22, 1.0
	v_cvt_scalef32_pk_bf16_fp8 v107, v22, 1.0 op_sel:[1,0,0]
	v_mfma_f32_4x4x4_16b_bf16 v[76:79], v[110:111], v[66:67], v[76:79]
	v_cvt_scalef32_pk_bf16_fp8 v108, v19, 1.0
	v_cvt_scalef32_pk_bf16_fp8 v109, v19, 1.0 op_sel:[1,0,0]
	v_mfma_f32_4x4x4_16b_bf16 v[72:75], v[104:105], v[68:69], v[72:75]
	v_cvt_scalef32_pk_bf16_fp8 v110, v23, 1.0
	v_cvt_scalef32_pk_bf16_fp8 v111, v23, 1.0 op_sel:[1,0,0]
	v_mfma_f32_4x4x4_16b_bf16 v[76:79], v[106:107], v[68:69], v[76:79]
	v_and_or_b32 v142, v142, s2, v240
	v_and_or_b32 v143, v143, s2, v240
	global_load_dwordx4 v[16:19], v142, s[80:81]
	global_load_dwordx4 v[20:23], v143, s[80:81]
	s_waitcnt vmcnt(16) lgkmcnt(0)
	ds_bpermute_b32 v142, v249, v135
	ds_bpermute_b32 v143, v250, v135
	v_cvt_scalef32_pk_bf16_fp8 v104, v24, 1.0
	v_cvt_scalef32_pk_bf16_fp8 v105, v24, 1.0 op_sel:[1,0,0]
	v_mfma_f32_4x4x4_16b_bf16 v[72:75], v[108:109], v[70:71], v[72:75]
	v_cvt_scalef32_pk_bf16_fp8 v106, v28, 1.0
	v_cvt_scalef32_pk_bf16_fp8 v107, v28, 1.0 op_sel:[1,0,0]
	v_mfma_f32_4x4x4_16b_bf16 v[76:79], v[110:111], v[70:71], v[76:79]
	v_cvt_scalef32_pk_bf16_fp8 v108, v25, 1.0
	v_cvt_scalef32_pk_bf16_fp8 v110, v29, 1.0
	v_cvt_scalef32_pk_bf16_fp8 v109, v25, 1.0 op_sel:[1,0,0]
	v_cvt_scalef32_pk_bf16_fp8 v111, v29, 1.0 op_sel:[1,0,0]
	v_cndmask_b32_e64 v148, v72, v73, s[88:89]
	v_cndmask_b32_e64 v149, v74, v75, s[88:89]
	v_cndmask_b32_e64 v92, v148, v149, s[86:87]
	v_mfma_f32_4x4x4_16b_bf16 v[72:75], v[104:105], v[64:65], 0
	v_cndmask_b32_e64 v150, v76, v77, s[88:89]
	v_cndmask_b32_e64 v151, v78, v79, s[88:89]
	v_cndmask_b32_e64 v93, v150, v151, s[86:87]
	v_mfma_f32_4x4x4_16b_bf16 v[76:79], v[106:107], v[64:65], 0
	v_cvt_scalef32_pk_bf16_fp8 v104, v26, 1.0
	v_cvt_scalef32_pk_bf16_fp8 v105, v26, 1.0 op_sel:[1,0,0]
	v_mfma_f32_4x4x4_16b_bf16 v[72:75], v[108:109], v[66:67], v[72:75]
	v_cvt_scalef32_pk_bf16_fp8 v106, v30, 1.0
	v_cvt_scalef32_pk_bf16_fp8 v107, v30, 1.0 op_sel:[1,0,0]
	v_mfma_f32_4x4x4_16b_bf16 v[76:79], v[110:111], v[66:67], v[76:79]
	v_cvt_scalef32_pk_bf16_fp8 v108, v27, 1.0
	v_cvt_scalef32_pk_bf16_fp8 v109, v27, 1.0 op_sel:[1,0,0]
	v_mfma_f32_4x4x4_16b_bf16 v[72:75], v[104:105], v[68:69], v[72:75]
	v_cvt_scalef32_pk_bf16_fp8 v110, v31, 1.0
	v_cvt_scalef32_pk_bf16_fp8 v111, v31, 1.0 op_sel:[1,0,0]
	v_mfma_f32_4x4x4_16b_bf16 v[76:79], v[106:107], v[68:69], v[76:79]
	v_and_or_b32 v244, v244, s2, v240
	v_and_or_b32 v245, v245, s2, v240
	global_load_dwordx4 v[24:27], v244, s[80:81]
	global_load_dwordx4 v[28:31], v245, s[80:81]
	s_waitcnt vmcnt(16) lgkmcnt(0)
; #define PG_ISSUE(BUF, TAB, e0_) do { const int isrc_ = ((e0_) < 64) ? myi0 : myi1; \
;       _Pragma("unroll") for (int e = 0; e < 8; ++e) { const int idx_ = __builtin_amdgcn_readlane(isrc_, ((e0_) + e) & 63); \
;         BUF[e] = *(const u32x4*)((TAB) + (size_t)idx_ * 1024 + lane * 16); } } while (0)
; DEV void peer_gather(const Params& P, int l, int m0, const int* idxs, const float* gs) {
;     ...
;     for (int e0 = 0; e0 < 128; e0 += 16) {
;       PG_ISSUE(b1, U, e0 + 8);
;       PG_U8(b0, 0, e0);
;       if (e0 + 16 < 128) PG_ISSUE(b0, U, e0 + 16); else PG_ISSUE(b0, V, 0);
;       PG_U8(b1, 0, e0 + 8);
	ds_bpermute_b32 v244, v251, v135
	ds_bpermute_b32 v245, v252, v135
	v_cvt_scalef32_pk_bf16_fp8 v104, v32, 1.0
	v_cvt_scalef32_pk_bf16_fp8 v105, v32, 1.0 op_sel:[1,0,0]
	v_mfma_f32_4x4x4_16b_bf16 v[72:75], v[108:109], v[70:71], v[72:75]
	v_cvt_scalef32_pk_bf16_fp8 v106, v36, 1.0
	v_cvt_scalef32_pk_bf16_fp8 v107, v36, 1.0 op_sel:[1,0,0]
	v_mfma_f32_4x4x4_16b_bf16 v[76:79], v[110:111], v[70:71], v[76:79]
	v_cvt_scalef32_pk_bf16_fp8 v108, v33, 1.0
	v_cvt_scalef32_pk_bf16_fp8 v110, v37, 1.0
	v_cvt_scalef32_pk_bf16_fp8 v109, v33, 1.0 op_sel:[1,0,0]
	v_cvt_scalef32_pk_bf16_fp8 v111, v37, 1.0 op_sel:[1,0,0]
	v_cndmask_b32_e64 v148, v72, v73, s[88:89]
	v_cndmask_b32_e64 v149, v74, v75, s[88:89]
	v_cndmask_b32_e64 v94, v148, v149, s[86:87]
	v_mfma_f32_4x4x4_16b_bf16 v[72:75], v[104:105], v[64:65], 0
	v_cndmask_b32_e64 v150, v76, v77, s[88:89]
	v_cndmask_b32_e64 v151, v78, v79, s[88:89]
	v_cndmask_b32_e64 v95, v150, v151, s[86:87]
	v_mfma_f32_4x4x4_16b_bf16 v[76:79], v[106:107], v[64:65], 0
	v_cvt_scalef32_pk_bf16_fp8 v104, v34, 1.0
	v_cvt_scalef32_pk_bf16_fp8 v105, v34, 1.0 op_sel:[1,0,0]
	v_mfma_f32_4x4x4_16b_bf16 v[72:75], v[108:109], v[66:67], v[72:75]
	v_cvt_scalef32_pk_bf16_fp8 v106, v38, 1.0
	v_cvt_scalef32_pk_bf16_fp8 v107, v38, 1.0 op_sel:[1,0,0]
	v_mfma_f32_4x4x4_16b_bf16 v[76:79], v[110:111], v[66:67], v[76:79]
	v_cvt_scalef32_pk_bf16_fp8 v108, v35, 1.0
	v_cvt_scalef32_pk_bf16_fp8 v109, v35, 1.0 op_sel:[1,0,0]
	v_mfma_f32_4x4x4_16b_bf16 v[72:75], v[104:105], v[68:69], v[72:75]
	v_cvt_scalef32_pk_bf16_fp8 v110, v39, 1.0
	v_cvt_scalef32_pk_bf16_fp8 v111, v39, 1.0 op_sel:[1,0,0]
	v_mfma_f32_4x4x4_16b_bf16 v[76:79], v[106:107], v[68:69], v[76:79]
	v_and_or_b32 v142, v142, s2, v240
	v_and_or_b32 v143, v143, s2, v240
	global_load_dwordx4 v[32:35], v142, s[80:81]
	global_load_dwordx4 v[36:39], v143, s[80:81]
	s_waitcnt vmcnt(16) lgkmcnt(0)
	ds_bpermute_b32 v142, v253, v135
	ds_bpermute_b32 v143, v254, v135
	v_cvt_scalef32_pk_bf16_fp8 v104, v40, 1.0
	v_cvt_scalef32_pk_bf16_fp8 v105, v40, 1.0 op_sel:[1,0,0]
	v_mfma_f32_4x4x4_16b_bf16 v[72:75], v[108:109], v[70:71], v[72:75]
	v_cvt_scalef32_pk_bf16_fp8 v106, v44, 1.0
	v_cvt_scalef32_pk_bf16_fp8 v107, v44, 1.0 op_sel:[1,0,0]
	v_mfma_f32_4x4x4_16b_bf16 v[76:79], v[110:111], v[70:71], v[76:79]
	v_cvt_scalef32_pk_bf16_fp8 v108, v41, 1.0
	v_cvt_scalef32_pk_bf16_fp8 v110, v45, 1.0
	v_cvt_scalef32_pk_bf16_fp8 v109, v41, 1.0 op_sel:[1,0,0]
	v_cvt_scalef32_pk_bf16_fp8 v111, v45, 1.0 op_sel:[1,0,0]
	v_cndmask_b32_e64 v148, v72, v73, s[88:89]
	v_cndmask_b32_e64 v149, v74, v75, s[88:89]
	v_cndmask_b32_e64 v96, v148, v149, s[86:87]
	v_mfma_f32_4x4x4_16b_bf16 v[72:75], v[104:105], v[64:65], 0
	v_cndmask_b32_e64 v150, v76, v77, s[88:89]
	v_cndmask_b32_e64 v151, v78, v79, s[88:89]
	v_cndmask_b32_e64 v97, v150, v151, s[86:87]
	v_mfma_f32_4x4x4_16b_bf16 v[76:79], v[106:107], v[64:65], 0
	v_cvt_scalef32_pk_bf16_fp8 v104, v42, 1.0
	v_cvt_scalef32_pk_bf16_fp8 v105, v42, 1.0 op_sel:[1,0,0]
	v_mfma_f32_4x4x4_16b_bf16 v[72:75], v[108:109], v[66:67], v[72:75]
	v_cvt_scalef32_pk_bf16_fp8 v106, v46, 1.0
	v_cvt_scalef32_pk_bf16_fp8 v107, v46, 1.0 op_sel:[1,0,0]
	v_mfma_f32_4x4x4_16b_bf16 v[76:79], v[110:111], v[66:67], v[76:79]
	v_cvt_scalef32_pk_bf16_fp8 v108, v43, 1.0
	v_cvt_scalef32_pk_bf16_fp8 v109, v43, 1.0 op_sel:[1,0,0]
	v_mfma_f32_4x4x4_16b_bf16 v[72:75], v[104:105], v[68:69], v[72:75]
	v_cvt_scalef32_pk_bf16_fp8 v110, v47, 1.0
	v_cvt_scalef32_pk_bf16_fp8 v111, v47, 1.0 op_sel:[1,0,0]
	v_mfma_f32_4x4x4_16b_bf16 v[76:79], v[106:107], v[68:69], v[76:79]
	v_and_or_b32 v244, v244, s2, v240
	v_and_or_b32 v245, v245, s2, v240
	global_load_dwordx4 v[40:43], v244, s[80:81]
	global_load_dwordx4 v[44:47], v245, s[80:81]
	s_waitcnt vmcnt(16) lgkmcnt(0)
	ds_bpermute_b32 v244, v255, v135
	ds_bpermute_b32 v245, v153, v135
	v_cvt_scalef32_pk_bf16_fp8 v104, v48, 1.0
	v_cvt_scalef32_pk_bf16_fp8 v105, v48, 1.0 op_sel:[1,0,0]
	v_mfma_f32_4x4x4_16b_bf16 v[72:75], v[108:109], v[70:71], v[72:75]
	v_cvt_scalef32_pk_bf16_fp8 v106, v52, 1.0
	v_cvt_scalef32_pk_bf16_fp8 v107, v52, 1.0 op_sel:[1,0,0]
	v_mfma_f32_4x4x4_16b_bf16 v[76:79], v[110:111], v[70:71], v[76:79]
	v_cvt_scalef32_pk_bf16_fp8 v108, v49, 1.0
	v_cvt_scalef32_pk_bf16_fp8 v110, v53, 1.0
	v_cvt_scalef32_pk_bf16_fp8 v109, v49, 1.0 op_sel:[1,0,0]
	v_cvt_scalef32_pk_bf16_fp8 v111, v53, 1.0 op_sel:[1,0,0]
	v_cndmask_b32_e64 v148, v72, v73, s[88:89]
	v_cndmask_b32_e64 v149, v74, v75, s[88:89]
	v_cndmask_b32_e64 v98, v148, v149, s[86:87]
	v_mfma_f32_4x4x4_16b_bf16 v[72:75], v[104:105], v[64:65], 0
	v_cndmask_b32_e64 v150, v76, v77, s[88:89]
	v_cndmask_b32_e64 v151, v78, v79, s[88:89]
	v_cndmask_b32_e64 v99, v150, v151, s[86:87]
	v_mfma_f32_4x4x4_16b_bf16 v[76:79], v[106:107], v[64:65], 0
	v_cvt_scalef32_pk_bf16_fp8 v104, v50, 1.0
	v_cvt_scalef32_pk_bf16_fp8 v105, v50, 1.0 op_sel:[1,0,0]
	v_mfma_f32_4x4x4_16b_bf16 v[72:75], v[108:109], v[66:67], v[72:75]
	v_cvt_scalef32_pk_bf16_fp8 v106, v54, 1.0
	v_cvt_scalef32_pk_bf16_fp8 v107, v54, 1.0 op_sel:[1,0,0]
	v_mfma_f32_4x4x4_16b_bf16 v[76:79], v[110:111], v[66:67], v[76:79]
	v_cvt_scalef32_pk_bf16_fp8 v108, v51, 1.0
	v_cvt_scalef32_pk_bf16_fp8 v109, v51, 1.0 op_sel:[1,0,0]
	v_mfma_f32_4x4x4_16b_bf16 v[72:75], v[104:105], v[68:69], v[72:75]
	v_cvt_scalef32_pk_bf16_fp8 v110, v55, 1.0
	v_cvt_scalef32_pk_bf16_fp8 v111, v55, 1.0 op_sel:[1,0,0]
	v_mfma_f32_4x4x4_16b_bf16 v[76:79], v[106:107], v[68:69], v[76:79]
	v_and_or_b32 v142, v142, s2, v240
	v_and_or_b32 v143, v143, s2, v240
	global_load_dwordx4 v[48:51], v142, s[80:81]
	global_load_dwordx4 v[52:55], v143, s[80:81]
	s_waitcnt vmcnt(16) lgkmcnt(0)
; #define PG_ISSUE(BUF, TAB, e0_) do { const int isrc_ = ((e0_) < 64) ? myi0 : myi1; \
;       _Pragma("unroll") for (int e = 0; e < 8; ++e) { const int idx_ = __builtin_amdgcn_readlane(isrc_, ((e0_) + e) & 63); \
;         BUF[e] = *(const u32x4*)((TAB) + (size_t)idx_ * 1024 + lane * 16); } } while (0)
; DEV void peer_gather(const Params& P, int l, int m0, const int* idxs, const float* gs) {
;     ...
;     PG_ISSUE(b0, U, 0);
; #pragma nounroll
;     for (int e0 = 0; e0 < 128; e0 += 16) {
;       PG_ISSUE(b1, U, e0 + 8);
;       PG_U8(b0, 0, e0);
;       if (e0 + 16 < 128) PG_ISSUE(b0, U, e0 + 16); else PG_ISSUE(b0, V, 0);
;       PG_U8(b1, 0, e0 + 8);
;     }
	v_cvt_scalef32_pk_bf16_fp8 v104, v56, 1.0
	v_cvt_scalef32_pk_bf16_fp8 v105, v56, 1.0 op_sel:[1,0,0]
	v_mfma_f32_4x4x4_16b_bf16 v[72:75], v[108:109], v[70:71], v[72:75]
	v_cvt_scalef32_pk_bf16_fp8 v106, v60, 1.0
	v_cvt_scalef32_pk_bf16_fp8 v107, v60, 1.0 op_sel:[1,0,0]
	v_mfma_f32_4x4x4_16b_bf16 v[76:79], v[110:111], v[70:71], v[76:79]
	v_cvt_scalef32_pk_bf16_fp8 v108, v57, 1.0
	v_cvt_scalef32_pk_bf16_fp8 v110, v61, 1.0
	v_cvt_scalef32_pk_bf16_fp8 v109, v57, 1.0 op_sel:[1,0,0]
	v_cvt_scalef32_pk_bf16_fp8 v111, v61, 1.0 op_sel:[1,0,0]
	v_cndmask_b32_e64 v148, v72, v73, s[88:89]
	v_cndmask_b32_e64 v149, v74, v75, s[88:89]
	v_cndmask_b32_e64 v100, v148, v149, s[86:87]
	v_mfma_f32_4x4x4_16b_bf16 v[72:75], v[104:105], v[64:65], 0
	v_cndmask_b32_e64 v150, v76, v77, s[88:89]
	v_cndmask_b32_e64 v151, v78, v79, s[88:89]
	v_cndmask_b32_e64 v101, v150, v151, s[86:87]
	v_mfma_f32_4x4x4_16b_bf16 v[76:79], v[106:107], v[64:65], 0
	v_cvt_scalef32_pk_bf16_fp8 v104, v58, 1.0
	v_cvt_scalef32_pk_bf16_fp8 v105, v58, 1.0 op_sel:[1,0,0]
	v_mfma_f32_4x4x4_16b_bf16 v[72:75], v[108:109], v[66:67], v[72:75]
	v_cvt_scalef32_pk_bf16_fp8 v106, v62, 1.0
	v_cvt_scalef32_pk_bf16_fp8 v107, v62, 1.0 op_sel:[1,0,0]
	v_mfma_f32_4x4x4_16b_bf16 v[76:79], v[110:111], v[66:67], v[76:79]
	v_cvt_scalef32_pk_bf16_fp8 v108, v59, 1.0
	v_cvt_scalef32_pk_bf16_fp8 v109, v59, 1.0 op_sel:[1,0,0]
	v_mfma_f32_4x4x4_16b_bf16 v[72:75], v[104:105], v[68:69], v[72:75]
	v_cvt_scalef32_pk_bf16_fp8 v110, v63, 1.0
	v_cvt_scalef32_pk_bf16_fp8 v111, v63, 1.0 op_sel:[1,0,0]
	v_mfma_f32_4x4x4_16b_bf16 v[76:79], v[106:107], v[68:69], v[76:79]
	v_and_or_b32 v244, v244, s2, v240
	v_and_or_b32 v245, v245, s2, v240
	global_load_dwordx4 v[56:59], v244, s[80:81]
	global_load_dwordx4 v[60:63], v245, s[80:81]
	v_mfma_f32_4x4x4_16b_bf16 v[72:75], v[108:109], v[70:71], v[72:75]
	v_mfma_f32_4x4x4_16b_bf16 v[76:79], v[110:111], v[70:71], v[76:79]
	s_add_u32 s92, s100, 2
	s_and_b32 s92, s92, 15
	v_lshl_add_u32 v116, s92, 9, v246
	ds_read_b32 v134, v116
	ds_read_b32 v135, v116 offset:256
	v_lshl_add_u32 v117, s98, 9, v247
	ds_read_b32 v136, v117
	ds_read_b32 v137, v117 offset:256
	v_cndmask_b32_e64 v148, v72, v73, s[88:89]
	v_cndmask_b32_e64 v149, v74, v75, s[88:89]
	v_cndmask_b32_e64 v102, v148, v149, s[86:87]
	v_cndmask_b32_e64 v150, v76, v77, s[88:89]
	v_cndmask_b32_e64 v151, v78, v79, s[88:89]
	v_cndmask_b32_e64 v103, v150, v151, s[86:87]
	v_cndmask_b32_e64 v144, v88, v92, s[90:91]
	v_cndmask_b32_e64 v92, v92, v88, s[90:91]
	v_cndmask_b32_e64 v145, v89, v93, s[90:91]
	v_cndmask_b32_e64 v93, v93, v89, s[90:91]
	v_cndmask_b32_e64 v146, v90, v94, s[90:91]
	v_cndmask_b32_e64 v94, v94, v90, s[90:91]
	v_cndmask_b32_e64 v147, v91, v95, s[90:91]
	v_cndmask_b32_e64 v95, v95, v91, s[90:91]
	v_add_f32_dpp v88, v92, v144 row_half_mirror row_mask:0xf bank_mask:0xf
	v_add_f32_dpp v89, v93, v145 row_half_mirror row_mask:0xf bank_mask:0xf
	v_add_f32_dpp v90, v94, v146 row_half_mirror row_mask:0xf bank_mask:0xf
	v_add_f32_dpp v91, v95, v147 row_half_mirror row_mask:0xf bank_mask:0xf
	v_cndmask_b32_e64 v144, v96, v100, s[90:91]
	v_cndmask_b32_e64 v100, v100, v96, s[90:91]
	v_cndmask_b32_e64 v145, v97, v101, s[90:91]
	v_cndmask_b32_e64 v101, v101, v97, s[90:91]
	v_cndmask_b32_e64 v146, v98, v102, s[90:91]
	v_cndmask_b32_e64 v102, v102, v98, s[90:91]
	v_cndmask_b32_e64 v147, v99, v103, s[90:91]
	v_cndmask_b32_e64 v103, v103, v99, s[90:91]
	v_add_f32_dpp v96, v100, v144 row_half_mirror row_mask:0xf bank_mask:0xf
	v_add_f32_dpp v97, v101, v145 row_half_mirror row_mask:0xf bank_mask:0xf
	v_add_f32_dpp v98, v102, v146 row_half_mirror row_mask:0xf bank_mask:0xf
	v_add_f32_dpp v99, v103, v147 row_half_mirror row_mask:0xf bank_mask:0xf
	v_cndmask_b32_e64 v144, v88, v90, s[86:87]
	v_cndmask_b32_e64 v90, v90, v88, s[86:87]
	v_cndmask_b32_e64 v145, v89, v91, s[86:87]
	v_cndmask_b32_e64 v91, v91, v89, s[86:87]
	v_cndmask_b32_e64 v146, v96, v98, s[86:87]
	v_cndmask_b32_e64 v98, v98, v96, s[86:87]
	v_cndmask_b32_e64 v147, v97, v99, s[86:87]
	v_cndmask_b32_e64 v99, v99, v97, s[86:87]
	v_add_f32_dpp v88, v90, v144 quad_perm:[2,3,0,1] row_mask:0xf bank_mask:0xf
	v_add_f32_dpp v89, v91, v145 quad_perm:[2,3,0,1] row_mask:0xf bank_mask:0xf
	v_add_f32_dpp v96, v98, v146 quad_perm:[2,3,0,1] row_mask:0xf bank_mask:0xf
	v_add_f32_dpp v97, v99, v147 quad_perm:[2,3,0,1] row_mask:0xf bank_mask:0xf
	v_cndmask_b32_e64 v144, v88, v89, s[88:89]
	v_cndmask_b32_e64 v89, v89, v88, s[88:89]
	v_cndmask_b32_e64 v145, v96, v97, s[88:89]
	v_cndmask_b32_e64 v97, v97, v96, s[88:89]
	s_nop 1
	v_add_f32_dpp v88, v89, v144 quad_perm:[1,0,3,2] row_mask:0xf bank_mask:0xf
	v_add_f32_dpp v96, v97, v145 quad_perm:[1,0,3,2] row_mask:0xf bank_mask:0xf
	s_nop 0
	ds_bpermute_b32 v144, v239, v88
	ds_bpermute_b32 v145, v239, v96
	s_waitcnt lgkmcnt(0)
	v_add_f32_e32 v136, v136, v144
	v_add_f32_e32 v137, v137, v145
	ds_write_b32 v117, v136
	ds_write_b32 v117, v137 offset:256
	s_add_u32 s100, s100, 1
	s_cmp_lt_u32 s100, 128
	s_cbranch_scc1 .Lpg0_uloop
	s_waitcnt vmcnt(0) lgkmcnt(0)
	s_mov_b32 s2, 0
.Lpg0_act:
	v_readlane_b32 s82, v231, 28
	v_readlane_b32 s83, v231, 29
	s_nop 4
	s_lshl_b32 s98, s2, 11
	s_add_u32 s98, s98, s101
	v_add_u32_e32 v116, s98, v234
	v_add_u32_e32 v117, 0x10000, v116
	ds_read_b32 v0, v116 offset:0
	ds_read_b32 v8, v117 offset:0
	ds_read_b32 v1, v116 offset:256
	ds_read_b32 v9, v117 offset:256
	ds_read_b32 v2, v116 offset:512
	ds_read_b32 v10, v117 offset:512
	ds_read_b32 v3, v116 offset:768
	ds_read_b32 v11, v117 offset:768
	ds_read_b32 v4, v116 offset:1024
	ds_read_b32 v12, v117 offset:1024
	ds_read_b32 v5, v116 offset:1280
	ds_read_b32 v13, v117 offset:1280
	ds_read_b32 v6, v116 offset:1536
	ds_read_b32 v14, v117 offset:1536
	ds_read_b32 v7, v116 offset:1792
	ds_read_b32 v15, v117 offset:1792
	s_waitcnt lgkmcnt(0)
	s_lshl_b32 s99, s2, 2
	s_add_u32 s99, s99, s33
	s_add_u32 s99, s99, 0
	s_lshl_b32 s99, s99, 9
	v_and_b32_e32 v0, 0x7f, v0
	v_lshl_add_u32 v0, v0, 2, s99
	global_load_dword v16, v0, s[82:83]
	v_and_b32_e32 v1, 0x7f, v1
	v_lshl_add_u32 v1, v1, 2, s99
	global_load_dword v17, v1, s[82:83]
	s_lshl_b32 s99, s2, 2
	s_add_u32 s99, s99, s33
	s_add_u32 s99, s99, 1
	s_lshl_b32 s99, s99, 9
	v_and_b32_e32 v2, 0x7f, v2
	v_lshl_add_u32 v2, v2, 2, s99
	global_load_dword v18, v2, s[82:83]
	v_and_b32_e32 v3, 0x7f, v3
	v_lshl_add_u32 v3, v3, 2, s99
	global_load_dword v19, v3, s[82:83]
	s_lshl_b32 s99, s2, 2
	s_add_u32 s99, s99, s33
	s_add_u32 s99, s99, 2
	s_lshl_b32 s99, s99, 9
	v_and_b32_e32 v4, 0x7f, v4
	v_lshl_add_u32 v4, v4, 2, s99
	global_load_dword v20, v4, s[82:83]
	v_and_b32_e32 v5, 0x7f, v5
	v_lshl_add_u32 v5, v5, 2, s99
	global_load_dword v21, v5, s[82:83]
	s_lshl_b32 s99, s2, 2
	s_add_u32 s99, s99, s33
	s_add_u32 s99, s99, 3
	s_lshl_b32 s99, s99, 9
	v_and_b32_e32 v6, 0x7f, v6
	v_lshl_add_u32 v6, v6, 2, s99
	global_load_dword v22, v6, s[82:83]
	v_and_b32_e32 v7, 0x7f, v7
	v_lshl_add_u32 v7, v7, 2, s99
	global_load_dword v23, v7, s[82:83]
	v_mul_f32_e32 v8, 0x3c800000, v8
	v_mul_f32_e32 v9, 0x3c800000, v9
	v_mul_f32_e32 v10, 0x3c800000, v10
	v_mul_f32_e32 v11, 0x3c800000, v11
	v_mul_f32_e32 v12, 0x3c800000, v12
	v_mul_f32_e32 v13, 0x3c800000, v13
	v_mul_f32_e32 v14, 0x3c800000, v14
	v_mul_f32_e32 v15, 0x3c800000, v15
	v_mul_f32_e32 v24, 0x3d372713, v8
	v_mul_f32_e32 v25, 0x3d372713, v9
	v_mul_f32_e32 v26, 0x3d372713, v10
	v_mul_f32_e32 v27, 0x3d372713, v11
	v_mul_f32_e32 v28, 0x3d372713, v12
	v_mul_f32_e32 v29, 0x3d372713, v13
	v_mul_f32_e32 v30, 0x3d372713, v14
	v_mul_f32_e32 v31, 0x3d372713, v15
	v_mul_f32_e32 v24, v8, v24
	v_mul_f32_e32 v25, v9, v25
	v_mul_f32_e32 v26, v10, v26
	v_mul_f32_e32 v27, v11, v27
	v_mul_f32_e32 v28, v12, v28
	v_mul_f32_e32 v29, v13, v29
	v_mul_f32_e32 v30, v14, v30
	v_mul_f32_e32 v31, v15, v31
	v_fma_f32 v24, v8, v24, v8
	v_fma_f32 v25, v9, v25, v9
	v_fma_f32 v26, v10, v26, v10
	v_fma_f32 v27, v11, v27, v11
	v_fma_f32 v28, v12, v28, v12
	v_fma_f32 v29, v13, v29, v13
	v_fma_f32 v30, v14, v30, v14
	v_fma_f32 v31, v15, v31, v15
	v_mul_f32_e32 v24, 0xbfcc422a, v24
	v_mul_f32_e32 v25, 0xbfcc422a, v25
	v_mul_f32_e32 v26, 0xbfcc422a, v26
	v_mul_f32_e32 v27, 0xbfcc422a, v27
	v_mul_f32_e32 v28, 0xbfcc422a, v28
	v_mul_f32_e32 v29, 0xbfcc422a, v29
	v_mul_f32_e32 v30, 0xbfcc422a, v30
	v_mul_f32_e32 v31, 0xbfcc422a, v31
	v_mul_f32_e32 v24, 0x3fb8aa3b, v24
	v_mul_f32_e32 v25, 0x3fb8aa3b, v25
	v_mul_f32_e32 v26, 0x3fb8aa3b, v26
	v_mul_f32_e32 v27, 0x3fb8aa3b, v27
	v_mul_f32_e32 v28, 0x3fb8aa3b, v28
	v_mul_f32_e32 v29, 0x3fb8aa3b, v29
	v_mul_f32_e32 v30, 0x3fb8aa3b, v30
	v_mul_f32_e32 v31, 0x3fb8aa3b, v31
	v_exp_f32_e32 v24, v24
	v_exp_f32_e32 v25, v25
	v_exp_f32_e32 v26, v26
	v_exp_f32_e32 v27, v27
	v_exp_f32_e32 v28, v28
	v_exp_f32_e32 v29, v29
	v_exp_f32_e32 v30, v30
	v_exp_f32_e32 v31, v31
	s_nop 0
	v_add_f32_e32 v24, 1.0, v24
	v_add_f32_e32 v25, 1.0, v25
	v_add_f32_e32 v26, 1.0, v26
	v_add_f32_e32 v27, 1.0, v27
	v_add_f32_e32 v28, 1.0, v28
	v_add_f32_e32 v29, 1.0, v29
	v_add_f32_e32 v30, 1.0, v30
	v_add_f32_e32 v31, 1.0, v31
	v_rcp_f32_e32 v24, v24
	v_rcp_f32_e32 v25, v25
	v_rcp_f32_e32 v26, v26
	v_rcp_f32_e32 v27, v27
	v_rcp_f32_e32 v28, v28
	v_rcp_f32_e32 v29, v29
	v_rcp_f32_e32 v30, v30
	v_rcp_f32_e32 v31, v31
	s_nop 0
	v_mul_f32_e32 v24, v8, v24
	v_mul_f32_e32 v25, v9, v25
	v_mul_f32_e32 v26, v10, v26
	v_mul_f32_e32 v27, v11, v27
	v_mul_f32_e32 v28, v12, v28
	v_mul_f32_e32 v29, v13, v29
	v_mul_f32_e32 v30, v14, v30
	v_mul_f32_e32 v31, v15, v31
	s_waitcnt vmcnt(0)
	v_mul_f32_e32 v24, v24, v16
	ds_write_b32 v117, v24 offset:0
	v_mul_f32_e32 v25, v25, v17
	ds_write_b32 v117, v25 offset:256
	v_mul_f32_e32 v26, v26, v18
	ds_write_b32 v117, v26 offset:512
	v_mul_f32_e32 v27, v27, v19
	ds_write_b32 v117, v27 offset:768
	v_mul_f32_e32 v28, v28, v20
	ds_write_b32 v117, v28 offset:1024
	v_mul_f32_e32 v29, v29, v21
	ds_write_b32 v117, v29 offset:1280
	v_mul_f32_e32 v30, v30, v22
	ds_write_b32 v117, v30 offset:1536
	v_mul_f32_e32 v31, v31, v23
	ds_write_b32 v117, v31 offset:1792
	s_add_u32 s2, s2, 1
	s_cmp_lt_u32 s2, 4
	s_cbranch_scc1 .Lpg0_act
; #define PG_ISSUE(BUF, TAB, e0_) do { const int isrc_ = ((e0_) < 64) ? myi0 : myi1; \
;       _Pragma("unroll") for (int e = 0; e < 8; ++e) { const int idx_ = __builtin_amdgcn_readlane(isrc_, ((e0_) + e) & 63); \
;         BUF[e] = *(const u32x4*)((TAB) + (size_t)idx_ * 1024 + lane * 16); } } while (0)
; DEV void peer_gather(const Params& P, int l, int m0, const int* idxs, const float* gs) {
;     ...
;     PG_ISSUE(b0, U, 0);
; #pragma nounroll
;     for (int e0 = 0; e0 < 128; e0 += 16) {
;       PG_ISSUE(b1, U, e0 + 8);
;       PG_U8(b0, 0, e0);
;       if (e0 + 16 < 128) PG_ISSUE(b0, U, e0 + 16); else PG_ISSUE(b0, V, 0);
;       PG_U8(b1, 0, e0 + 8);
;     }
;     float* hrow = P.out + tok * DM + lane * 16;
;     f32x4 hv[4];
; #pragma unroll
;     for (int q = 0; q < 4; ++q) hv[q] = *(const f32x4*)(hrow + 4 * q);
;     if (i + 1 < 16) {
;       const int tn = tt + 1;
;       nxa = *(const u32x4*)(hn + (size_t)(m0 + tn) * DM + lane * 16); nxb = *(const u32x4*)(hn + (size_t)(m0 + tn) * DM + lane * 16 + 8);
;       ni0 = idxs[tn * 128 + lane]; ni1 = idxs[tn * 128 + 64 + lane]; ng0 = gs[tn * 128 + lane]; ng1 = gs[tn * 128 + 64 + lane];
;     }
; #pragma nounroll
;     for (int e0 = 0; e0 < 128; e0 += 16) {
;       PG_ISSUE(b1, V, e0 + 8);
;       if (e0 == 64 && i + 1 < 16) sort_lists(lane, ni0, ni1, ng0, ng1);
;       PG_V16(b0, e0);
;       if (e0 + 16 < 128) PG_ISSUE(b0, V, e0 + 16);
;       PG_V16(b1, e0 + 8);
;     }
	s_waitcnt lgkmcnt(0)
	v_add_u32_e32 v249, 0, v237
	v_add_u32_e32 v250, 32, v237
	v_add_u32_e32 v251, 64, v237
	v_add_u32_e32 v252, 96, v237
	v_add_u32_e32 v253, 128, v237
	v_add_u32_e32 v254, 160, v237
	v_add_u32_e32 v255, 192, v237
	v_add_u32_e32 v153, 224, v237
	v_readfirstlane_b32 s80, v126
	v_readfirstlane_b32 s81, v127
	s_nop 4
	v_add_u32_e32 v246, s101, v234
	v_add_u32_e32 v247, 0x10000, v246
	v_readfirstlane_b32 s82, v132
	v_readfirstlane_b32 s83, v133
	s_nop 4
	s_mov_b32 s2, 0xffffff80
	s_lshl_b32 vcc_lo, s3, 12
	s_add_u32 s82, s82, vcc_lo
	s_addc_u32 s83, s83, 0
	s_mov_b32 s88, 0xff00ff00
	s_mov_b32 s89, 0xff00ff00
	s_mov_b32 s100, 0
	s_mov_b32 s98, 0
	s_mov_b32 s99, 0
	v_lshl_add_u32 v116, s98, 9, v246
	ds_read_b32 v134, v116
	ds_read_b32 v135, v116 offset:256
	v_lshl_or_b32 v240, s99, 21, v235
	s_waitcnt lgkmcnt(0)
	ds_bpermute_b32 v142, v249, v134
	ds_bpermute_b32 v143, v250, v134
	s_waitcnt lgkmcnt(0)
	v_and_or_b32 v142, v142, s2, v240
	v_and_or_b32 v143, v143, s2, v240
	global_load_dwordx4 v[0:3], v142, s[80:81]
	global_load_dwordx4 v[4:7], v143, s[80:81]
	ds_bpermute_b32 v142, v251, v134
	ds_bpermute_b32 v143, v252, v134
	s_waitcnt lgkmcnt(0)
	v_and_or_b32 v142, v142, s2, v240
	v_and_or_b32 v143, v143, s2, v240
	global_load_dwordx4 v[8:11], v142, s[80:81]
	global_load_dwordx4 v[12:15], v143, s[80:81]
	ds_bpermute_b32 v142, v253, v134
	ds_bpermute_b32 v143, v254, v134
	s_waitcnt lgkmcnt(0)
	v_and_or_b32 v142, v142, s2, v240
	v_and_or_b32 v143, v143, s2, v240
	global_load_dwordx4 v[16:19], v142, s[80:81]
	global_load_dwordx4 v[20:23], v143, s[80:81]
	ds_bpermute_b32 v142, v255, v134
	ds_bpermute_b32 v143, v153, v134
	s_waitcnt lgkmcnt(0)
	v_and_or_b32 v142, v142, s2, v240
	v_and_or_b32 v143, v143, s2, v240
	global_load_dwordx4 v[24:27], v142, s[80:81]
	global_load_dwordx4 v[28:31], v143, s[80:81]
	ds_bpermute_b32 v142, v249, v135
	ds_bpermute_b32 v143, v250, v135
	s_waitcnt lgkmcnt(0)
	v_and_or_b32 v142, v142, s2, v240
	v_and_or_b32 v143, v143, s2, v240
	global_load_dwordx4 v[32:35], v142, s[80:81]
	global_load_dwordx4 v[36:39], v143, s[80:81]
	ds_bpermute_b32 v142, v251, v135
	ds_bpermute_b32 v143, v252, v135
	s_waitcnt lgkmcnt(0)
	v_and_or_b32 v142, v142, s2, v240
	v_and_or_b32 v143, v143, s2, v240
	global_load_dwordx4 v[40:43], v142, s[80:81]
	global_load_dwordx4 v[44:47], v143, s[80:81]
	ds_bpermute_b32 v142, v253, v135
	ds_bpermute_b32 v143, v254, v135
	s_waitcnt lgkmcnt(0)
	v_and_or_b32 v142, v142, s2, v240
	v_and_or_b32 v143, v143, s2, v240
	global_load_dwordx4 v[48:51], v142, s[80:81]
	global_load_dwordx4 v[52:55], v143, s[80:81]
	ds_bpermute_b32 v142, v255, v135
	ds_bpermute_b32 v143, v153, v135
	s_waitcnt lgkmcnt(0)
	v_and_or_b32 v142, v142, s2, v240
	v_and_or_b32 v143, v143, s2, v240
	global_load_dwordx4 v[56:59], v142, s[80:81]
	global_load_dwordx4 v[60:63], v143, s[80:81]
	s_mov_b32 s92, 1
	v_lshl_add_u32 v116, s92, 9, v246
	ds_read_b32 v134, v116
	ds_read_b32 v135, v116 offset:256
	v_lshl_add_u32 v117, s98, 9, v247
	ds_read_b32 v136, v117
	ds_read_b32 v137, v117 offset:256
	s_waitcnt vmcnt(0)
.Lpg0_vloop:
	s_and_b32 s98, s100, 15
	s_lshr_b32 s99, s100, 4
	s_add_u32 s93, s100, 1
	s_min_u32 s93, s93, 127
	s_lshr_b32 s93, s93, 4
	s_lshl3_add_u32 vcc_lo, s98, s99
	v_lshl_add_u32 v119, vcc_lo, 9, v238
	global_load_dword v80, v119, s[82:83]
	global_load_dword v81, v119, s[82:83] offset:32
	v_lshl_or_b32 v240, s93, 21, v235
	s_waitcnt lgkmcnt(0)
	ds_bpermute_b32 v138, v249, v136
	ds_bpermute_b32 v140, v250, v136
	ds_bpermute_b32 v142, v249, v134
	ds_bpermute_b32 v143, v250, v134
	ds_bpermute_b32 v244, v251, v134
	ds_bpermute_b32 v245, v252, v134
	ds_bpermute_b32 v144, v251, v136
	ds_bpermute_b32 v146, v252, v136
	s_waitcnt vmcnt(18) lgkmcnt(4)
	v_cvt_pk_f32_fp8_e32 v[104:105], v0
	v_cvt_pk_f32_fp8_e32 v[108:109], v4
	v_cvt_pk_f32_fp8_sdwa v[106:107], v0 src0_sel:WORD_1
	v_cvt_pk_f32_fp8_sdwa v[110:111], v4 src0_sel:WORD_1
	v_pk_mul_f32 v[64:65], v[104:105], v[138:139] op_sel_hi:[1,0]
	v_pk_mul_f32 v[66:67], v[106:107], v[138:139] op_sel_hi:[1,0]
	v_pk_fma_f32 v[64:65], v[108:109], v[140:141], v[64:65] op_sel_hi:[1,0,1]
	v_pk_fma_f32 v[66:67], v[110:111], v[140:141], v[66:67] op_sel_hi:[1,0,1]
	v_cvt_pk_f32_fp8_e32 v[104:105], v1
	v_cvt_pk_f32_fp8_e32 v[108:109], v5
	v_cvt_pk_f32_fp8_sdwa v[106:107], v1 src0_sel:WORD_1
	v_cvt_pk_f32_fp8_sdwa v[110:111], v5 src0_sel:WORD_1
	v_pk_mul_f32 v[68:69], v[104:105], v[138:139] op_sel_hi:[1,0]
	v_pk_mul_f32 v[70:71], v[106:107], v[138:139] op_sel_hi:[1,0]
	v_pk_fma_f32 v[68:69], v[108:109], v[140:141], v[68:69] op_sel_hi:[1,0,1]
	v_pk_fma_f32 v[70:71], v[110:111], v[140:141], v[70:71] op_sel_hi:[1,0,1]
	v_cvt_pk_f32_fp8_e32 v[104:105], v2
	v_cvt_pk_f32_fp8_e32 v[108:109], v6
	v_cvt_pk_f32_fp8_sdwa v[106:107], v2 src0_sel:WORD_1
	v_cvt_pk_f32_fp8_sdwa v[110:111], v6 src0_sel:WORD_1
	v_pk_mul_f32 v[72:73], v[104:105], v[138:139] op_sel_hi:[1,0]
	v_pk_mul_f32 v[74:75], v[106:107], v[138:139] op_sel_hi:[1,0]
	v_pk_fma_f32 v[72:73], v[108:109], v[140:141], v[72:73] op_sel_hi:[1,0,1]
	v_pk_fma_f32 v[74:75], v[110:111], v[140:141], v[74:75] op_sel_hi:[1,0,1]
	v_cvt_pk_f32_fp8_e32 v[104:105], v3
	v_cvt_pk_f32_fp8_e32 v[108:109], v7
	v_cvt_pk_f32_fp8_sdwa v[106:107], v3 src0_sel:WORD_1
	v_cvt_pk_f32_fp8_sdwa v[110:111], v7 src0_sel:WORD_1
	v_pk_mul_f32 v[76:77], v[104:105], v[138:139] op_sel_hi:[1,0]
	v_pk_mul_f32 v[78:79], v[106:107], v[138:139] op_sel_hi:[1,0]
	v_and_or_b32 v142, v142, s2, v240
	v_and_or_b32 v143, v143, s2, v240
	global_load_dwordx4 v[0:3], v142, s[80:81]
	global_load_dwordx4 v[4:7], v143, s[80:81]
	v_pk_fma_f32 v[76:77], v[108:109], v[140:141], v[76:77] op_sel_hi:[1,0,1]
	v_pk_fma_f32 v[78:79], v[110:111], v[140:141], v[78:79] op_sel_hi:[1,0,1]
	ds_bpermute_b32 v142, v253, v134
	ds_bpermute_b32 v143, v254, v134
	ds_bpermute_b32 v138, v253, v136
	ds_bpermute_b32 v140, v254, v136
	s_waitcnt vmcnt(18) lgkmcnt(4)
; #define PG_ISSUE(BUF, TAB, e0_) do { const int isrc_ = ((e0_) < 64) ? myi0 : myi1; \
;       _Pragma("unroll") for (int e = 0; e < 8; ++e) { const int idx_ = __builtin_amdgcn_readlane(isrc_, ((e0_) + e) & 63); \
;         BUF[e] = *(const u32x4*)((TAB) + (size_t)idx_ * 1024 + lane * 16); } } while (0)
; DEV void peer_gather(const Params& P, int l, int m0, const int* idxs, const float* gs) {
;     ...
;     for (int e0 = 0; e0 < 128; e0 += 16) {
;       PG_ISSUE(b1, V, e0 + 8);
;       if (e0 == 64 && i + 1 < 16) sort_lists(lane, ni0, ni1, ng0, ng1);
;       PG_V16(b0, e0);
;       if (e0 + 16 < 128) PG_ISSUE(b0, V, e0 + 16);
;       PG_V16(b1, e0 + 8);
;     }
	v_cvt_pk_f32_fp8_e32 v[104:105], v8
	v_cvt_pk_f32_fp8_e32 v[108:109], v12
	v_cvt_pk_f32_fp8_sdwa v[106:107], v8 src0_sel:WORD_1
	v_cvt_pk_f32_fp8_sdwa v[110:111], v12 src0_sel:WORD_1
	v_pk_fma_f32 v[64:65], v[104:105], v[144:145], v[64:65] op_sel_hi:[1,0,1]
	v_pk_fma_f32 v[66:67], v[106:107], v[144:145], v[66:67] op_sel_hi:[1,0,1]
	v_pk_fma_f32 v[64:65], v[108:109], v[146:147], v[64:65] op_sel_hi:[1,0,1]
	v_pk_fma_f32 v[66:67], v[110:111], v[146:147], v[66:67] op_sel_hi:[1,0,1]
	v_cvt_pk_f32_fp8_e32 v[104:105], v9
	v_cvt_pk_f32_fp8_e32 v[108:109], v13
	v_cvt_pk_f32_fp8_sdwa v[106:107], v9 src0_sel:WORD_1
	v_cvt_pk_f32_fp8_sdwa v[110:111], v13 src0_sel:WORD_1
	v_pk_fma_f32 v[68:69], v[104:105], v[144:145], v[68:69] op_sel_hi:[1,0,1]
	v_pk_fma_f32 v[70:71], v[106:107], v[144:145], v[70:71] op_sel_hi:[1,0,1]
	v_pk_fma_f32 v[68:69], v[108:109], v[146:147], v[68:69] op_sel_hi:[1,0,1]
	v_pk_fma_f32 v[70:71], v[110:111], v[146:147], v[70:71] op_sel_hi:[1,0,1]
	v_cvt_pk_f32_fp8_e32 v[104:105], v10
	v_cvt_pk_f32_fp8_e32 v[108:109], v14
	v_cvt_pk_f32_fp8_sdwa v[106:107], v10 src0_sel:WORD_1
	v_cvt_pk_f32_fp8_sdwa v[110:111], v14 src0_sel:WORD_1
	v_pk_fma_f32 v[72:73], v[104:105], v[144:145], v[72:73] op_sel_hi:[1,0,1]
	v_pk_fma_f32 v[74:75], v[106:107], v[144:145], v[74:75] op_sel_hi:[1,0,1]
	v_pk_fma_f32 v[72:73], v[108:109], v[146:147], v[72:73] op_sel_hi:[1,0,1]
	v_pk_fma_f32 v[74:75], v[110:111], v[146:147], v[74:75] op_sel_hi:[1,0,1]
	v_cvt_pk_f32_fp8_e32 v[104:105], v11
	v_cvt_pk_f32_fp8_e32 v[108:109], v15
	v_cvt_pk_f32_fp8_sdwa v[106:107], v11 src0_sel:WORD_1
	v_cvt_pk_f32_fp8_sdwa v[110:111], v15 src0_sel:WORD_1
	v_pk_fma_f32 v[76:77], v[104:105], v[144:145], v[76:77] op_sel_hi:[1,0,1]
	v_pk_fma_f32 v[78:79], v[106:107], v[144:145], v[78:79] op_sel_hi:[1,0,1]
	v_and_or_b32 v244, v244, s2, v240
	v_and_or_b32 v245, v245, s2, v240
	global_load_dwordx4 v[8:11], v244, s[80:81]
	global_load_dwordx4 v[12:15], v245, s[80:81]
	v_pk_fma_f32 v[76:77], v[108:109], v[146:147], v[76:77] op_sel_hi:[1,0,1]
	v_pk_fma_f32 v[78:79], v[110:111], v[146:147], v[78:79] op_sel_hi:[1,0,1]
	ds_bpermute_b32 v244, v255, v134
	ds_bpermute_b32 v245, v153, v134
	ds_bpermute_b32 v144, v255, v136
	ds_bpermute_b32 v146, v153, v136
	s_waitcnt vmcnt(18) lgkmcnt(4)
	v_cvt_pk_f32_fp8_e32 v[104:105], v16
	v_cvt_pk_f32_fp8_e32 v[108:109], v20
	v_cvt_pk_f32_fp8_sdwa v[106:107], v16 src0_sel:WORD_1
	v_cvt_pk_f32_fp8_sdwa v[110:111], v20 src0_sel:WORD_1
	v_pk_fma_f32 v[64:65], v[104:105], v[138:139], v[64:65] op_sel_hi:[1,0,1]
	v_pk_fma_f32 v[66:67], v[106:107], v[138:139], v[66:67] op_sel_hi:[1,0,1]
	v_pk_fma_f32 v[64:65], v[108:109], v[140:141], v[64:65] op_sel_hi:[1,0,1]
	v_pk_fma_f32 v[66:67], v[110:111], v[140:141], v[66:67] op_sel_hi:[1,0,1]
	v_cvt_pk_f32_fp8_e32 v[104:105], v17
	v_cvt_pk_f32_fp8_e32 v[108:109], v21
	v_cvt_pk_f32_fp8_sdwa v[106:107], v17 src0_sel:WORD_1
	v_cvt_pk_f32_fp8_sdwa v[110:111], v21 src0_sel:WORD_1
	v_pk_fma_f32 v[68:69], v[104:105], v[138:139], v[68:69] op_sel_hi:[1,0,1]
	v_pk_fma_f32 v[70:71], v[106:107], v[138:139], v[70:71] op_sel_hi:[1,0,1]
	v_pk_fma_f32 v[68:69], v[108:109], v[140:141], v[68:69] op_sel_hi:[1,0,1]
	v_pk_fma_f32 v[70:71], v[110:111], v[140:141], v[70:71] op_sel_hi:[1,0,1]
	v_cvt_pk_f32_fp8_e32 v[104:105], v18
	v_cvt_pk_f32_fp8_e32 v[108:109], v22
	v_cvt_pk_f32_fp8_sdwa v[106:107], v18 src0_sel:WORD_1
	v_cvt_pk_f32_fp8_sdwa v[110:111], v22 src0_sel:WORD_1
	v_pk_fma_f32 v[72:73], v[104:105], v[138:139], v[72:73] op_sel_hi:[1,0,1]
	v_pk_fma_f32 v[74:75], v[106:107], v[138:139], v[74:75] op_sel_hi:[1,0,1]
	v_pk_fma_f32 v[72:73], v[108:109], v[140:141], v[72:73] op_sel_hi:[1,0,1]
	v_pk_fma_f32 v[74:75], v[110:111], v[140:141], v[74:75] op_sel_hi:[1,0,1]
	v_cvt_pk_f32_fp8_e32 v[104:105], v19
	v_cvt_pk_f32_fp8_e32 v[108:109], v23
	v_cvt_pk_f32_fp8_sdwa v[106:107], v19 src0_sel:WORD_1
	v_cvt_pk_f32_fp8_sdwa v[110:111], v23 src0_sel:WORD_1
	v_pk_fma_f32 v[76:77], v[104:105], v[138:139], v[76:77] op_sel_hi:[1,0,1]
	v_pk_fma_f32 v[78:79], v[106:107], v[138:139], v[78:79] op_sel_hi:[1,0,1]
	v_and_or_b32 v142, v142, s2, v240
	v_and_or_b32 v143, v143, s2, v240
	global_load_dwordx4 v[16:19], v142, s[80:81]
	global_load_dwordx4 v[20:23], v143, s[80:81]
	v_pk_fma_f32 v[76:77], v[108:109], v[140:141], v[76:77] op_sel_hi:[1,0,1]
	v_pk_fma_f32 v[78:79], v[110:111], v[140:141], v[78:79] op_sel_hi:[1,0,1]
	ds_bpermute_b32 v142, v249, v135
	ds_bpermute_b32 v143, v250, v135
	ds_bpermute_b32 v138, v249, v137
	ds_bpermute_b32 v140, v250, v137
	s_waitcnt vmcnt(18) lgkmcnt(4)
; #define PG_ISSUE(BUF, TAB, e0_) do { const int isrc_ = ((e0_) < 64) ? myi0 : myi1; \
;       _Pragma("unroll") for (int e = 0; e < 8; ++e) { const int idx_ = __builtin_amdgcn_readlane(isrc_, ((e0_) + e) & 63); \
;         BUF[e] = *(const u32x4*)((TAB) + (size_t)idx_ * 1024 + lane * 16); } } while (0)
; DEV void peer_gather(const Params& P, int l, int m0, const int* idxs, const float* gs) {
;     ...
;     for (int e0 = 0; e0 < 128; e0 += 16) {
;       PG_ISSUE(b1, V, e0 + 8);
;       if (e0 == 64 && i + 1 < 16) sort_lists(lane, ni0, ni1, ng0, ng1);
;       PG_V16(b0, e0);
;       if (e0 + 16 < 128) PG_ISSUE(b0, V, e0 + 16);
;       PG_V16(b1, e0 + 8);
;     }
	v_cvt_pk_f32_fp8_e32 v[104:105], v24
	v_cvt_pk_f32_fp8_e32 v[108:109], v28
	v_cvt_pk_f32_fp8_sdwa v[106:107], v24 src0_sel:WORD_1
	v_cvt_pk_f32_fp8_sdwa v[110:111], v28 src0_sel:WORD_1
	v_pk_fma_f32 v[64:65], v[104:105], v[144:145], v[64:65] op_sel_hi:[1,0,1]
	v_pk_fma_f32 v[66:67], v[106:107], v[144:145], v[66:67] op_sel_hi:[1,0,1]
	v_pk_fma_f32 v[64:65], v[108:109], v[146:147], v[64:65] op_sel_hi:[1,0,1]
	v_pk_fma_f32 v[66:67], v[110:111], v[146:147], v[66:67] op_sel_hi:[1,0,1]
	v_cvt_pk_f32_fp8_e32 v[104:105], v25
	v_cvt_pk_f32_fp8_e32 v[108:109], v29
	v_cvt_pk_f32_fp8_sdwa v[106:107], v25 src0_sel:WORD_1
	v_cvt_pk_f32_fp8_sdwa v[110:111], v29 src0_sel:WORD_1
	v_pk_fma_f32 v[68:69], v[104:105], v[144:145], v[68:69] op_sel_hi:[1,0,1]
	v_pk_fma_f32 v[70:71], v[106:107], v[144:145], v[70:71] op_sel_hi:[1,0,1]
	v_pk_fma_f32 v[68:69], v[108:109], v[146:147], v[68:69] op_sel_hi:[1,0,1]
	v_pk_fma_f32 v[70:71], v[110:111], v[146:147], v[70:71] op_sel_hi:[1,0,1]
	v_cvt_pk_f32_fp8_e32 v[104:105], v26
	v_cvt_pk_f32_fp8_e32 v[108:109], v30
	v_cvt_pk_f32_fp8_sdwa v[106:107], v26 src0_sel:WORD_1
	v_cvt_pk_f32_fp8_sdwa v[110:111], v30 src0_sel:WORD_1
	v_pk_fma_f32 v[72:73], v[104:105], v[144:145], v[72:73] op_sel_hi:[1,0,1]
	v_pk_fma_f32 v[74:75], v[106:107], v[144:145], v[74:75] op_sel_hi:[1,0,1]
	v_pk_fma_f32 v[72:73], v[108:109], v[146:147], v[72:73] op_sel_hi:[1,0,1]
	v_pk_fma_f32 v[74:75], v[110:111], v[146:147], v[74:75] op_sel_hi:[1,0,1]
	v_cvt_pk_f32_fp8_e32 v[104:105], v27
	v_cvt_pk_f32_fp8_e32 v[108:109], v31
	v_cvt_pk_f32_fp8_sdwa v[106:107], v27 src0_sel:WORD_1
	v_cvt_pk_f32_fp8_sdwa v[110:111], v31 src0_sel:WORD_1
	v_pk_fma_f32 v[76:77], v[104:105], v[144:145], v[76:77] op_sel_hi:[1,0,1]
	v_pk_fma_f32 v[78:79], v[106:107], v[144:145], v[78:79] op_sel_hi:[1,0,1]
	v_and_or_b32 v244, v244, s2, v240
	v_and_or_b32 v245, v245, s2, v240
	global_load_dwordx4 v[24:27], v244, s[80:81]
	global_load_dwordx4 v[28:31], v245, s[80:81]
	v_pk_fma_f32 v[76:77], v[108:109], v[146:147], v[76:77] op_sel_hi:[1,0,1]
	v_pk_fma_f32 v[78:79], v[110:111], v[146:147], v[78:79] op_sel_hi:[1,0,1]
	ds_bpermute_b32 v244, v251, v135
	ds_bpermute_b32 v245, v252, v135
	ds_bpermute_b32 v144, v251, v137
	ds_bpermute_b32 v146, v252, v137
	s_waitcnt vmcnt(18) lgkmcnt(4)
	v_cvt_pk_f32_fp8_e32 v[104:105], v32
	v_cvt_pk_f32_fp8_e32 v[108:109], v36
	v_cvt_pk_f32_fp8_sdwa v[106:107], v32 src0_sel:WORD_1
	v_cvt_pk_f32_fp8_sdwa v[110:111], v36 src0_sel:WORD_1
	v_pk_fma_f32 v[64:65], v[104:105], v[138:139], v[64:65] op_sel_hi:[1,0,1]
	v_pk_fma_f32 v[66:67], v[106:107], v[138:139], v[66:67] op_sel_hi:[1,0,1]
	v_pk_fma_f32 v[64:65], v[108:109], v[140:141], v[64:65] op_sel_hi:[1,0,1]
	v_pk_fma_f32 v[66:67], v[110:111], v[140:141], v[66:67] op_sel_hi:[1,0,1]
	v_cvt_pk_f32_fp8_e32 v[104:105], v33
	v_cvt_pk_f32_fp8_e32 v[108:109], v37
	v_cvt_pk_f32_fp8_sdwa v[106:107], v33 src0_sel:WORD_1
	v_cvt_pk_f32_fp8_sdwa v[110:111], v37 src0_sel:WORD_1
	v_pk_fma_f32 v[68:69], v[104:105], v[138:139], v[68:69] op_sel_hi:[1,0,1]
	v_pk_fma_f32 v[70:71], v[106:107], v[138:139], v[70:71] op_sel_hi:[1,0,1]
	v_pk_fma_f32 v[68:69], v[108:109], v[140:141], v[68:69] op_sel_hi:[1,0,1]
	v_pk_fma_f32 v[70:71], v[110:111], v[140:141], v[70:71] op_sel_hi:[1,0,1]
	v_cvt_pk_f32_fp8_e32 v[104:105], v34
	v_cvt_pk_f32_fp8_e32 v[108:109], v38
	v_cvt_pk_f32_fp8_sdwa v[106:107], v34 src0_sel:WORD_1
	v_cvt_pk_f32_fp8_sdwa v[110:111], v38 src0_sel:WORD_1
	v_pk_fma_f32 v[72:73], v[104:105], v[138:139], v[72:73] op_sel_hi:[1,0,1]
	v_pk_fma_f32 v[74:75], v[106:107], v[138:139], v[74:75] op_sel_hi:[1,0,1]
	v_pk_fma_f32 v[72:73], v[108:109], v[140:141], v[72:73] op_sel_hi:[1,0,1]
	v_pk_fma_f32 v[74:75], v[110:111], v[140:141], v[74:75] op_sel_hi:[1,0,1]
	v_cvt_pk_f32_fp8_e32 v[104:105], v35
	v_cvt_pk_f32_fp8_e32 v[108:109], v39
	v_cvt_pk_f32_fp8_sdwa v[106:107], v35 src0_sel:WORD_1
	v_cvt_pk_f32_fp8_sdwa v[110:111], v39 src0_sel:WORD_1
	v_pk_fma_f32 v[76:77], v[104:105], v[138:139], v[76:77] op_sel_hi:[1,0,1]
	v_pk_fma_f32 v[78:79], v[106:107], v[138:139], v[78:79] op_sel_hi:[1,0,1]
	v_and_or_b32 v142, v142, s2, v240
	v_and_or_b32 v143, v143, s2, v240
	global_load_dwordx4 v[32:35], v142, s[80:81]
	global_load_dwordx4 v[36:39], v143, s[80:81]
	v_pk_fma_f32 v[76:77], v[108:109], v[140:141], v[76:77] op_sel_hi:[1,0,1]
	v_pk_fma_f32 v[78:79], v[110:111], v[140:141], v[78:79] op_sel_hi:[1,0,1]
	ds_bpermute_b32 v142, v253, v135
	ds_bpermute_b32 v143, v254, v135
	ds_bpermute_b32 v138, v253, v137
	ds_bpermute_b32 v140, v254, v137
	s_waitcnt vmcnt(18) lgkmcnt(4)
; #define PG_ISSUE(BUF, TAB, e0_) do { const int isrc_ = ((e0_) < 64) ? myi0 : myi1; \
;       _Pragma("unroll") for (int e = 0; e < 8; ++e) { const int idx_ = __builtin_amdgcn_readlane(isrc_, ((e0_) + e) & 63); \
;         BUF[e] = *(const u32x4*)((TAB) + (size_t)idx_ * 1024 + lane * 16); } } while (0)
; DEV void peer_gather(const Params& P, int l, int m0, const int* idxs, const float* gs) {
;     ...
;     for (int e0 = 0; e0 < 128; e0 += 16) {
;       PG_ISSUE(b1, V, e0 + 8);
;       if (e0 == 64 && i + 1 < 16) sort_lists(lane, ni0, ni1, ng0, ng1);
;       PG_V16(b0, e0);
;       if (e0 + 16 < 128) PG_ISSUE(b0, V, e0 + 16);
;       PG_V16(b1, e0 + 8);
;     }
	v_cvt_pk_f32_fp8_e32 v[104:105], v40
	v_cvt_pk_f32_fp8_e32 v[108:109], v44
	v_cvt_pk_f32_fp8_sdwa v[106:107], v40 src0_sel:WORD_1
	v_cvt_pk_f32_fp8_sdwa v[110:111], v44 src0_sel:WORD_1
	v_pk_fma_f32 v[64:65], v[104:105], v[144:145], v[64:65] op_sel_hi:[1,0,1]
	v_pk_fma_f32 v[66:67], v[106:107], v[144:145], v[66:67] op_sel_hi:[1,0,1]
	v_pk_fma_f32 v[64:65], v[108:109], v[146:147], v[64:65] op_sel_hi:[1,0,1]
	v_pk_fma_f32 v[66:67], v[110:111], v[146:147], v[66:67] op_sel_hi:[1,0,1]
	v_cvt_pk_f32_fp8_e32 v[104:105], v41
	v_cvt_pk_f32_fp8_e32 v[108:109], v45
	v_cvt_pk_f32_fp8_sdwa v[106:107], v41 src0_sel:WORD_1
	v_cvt_pk_f32_fp8_sdwa v[110:111], v45 src0_sel:WORD_1
	v_pk_fma_f32 v[68:69], v[104:105], v[144:145], v[68:69] op_sel_hi:[1,0,1]
	v_pk_fma_f32 v[70:71], v[106:107], v[144:145], v[70:71] op_sel_hi:[1,0,1]
	v_pk_fma_f32 v[68:69], v[108:109], v[146:147], v[68:69] op_sel_hi:[1,0,1]
	v_pk_fma_f32 v[70:71], v[110:111], v[146:147], v[70:71] op_sel_hi:[1,0,1]
	v_cvt_pk_f32_fp8_e32 v[104:105], v42
	v_cvt_pk_f32_fp8_e32 v[108:109], v46
	v_cvt_pk_f32_fp8_sdwa v[106:107], v42 src0_sel:WORD_1
	v_cvt_pk_f32_fp8_sdwa v[110:111], v46 src0_sel:WORD_1
	v_pk_fma_f32 v[72:73], v[104:105], v[144:145], v[72:73] op_sel_hi:[1,0,1]
	v_pk_fma_f32 v[74:75], v[106:107], v[144:145], v[74:75] op_sel_hi:[1,0,1]
	v_pk_fma_f32 v[72:73], v[108:109], v[146:147], v[72:73] op_sel_hi:[1,0,1]
	v_pk_fma_f32 v[74:75], v[110:111], v[146:147], v[74:75] op_sel_hi:[1,0,1]
	v_cvt_pk_f32_fp8_e32 v[104:105], v43
	v_cvt_pk_f32_fp8_e32 v[108:109], v47
	v_cvt_pk_f32_fp8_sdwa v[106:107], v43 src0_sel:WORD_1
	v_cvt_pk_f32_fp8_sdwa v[110:111], v47 src0_sel:WORD_1
	v_pk_fma_f32 v[76:77], v[104:105], v[144:145], v[76:77] op_sel_hi:[1,0,1]
	v_pk_fma_f32 v[78:79], v[106:107], v[144:145], v[78:79] op_sel_hi:[1,0,1]
	v_and_or_b32 v244, v244, s2, v240
	v_and_or_b32 v245, v245, s2, v240
	global_load_dwordx4 v[40:43], v244, s[80:81]
	global_load_dwordx4 v[44:47], v245, s[80:81]
	v_pk_fma_f32 v[76:77], v[108:109], v[146:147], v[76:77] op_sel_hi:[1,0,1]
	v_pk_fma_f32 v[78:79], v[110:111], v[146:147], v[78:79] op_sel_hi:[1,0,1]
	ds_bpermute_b32 v244, v255, v135
	ds_bpermute_b32 v245, v153, v135
	ds_bpermute_b32 v144, v255, v137
	ds_bpermute_b32 v146, v153, v137
	s_waitcnt vmcnt(18) lgkmcnt(4)
	v_cvt_pk_f32_fp8_e32 v[104:105], v48
	v_cvt_pk_f32_fp8_e32 v[108:109], v52
	v_cvt_pk_f32_fp8_sdwa v[106:107], v48 src0_sel:WORD_1
	v_cvt_pk_f32_fp8_sdwa v[110:111], v52 src0_sel:WORD_1
	v_pk_fma_f32 v[64:65], v[104:105], v[138:139], v[64:65] op_sel_hi:[1,0,1]
	v_pk_fma_f32 v[66:67], v[106:107], v[138:139], v[66:67] op_sel_hi:[1,0,1]
	v_pk_fma_f32 v[64:65], v[108:109], v[140:141], v[64:65] op_sel_hi:[1,0,1]
	v_pk_fma_f32 v[66:67], v[110:111], v[140:141], v[66:67] op_sel_hi:[1,0,1]
	v_cvt_pk_f32_fp8_e32 v[104:105], v49
	v_cvt_pk_f32_fp8_e32 v[108:109], v53
	v_cvt_pk_f32_fp8_sdwa v[106:107], v49 src0_sel:WORD_1
	v_cvt_pk_f32_fp8_sdwa v[110:111], v53 src0_sel:WORD_1
	v_pk_fma_f32 v[68:69], v[104:105], v[138:139], v[68:69] op_sel_hi:[1,0,1]
	v_pk_fma_f32 v[70:71], v[106:107], v[138:139], v[70:71] op_sel_hi:[1,0,1]
	v_pk_fma_f32 v[68:69], v[108:109], v[140:141], v[68:69] op_sel_hi:[1,0,1]
	v_pk_fma_f32 v[70:71], v[110:111], v[140:141], v[70:71] op_sel_hi:[1,0,1]
	v_cvt_pk_f32_fp8_e32 v[104:105], v50
	v_cvt_pk_f32_fp8_e32 v[108:109], v54
	v_cvt_pk_f32_fp8_sdwa v[106:107], v50 src0_sel:WORD_1
	v_cvt_pk_f32_fp8_sdwa v[110:111], v54 src0_sel:WORD_1
	v_pk_fma_f32 v[72:73], v[104:105], v[138:139], v[72:73] op_sel_hi:[1,0,1]
	v_pk_fma_f32 v[74:75], v[106:107], v[138:139], v[74:75] op_sel_hi:[1,0,1]
	v_pk_fma_f32 v[72:73], v[108:109], v[140:141], v[72:73] op_sel_hi:[1,0,1]
	v_pk_fma_f32 v[74:75], v[110:111], v[140:141], v[74:75] op_sel_hi:[1,0,1]
	v_cvt_pk_f32_fp8_e32 v[104:105], v51
	v_cvt_pk_f32_fp8_e32 v[108:109], v55
	v_cvt_pk_f32_fp8_sdwa v[106:107], v51 src0_sel:WORD_1
	v_cvt_pk_f32_fp8_sdwa v[110:111], v55 src0_sel:WORD_1
	v_pk_fma_f32 v[76:77], v[104:105], v[138:139], v[76:77] op_sel_hi:[1,0,1]
	v_pk_fma_f32 v[78:79], v[106:107], v[138:139], v[78:79] op_sel_hi:[1,0,1]
	v_and_or_b32 v142, v142, s2, v240
	v_and_or_b32 v143, v143, s2, v240
	global_load_dwordx4 v[48:51], v142, s[80:81]
	global_load_dwordx4 v[52:55], v143, s[80:81]
	v_pk_fma_f32 v[76:77], v[108:109], v[140:141], v[76:77] op_sel_hi:[1,0,1]
	v_pk_fma_f32 v[78:79], v[110:111], v[140:141], v[78:79] op_sel_hi:[1,0,1]
	s_waitcnt vmcnt(18) lgkmcnt(0)
; #define PG_ISSUE(BUF, TAB, e0_) do { const int isrc_ = ((e0_) < 64) ? myi0 : myi1; \
;       _Pragma("unroll") for (int e = 0; e < 8; ++e) { const int idx_ = __builtin_amdgcn_readlane(isrc_, ((e0_) + e) & 63); \
;         BUF[e] = *(const u32x4*)((TAB) + (size_t)idx_ * 1024 + lane * 16); } } while (0)
; DEV void peer_gather(const Params& P, int l, int m0, const int* idxs, const float* gs) {
;     ...
;     PG_ISSUE(b0, U, 0);
; #pragma nounroll
;     for (int e0 = 0; e0 < 128; e0 += 16) {
;       PG_ISSUE(b1, U, e0 + 8);
;       PG_U8(b0, 0, e0);
;       if (e0 + 16 < 128) PG_ISSUE(b0, U, e0 + 16); else PG_ISSUE(b0, V, 0);
;       PG_U8(b1, 0, e0 + 8);
;     }
;     float* hrow = P.out + tok * DM + lane * 16;
;     f32x4 hv[4];
; #pragma unroll
;     for (int q = 0; q < 4; ++q) hv[q] = *(const f32x4*)(hrow + 4 * q);
;     if (i + 1 < 16) {
;       const int tn = tt + 1;
;       nxa = *(const u32x4*)(hn + (size_t)(m0 + tn) * DM + lane * 16); nxb = *(const u32x4*)(hn + (size_t)(m0 + tn) * DM + lane * 16 + 8);
;       ni0 = idxs[tn * 128 + lane]; ni1 = idxs[tn * 128 + 64 + lane]; ng0 = gs[tn * 128 + lane]; ng1 = gs[tn * 128 + 64 + lane];
;     }
; #pragma nounroll
;     for (int e0 = 0; e0 < 128; e0 += 16) {
;       PG_ISSUE(b1, V, e0 + 8);
;       if (e0 == 64 && i + 1 < 16) sort_lists(lane, ni0, ni1, ng0, ng1);
;       PG_V16(b0, e0);
;       if (e0 + 16 < 128) PG_ISSUE(b0, V, e0 + 16);
;       PG_V16(b1, e0 + 8);
;     }
;     ...
;     float ss = 0.f;
; #pragma unroll
;     for (int q = 0; q < 4; ++q) {
;       hv[q][0] += acc[2 * q][0] * TAB_INV; hv[q][1] += acc[2 * q][1] * TAB_INV; hv[q][2] += acc[2 * q + 1][0] * TAB_INV; hv[q][3] += acc[2 * q + 1][1] * TAB_INV;
;       ss += hv[q][0] * hv[q][0] + hv[q][1] * hv[q][1] + hv[q][2] * hv[q][2] + hv[q][3] * hv[q][3];
;       *(f32x4*)(hrow + 4 * q) = hv[q];
	v_cvt_pk_f32_fp8_e32 v[104:105], v56
	v_cvt_pk_f32_fp8_e32 v[108:109], v60
	v_cvt_pk_f32_fp8_sdwa v[106:107], v56 src0_sel:WORD_1
	v_cvt_pk_f32_fp8_sdwa v[110:111], v60 src0_sel:WORD_1
	v_pk_fma_f32 v[64:65], v[104:105], v[144:145], v[64:65] op_sel_hi:[1,0,1]
	v_pk_fma_f32 v[66:67], v[106:107], v[144:145], v[66:67] op_sel_hi:[1,0,1]
	v_pk_fma_f32 v[64:65], v[108:109], v[146:147], v[64:65] op_sel_hi:[1,0,1]
	v_pk_fma_f32 v[66:67], v[110:111], v[146:147], v[66:67] op_sel_hi:[1,0,1]
	v_cvt_pk_f32_fp8_e32 v[104:105], v57
	v_cvt_pk_f32_fp8_e32 v[108:109], v61
	v_cvt_pk_f32_fp8_sdwa v[106:107], v57 src0_sel:WORD_1
	v_cvt_pk_f32_fp8_sdwa v[110:111], v61 src0_sel:WORD_1
	v_pk_fma_f32 v[68:69], v[104:105], v[144:145], v[68:69] op_sel_hi:[1,0,1]
	v_pk_fma_f32 v[70:71], v[106:107], v[144:145], v[70:71] op_sel_hi:[1,0,1]
	v_pk_fma_f32 v[68:69], v[108:109], v[146:147], v[68:69] op_sel_hi:[1,0,1]
	v_pk_fma_f32 v[70:71], v[110:111], v[146:147], v[70:71] op_sel_hi:[1,0,1]
	v_cvt_pk_f32_fp8_e32 v[104:105], v58
	v_cvt_pk_f32_fp8_e32 v[108:109], v62
	v_cvt_pk_f32_fp8_sdwa v[106:107], v58 src0_sel:WORD_1
	v_cvt_pk_f32_fp8_sdwa v[110:111], v62 src0_sel:WORD_1
	v_pk_fma_f32 v[72:73], v[104:105], v[144:145], v[72:73] op_sel_hi:[1,0,1]
	v_pk_fma_f32 v[74:75], v[106:107], v[144:145], v[74:75] op_sel_hi:[1,0,1]
	v_pk_fma_f32 v[72:73], v[108:109], v[146:147], v[72:73] op_sel_hi:[1,0,1]
	v_pk_fma_f32 v[74:75], v[110:111], v[146:147], v[74:75] op_sel_hi:[1,0,1]
	v_cvt_pk_f32_fp8_e32 v[104:105], v59
	v_cvt_pk_f32_fp8_e32 v[108:109], v63
	v_cvt_pk_f32_fp8_sdwa v[106:107], v59 src0_sel:WORD_1
	v_cvt_pk_f32_fp8_sdwa v[110:111], v63 src0_sel:WORD_1
	v_pk_fma_f32 v[76:77], v[104:105], v[144:145], v[76:77] op_sel_hi:[1,0,1]
	v_pk_fma_f32 v[78:79], v[106:107], v[144:145], v[78:79] op_sel_hi:[1,0,1]
	v_and_or_b32 v244, v244, s2, v240
	v_and_or_b32 v245, v245, s2, v240
	global_load_dwordx4 v[56:59], v244, s[80:81]
	global_load_dwordx4 v[60:63], v245, s[80:81]
	v_pk_fma_f32 v[76:77], v[108:109], v[146:147], v[76:77] op_sel_hi:[1,0,1]
	v_pk_fma_f32 v[78:79], v[110:111], v[146:147], v[78:79] op_sel_hi:[1,0,1]
	s_add_u32 s92, s100, 2
	s_and_b32 s92, s92, 15
	v_lshl_add_u32 v116, s92, 9, v246
	ds_read_b32 v134, v116
	ds_read_b32 v135, v116 offset:256
	s_add_u32 s92, s100, 1
	s_and_b32 s92, s92, 15
	v_lshl_add_u32 v117, s92, 9, v247
	ds_read_b32 v136, v117
	ds_read_b32 v137, v117 offset:256
	s_nop 1
	v_permlane32_swap_b32_e32 v64, v65
	v_permlane32_swap_b32_e32 v66, v67
	v_permlane32_swap_b32_e32 v68, v69
	v_permlane32_swap_b32_e32 v70, v71
	v_permlane32_swap_b32_e32 v72, v73
	v_permlane32_swap_b32_e32 v74, v75
	v_permlane32_swap_b32_e32 v76, v77
	v_permlane32_swap_b32_e32 v78, v79
	v_add_f32_e32 v64, v64, v65
	v_add_f32_e32 v66, v66, v67
	v_add_f32_e32 v68, v68, v69
	v_add_f32_e32 v70, v70, v71
	v_add_f32_e32 v72, v72, v73
	v_add_f32_e32 v74, v74, v75
	v_add_f32_e32 v76, v76, v77
	v_add_f32_e32 v78, v78, v79
	s_nop 1
	v_permlane16_swap_b32_e32 v64, v66
	v_permlane16_swap_b32_e32 v68, v70
	v_permlane16_swap_b32_e32 v72, v74
	v_permlane16_swap_b32_e32 v76, v78
	v_add_f32_e32 v64, v64, v66
	v_add_f32_e32 v68, v68, v70
	v_add_f32_e32 v72, v72, v74
	v_add_f32_e32 v76, v76, v78
	s_nop 0
	v_cndmask_b32_e64 v65, v64, v68, s[88:89]
	v_cndmask_b32_e64 v66, v68, v64, s[88:89]
	v_cndmask_b32_e64 v73, v72, v76, s[88:89]
	v_cndmask_b32_e64 v74, v76, v72, s[88:89]
	s_nop 1
	v_add_f32_dpp v64, v66, v65 row_ror:8 row_mask:0xf bank_mask:0xf
	v_add_f32_dpp v72, v74, v73 row_ror:8 row_mask:0xf bank_mask:0xf
	s_waitcnt vmcnt(16)
	v_fmac_f32_e32 v80, 0x3c800000, v64
	v_fmac_f32_e32 v81, 0x3c800000, v72
	global_store_dword v119, v80, s[82:83]
	global_store_dword v119, v81, s[82:83] offset:32
	s_add_u32 s100, s100, 1
	s_cmp_lt_u32 s100, 128
	s_cbranch_scc1 .Lpg0_vloop
	s_waitcnt vmcnt(0) lgkmcnt(0)
	v_readfirstlane_b32 s88, v130
	v_readfirstlane_b32 s89, v131
	s_nop 4
	v_lshlrev_b32_e32 v117, 6, v233
	global_load_dwordx4 v[16:19], v117, s[88:89] offset:0
	global_load_dwordx4 v[20:23], v117, s[88:89] offset:16
	global_load_dwordx4 v[24:27], v117, s[88:89] offset:32
	global_load_dwordx4 v[28:31], v117, s[88:89] offset:48
	s_mov_b32 s2, 0

; DEV void sort_lists(int lane, int& myi0, int& myi1, float& myg0, float& myg1) {
; #pragma unroll
;     for (int k = 2; k <= 128; k <<= 1) {
; #pragma unroll
;       for (int j = k >> 1; j >= 1; j >>= 1) {
;         if (j == 64) {
;           const bool sw_ = myi1 < myi0;
;           const int ti = sw_ ? myi1 : myi0, tj = sw_ ? myi0 : myi1; const float tg = sw_ ? myg1 : myg0, th = sw_ ? myg0 : myg1;
;           myi0 = ti; myi1 = tj; myg0 = tg; myg1 = th;
;         } else {
;           const bool lower = (lane & j) == 0;
;           {
;             const bool up = (k == 128) ? true : ((k == 64) ? true : ((lane & k) == 0));
;             const int oi = __shfl_xor(myi0, j); const float og = __shfl_xor(myg0, j);
;             const bool take = (lower == up) ? (oi < myi0) : (oi > myi0);
;             myi0 = take ? oi : myi0; myg0 = take ? og : myg0;
;           }
;           {
;             const bool up = (k == 128) ? true : ((k == 64) ? false : ((lane & k) == 0));
;             const int oi = __shfl_xor(myi1, j); const float og = __shfl_xor(myg1, j);
;             const bool take = (lower == up) ? (oi < myi1) : (oi > myi1);
;             myi1 = take ? oi : myi1; myg1 = take ? og : myg1;
;           }
;         }
;       }
;     }
; }
.Lpg1_p0:
	v_readlane_b32 s82, v231, 13
	v_readlane_b32 s83, v231, 14
	s_nop 4
	s_lshl_b32 s98, s2, 2
	s_add_u32 s98, s98, s33
	s_add_u32 s98, s98, 0
	s_lshl_b32 s98, s98, 9
	v_add_u32_e32 v116, s98, v234
	global_load_dword v241, v116, s[82:83]
	global_load_dword v242, v116, s[82:83] offset:256
	s_lshl_b32 s98, s2, 2
	s_add_u32 s98, s98, s33
	s_add_u32 s98, s98, 1
	s_lshl_b32 s98, s98, 9
	v_add_u32_e32 v117, s98, v234
	global_load_dword v243, v117, s[82:83]
	global_load_dword v244, v117, s[82:83] offset:256
	s_lshl_b32 s98, s2, 2
	s_add_u32 s98, s98, s33
	s_add_u32 s98, s98, 2
	s_lshl_b32 s98, s98, 9
	v_add_u32_e32 v118, s98, v234
	global_load_dword v245, v118, s[82:83]
	global_load_dword v246, v118, s[82:83] offset:256
	s_lshl_b32 s98, s2, 2
	s_add_u32 s98, s98, s33
	s_add_u32 s98, s98, 3
	s_lshl_b32 s98, s98, 9
	v_add_u32_e32 v119, s98, v234
	global_load_dword v247, v119, s[82:83]
	global_load_dword v248, v119, s[82:83] offset:256
	s_waitcnt vmcnt(0)
	v_or_b32_e32 v116, 64, v233
	v_lshl_or_b32 v241, v241, 7, v233
	v_lshl_or_b32 v242, v242, 7, v116
	v_lshl_or_b32 v243, v243, 7, v233
	v_lshl_or_b32 v244, v244, 7, v116
	v_lshl_or_b32 v245, v245, 7, v233
	v_lshl_or_b32 v246, v246, 7, v116
	v_lshl_or_b32 v247, v247, 7, v233
	v_lshl_or_b32 v248, v248, 7, v116
	v_xor_b32_e32 v116, 4, v234
	ds_bpermute_b32 v0, v116, v241
	ds_bpermute_b32 v1, v116, v243
	ds_bpermute_b32 v2, v116, v245
	ds_bpermute_b32 v3, v116, v247
	ds_bpermute_b32 v4, v116, v242
	ds_bpermute_b32 v5, v116, v244
	ds_bpermute_b32 v6, v116, v246
	ds_bpermute_b32 v7, v116, v248
	s_waitcnt lgkmcnt(0)
	s_mov_b32 s88, 0x99999999
	s_mov_b32 s89, 0x99999999
	v_min_u32_e32 v104, v241, v0
	v_max_u32_e32 v105, v241, v0
	v_cndmask_b32_e64 v241, v105, v104, s[88:89]
	v_min_u32_e32 v106, v243, v1
	v_max_u32_e32 v107, v243, v1
	v_cndmask_b32_e64 v243, v107, v106, s[88:89]
	v_min_u32_e32 v104, v245, v2
	v_max_u32_e32 v105, v245, v2
	v_cndmask_b32_e64 v245, v105, v104, s[88:89]
	v_min_u32_e32 v106, v247, v3
	v_max_u32_e32 v107, v247, v3
	v_cndmask_b32_e64 v247, v107, v106, s[88:89]
	v_min_u32_e32 v104, v242, v4
	v_max_u32_e32 v105, v242, v4
	v_cndmask_b32_e64 v242, v105, v104, s[88:89]
	v_min_u32_e32 v106, v244, v5
	v_max_u32_e32 v107, v244, v5
	v_cndmask_b32_e64 v244, v107, v106, s[88:89]
	v_min_u32_e32 v104, v246, v6
	v_max_u32_e32 v105, v246, v6
	v_cndmask_b32_e64 v246, v105, v104, s[88:89]
	v_min_u32_e32 v106, v248, v7
	v_max_u32_e32 v107, v248, v7
	v_cndmask_b32_e64 v248, v107, v106, s[88:89]
	v_xor_b32_e32 v116, 8, v234
	ds_bpermute_b32 v0, v116, v241
	ds_bpermute_b32 v1, v116, v243
	ds_bpermute_b32 v2, v116, v245
	ds_bpermute_b32 v3, v116, v247
	ds_bpermute_b32 v4, v116, v242
	ds_bpermute_b32 v5, v116, v244
	ds_bpermute_b32 v6, v116, v246
	ds_bpermute_b32 v7, v116, v248
	s_waitcnt lgkmcnt(0)
	s_mov_b32 s88, 0xc3c3c3c3
	s_mov_b32 s89, 0xc3c3c3c3
	v_min_u32_e32 v104, v241, v0
	v_max_u32_e32 v105, v241, v0
	v_cndmask_b32_e64 v241, v105, v104, s[88:89]
	v_min_u32_e32 v106, v243, v1
	v_max_u32_e32 v107, v243, v1
	v_cndmask_b32_e64 v243, v107, v106, s[88:89]
	v_min_u32_e32 v104, v245, v2
	v_max_u32_e32 v105, v245, v2
	v_cndmask_b32_e64 v245, v105, v104, s[88:89]
	v_min_u32_e32 v106, v247, v3
	v_max_u32_e32 v107, v247, v3
	v_cndmask_b32_e64 v247, v107, v106, s[88:89]
	v_min_u32_e32 v104, v242, v4
	v_max_u32_e32 v105, v242, v4
	v_cndmask_b32_e64 v242, v105, v104, s[88:89]
	v_min_u32_e32 v106, v244, v5
	v_max_u32_e32 v107, v244, v5
	v_cndmask_b32_e64 v244, v107, v106, s[88:89]
	v_min_u32_e32 v104, v246, v6
	v_max_u32_e32 v105, v246, v6
	v_cndmask_b32_e64 v246, v105, v104, s[88:89]
	v_min_u32_e32 v106, v248, v7
	v_max_u32_e32 v107, v248, v7
	v_cndmask_b32_e64 v248, v107, v106, s[88:89]
	v_xor_b32_e32 v116, 4, v234
	ds_bpermute_b32 v0, v116, v241
	ds_bpermute_b32 v1, v116, v243
	ds_bpermute_b32 v2, v116, v245
	ds_bpermute_b32 v3, v116, v247
	ds_bpermute_b32 v4, v116, v242
	ds_bpermute_b32 v5, v116, v244
	ds_bpermute_b32 v6, v116, v246
	ds_bpermute_b32 v7, v116, v248
	s_waitcnt lgkmcnt(0)
	s_mov_b32 s88, 0xa5a5a5a5
	s_mov_b32 s89, 0xa5a5a5a5
	v_min_u32_e32 v104, v241, v0
	v_max_u32_e32 v105, v241, v0
	v_cndmask_b32_e64 v241, v105, v104, s[88:89]
	v_min_u32_e32 v106, v243, v1
	v_max_u32_e32 v107, v243, v1
	v_cndmask_b32_e64 v243, v107, v106, s[88:89]
	v_min_u32_e32 v104, v245, v2
	v_max_u32_e32 v105, v245, v2
	v_cndmask_b32_e64 v245, v105, v104, s[88:89]
	v_min_u32_e32 v106, v247, v3
	v_max_u32_e32 v107, v247, v3
	v_cndmask_b32_e64 v247, v107, v106, s[88:89]
	v_min_u32_e32 v104, v242, v4
	v_max_u32_e32 v105, v242, v4
	v_cndmask_b32_e64 v242, v105, v104, s[88:89]
	v_min_u32_e32 v106, v244, v5
	v_max_u32_e32 v107, v244, v5
	v_cndmask_b32_e64 v244, v107, v106, s[88:89]
	v_min_u32_e32 v104, v246, v6
	v_max_u32_e32 v105, v246, v6
	v_cndmask_b32_e64 v246, v105, v104, s[88:89]
	v_min_u32_e32 v106, v248, v7
	v_max_u32_e32 v107, v248, v7
	v_cndmask_b32_e64 v248, v107, v106, s[88:89]
	v_xor_b32_e32 v116, 16, v234
	ds_bpermute_b32 v0, v116, v241
	ds_bpermute_b32 v1, v116, v243
	ds_bpermute_b32 v2, v116, v245
	ds_bpermute_b32 v3, v116, v247
	ds_bpermute_b32 v4, v116, v242
	ds_bpermute_b32 v5, v116, v244
	ds_bpermute_b32 v6, v116, v246
	ds_bpermute_b32 v7, v116, v248
	s_waitcnt lgkmcnt(0)
; DEV void sort_lists(int lane, int& myi0, int& myi1, float& myg0, float& myg1) {
; #pragma unroll
;     for (int k = 2; k <= 128; k <<= 1) {
; #pragma unroll
;       for (int j = k >> 1; j >= 1; j >>= 1) {
;         if (j == 64) {
;           const bool sw_ = myi1 < myi0;
;           const int ti = sw_ ? myi1 : myi0, tj = sw_ ? myi0 : myi1; const float tg = sw_ ? myg1 : myg0, th = sw_ ? myg0 : myg1;
;           myi0 = ti; myi1 = tj; myg0 = tg; myg1 = th;
;         } else {
;           const bool lower = (lane & j) == 0;
;           {
;             const bool up = (k == 128) ? true : ((k == 64) ? true : ((lane & k) == 0));
;             const int oi = __shfl_xor(myi0, j); const float og = __shfl_xor(myg0, j);
;             const bool take = (lower == up) ? (oi < myi0) : (oi > myi0);
;             myi0 = take ? oi : myi0; myg0 = take ? og : myg0;
;           }
;           {
;             const bool up = (k == 128) ? true : ((k == 64) ? false : ((lane & k) == 0));
;             const int oi = __shfl_xor(myi1, j); const float og = __shfl_xor(myg1, j);
;             const bool take = (lower == up) ? (oi < myi1) : (oi > myi1);
;             myi1 = take ? oi : myi1; myg1 = take ? og : myg1;
;           }
;         }
;       }
;     }
; }
	s_mov_b32 s88, 0xf00ff00f
	s_mov_b32 s89, 0xf00ff00f
	v_min_u32_e32 v104, v241, v0
	v_max_u32_e32 v105, v241, v0
	v_cndmask_b32_e64 v241, v105, v104, s[88:89]
	v_min_u32_e32 v106, v243, v1
	v_max_u32_e32 v107, v243, v1
	v_cndmask_b32_e64 v243, v107, v106, s[88:89]
	v_min_u32_e32 v104, v245, v2
	v_max_u32_e32 v105, v245, v2
	v_cndmask_b32_e64 v245, v105, v104, s[88:89]
	v_min_u32_e32 v106, v247, v3
	v_max_u32_e32 v107, v247, v3
	v_cndmask_b32_e64 v247, v107, v106, s[88:89]
	v_min_u32_e32 v104, v242, v4
	v_max_u32_e32 v105, v242, v4
	v_cndmask_b32_e64 v242, v105, v104, s[88:89]
	v_min_u32_e32 v106, v244, v5
	v_max_u32_e32 v107, v244, v5
	v_cndmask_b32_e64 v244, v107, v106, s[88:89]
	v_min_u32_e32 v104, v246, v6
	v_max_u32_e32 v105, v246, v6
	v_cndmask_b32_e64 v246, v105, v104, s[88:89]
	v_min_u32_e32 v106, v248, v7
	v_max_u32_e32 v107, v248, v7
	v_cndmask_b32_e64 v248, v107, v106, s[88:89]
	v_xor_b32_e32 v116, 8, v234
	ds_bpermute_b32 v0, v116, v241
	ds_bpermute_b32 v1, v116, v243
	ds_bpermute_b32 v2, v116, v245
	ds_bpermute_b32 v3, v116, v247
	ds_bpermute_b32 v4, v116, v242
	ds_bpermute_b32 v5, v116, v244
	ds_bpermute_b32 v6, v116, v246
	ds_bpermute_b32 v7, v116, v248
	s_waitcnt lgkmcnt(0)
	s_mov_b32 s88, 0xcc33cc33
	s_mov_b32 s89, 0xcc33cc33
	v_min_u32_e32 v104, v241, v0
	v_max_u32_e32 v105, v241, v0
	v_cndmask_b32_e64 v241, v105, v104, s[88:89]
	v_min_u32_e32 v106, v243, v1
	v_max_u32_e32 v107, v243, v1
	v_cndmask_b32_e64 v243, v107, v106, s[88:89]
	v_min_u32_e32 v104, v245, v2
	v_max_u32_e32 v105, v245, v2
	v_cndmask_b32_e64 v245, v105, v104, s[88:89]
	v_min_u32_e32 v106, v247, v3
	v_max_u32_e32 v107, v247, v3
	v_cndmask_b32_e64 v247, v107, v106, s[88:89]
	v_min_u32_e32 v104, v242, v4
	v_max_u32_e32 v105, v242, v4
	v_cndmask_b32_e64 v242, v105, v104, s[88:89]
	v_min_u32_e32 v106, v244, v5
	v_max_u32_e32 v107, v244, v5
	v_cndmask_b32_e64 v244, v107, v106, s[88:89]
	v_min_u32_e32 v104, v246, v6
	v_max_u32_e32 v105, v246, v6
	v_cndmask_b32_e64 v246, v105, v104, s[88:89]
	v_min_u32_e32 v106, v248, v7
	v_max_u32_e32 v107, v248, v7
	v_cndmask_b32_e64 v248, v107, v106, s[88:89]
	v_xor_b32_e32 v116, 4, v234
	ds_bpermute_b32 v0, v116, v241
	ds_bpermute_b32 v1, v116, v243
	ds_bpermute_b32 v2, v116, v245
	ds_bpermute_b32 v3, v116, v247
	ds_bpermute_b32 v4, v116, v242
	ds_bpermute_b32 v5, v116, v244
	ds_bpermute_b32 v6, v116, v246
	ds_bpermute_b32 v7, v116, v248
	s_waitcnt lgkmcnt(0)
	s_mov_b32 s88, 0xaa55aa55
	s_mov_b32 s89, 0xaa55aa55
	v_min_u32_e32 v104, v241, v0
	v_max_u32_e32 v105, v241, v0
	v_cndmask_b32_e64 v241, v105, v104, s[88:89]
	v_min_u32_e32 v106, v243, v1
	v_max_u32_e32 v107, v243, v1
	v_cndmask_b32_e64 v243, v107, v106, s[88:89]
	v_min_u32_e32 v104, v245, v2
	v_max_u32_e32 v105, v245, v2
	v_cndmask_b32_e64 v245, v105, v104, s[88:89]
	v_min_u32_e32 v106, v247, v3
	v_max_u32_e32 v107, v247, v3
	v_cndmask_b32_e64 v247, v107, v106, s[88:89]
	v_min_u32_e32 v104, v242, v4
	v_max_u32_e32 v105, v242, v4
	v_cndmask_b32_e64 v242, v105, v104, s[88:89]
	v_min_u32_e32 v106, v244, v5
	v_max_u32_e32 v107, v244, v5
	v_cndmask_b32_e64 v244, v107, v106, s[88:89]
	v_min_u32_e32 v104, v246, v6
	v_max_u32_e32 v105, v246, v6
	v_cndmask_b32_e64 v246, v105, v104, s[88:89]
	v_min_u32_e32 v106, v248, v7
	v_max_u32_e32 v107, v248, v7
	v_cndmask_b32_e64 v248, v107, v106, s[88:89]
	v_xor_b32_e32 v116, 32, v234
	ds_bpermute_b32 v0, v116, v241
	ds_bpermute_b32 v1, v116, v243
	ds_bpermute_b32 v2, v116, v245
	ds_bpermute_b32 v3, v116, v247
	ds_bpermute_b32 v4, v116, v242
	ds_bpermute_b32 v5, v116, v244
	ds_bpermute_b32 v6, v116, v246
	ds_bpermute_b32 v7, v116, v248
	s_waitcnt lgkmcnt(0)
	s_mov_b32 s88, 0xff0000ff
	s_mov_b32 s89, 0xff0000ff
	v_min_u32_e32 v104, v241, v0
	v_max_u32_e32 v105, v241, v0
	v_cndmask_b32_e64 v241, v105, v104, s[88:89]
	v_min_u32_e32 v106, v243, v1
	v_max_u32_e32 v107, v243, v1
	v_cndmask_b32_e64 v243, v107, v106, s[88:89]
	v_min_u32_e32 v104, v245, v2
	v_max_u32_e32 v105, v245, v2
	v_cndmask_b32_e64 v245, v105, v104, s[88:89]
	v_min_u32_e32 v106, v247, v3
	v_max_u32_e32 v107, v247, v3
	v_cndmask_b32_e64 v247, v107, v106, s[88:89]
	v_min_u32_e32 v104, v242, v4
	v_max_u32_e32 v105, v242, v4
	v_cndmask_b32_e64 v242, v105, v104, s[88:89]
	v_min_u32_e32 v106, v244, v5
	v_max_u32_e32 v107, v244, v5
	v_cndmask_b32_e64 v244, v107, v106, s[88:89]
	v_min_u32_e32 v104, v246, v6
	v_max_u32_e32 v105, v246, v6
	v_cndmask_b32_e64 v246, v105, v104, s[88:89]
	v_min_u32_e32 v106, v248, v7
	v_max_u32_e32 v107, v248, v7
	v_cndmask_b32_e64 v248, v107, v106, s[88:89]
	v_xor_b32_e32 v116, 16, v234
	ds_bpermute_b32 v0, v116, v241
	ds_bpermute_b32 v1, v116, v243
	ds_bpermute_b32 v2, v116, v245
	ds_bpermute_b32 v3, v116, v247
	ds_bpermute_b32 v4, v116, v242
	ds_bpermute_b32 v5, v116, v244
	ds_bpermute_b32 v6, v116, v246
	ds_bpermute_b32 v7, v116, v248
	s_waitcnt lgkmcnt(0)
	s_mov_b32 s88, 0xf0f00f0f
	s_mov_b32 s89, 0xf0f00f0f
	v_min_u32_e32 v104, v241, v0
	v_max_u32_e32 v105, v241, v0
	v_cndmask_b32_e64 v241, v105, v104, s[88:89]
	v_min_u32_e32 v106, v243, v1
	v_max_u32_e32 v107, v243, v1
	v_cndmask_b32_e64 v243, v107, v106, s[88:89]
	v_min_u32_e32 v104, v245, v2
	v_max_u32_e32 v105, v245, v2
	v_cndmask_b32_e64 v245, v105, v104, s[88:89]
	v_min_u32_e32 v106, v247, v3
	v_max_u32_e32 v107, v247, v3
	v_cndmask_b32_e64 v247, v107, v106, s[88:89]
	v_min_u32_e32 v104, v242, v4
	v_max_u32_e32 v105, v242, v4
	v_cndmask_b32_e64 v242, v105, v104, s[88:89]
	v_min_u32_e32 v106, v244, v5
	v_max_u32_e32 v107, v244, v5
	v_cndmask_b32_e64 v244, v107, v106, s[88:89]
	v_min_u32_e32 v104, v246, v6
	v_max_u32_e32 v105, v246, v6
	v_cndmask_b32_e64 v246, v105, v104, s[88:89]
	v_min_u32_e32 v106, v248, v7
	v_max_u32_e32 v107, v248, v7
	v_cndmask_b32_e64 v248, v107, v106, s[88:89]
	v_xor_b32_e32 v116, 8, v234
	ds_bpermute_b32 v0, v116, v241
	ds_bpermute_b32 v1, v116, v243
	ds_bpermute_b32 v2, v116, v245
	ds_bpermute_b32 v3, v116, v247
	ds_bpermute_b32 v4, v116, v242
	ds_bpermute_b32 v5, v116, v244
	ds_bpermute_b32 v6, v116, v246
	ds_bpermute_b32 v7, v116, v248
	s_waitcnt lgkmcnt(0)
; DEV void sort_lists(int lane, int& myi0, int& myi1, float& myg0, float& myg1) {
; #pragma unroll
;     for (int k = 2; k <= 128; k <<= 1) {
; #pragma unroll
;       for (int j = k >> 1; j >= 1; j >>= 1) {
;         if (j == 64) {
;           const bool sw_ = myi1 < myi0;
;           const int ti = sw_ ? myi1 : myi0, tj = sw_ ? myi0 : myi1; const float tg = sw_ ? myg1 : myg0, th = sw_ ? myg0 : myg1;
;           myi0 = ti; myi1 = tj; myg0 = tg; myg1 = th;
;         } else {
;           const bool lower = (lane & j) == 0;
;           {
;             const bool up = (k == 128) ? true : ((k == 64) ? true : ((lane & k) == 0));
;             const int oi = __shfl_xor(myi0, j); const float og = __shfl_xor(myg0, j);
;             const bool take = (lower == up) ? (oi < myi0) : (oi > myi0);
;             myi0 = take ? oi : myi0; myg0 = take ? og : myg0;
;           }
;           {
;             const bool up = (k == 128) ? true : ((k == 64) ? false : ((lane & k) == 0));
;             const int oi = __shfl_xor(myi1, j); const float og = __shfl_xor(myg1, j);
;             const bool take = (lower == up) ? (oi < myi1) : (oi > myi1);
;             myi1 = take ? oi : myi1; myg1 = take ? og : myg1;
;           }
;         }
;       }
;     }
; }
	s_mov_b32 s88, 0xcccc3333
	s_mov_b32 s89, 0xcccc3333
	v_min_u32_e32 v104, v241, v0
	v_max_u32_e32 v105, v241, v0
	v_cndmask_b32_e64 v241, v105, v104, s[88:89]
	v_min_u32_e32 v106, v243, v1
	v_max_u32_e32 v107, v243, v1
	v_cndmask_b32_e64 v243, v107, v106, s[88:89]
	v_min_u32_e32 v104, v245, v2
	v_max_u32_e32 v105, v245, v2
	v_cndmask_b32_e64 v245, v105, v104, s[88:89]
	v_min_u32_e32 v106, v247, v3
	v_max_u32_e32 v107, v247, v3
	v_cndmask_b32_e64 v247, v107, v106, s[88:89]
	v_min_u32_e32 v104, v242, v4
	v_max_u32_e32 v105, v242, v4
	v_cndmask_b32_e64 v242, v105, v104, s[88:89]
	v_min_u32_e32 v106, v244, v5
	v_max_u32_e32 v107, v244, v5
	v_cndmask_b32_e64 v244, v107, v106, s[88:89]
	v_min_u32_e32 v104, v246, v6
	v_max_u32_e32 v105, v246, v6
	v_cndmask_b32_e64 v246, v105, v104, s[88:89]
	v_min_u32_e32 v106, v248, v7
	v_max_u32_e32 v107, v248, v7
	v_cndmask_b32_e64 v248, v107, v106, s[88:89]
	v_xor_b32_e32 v116, 4, v234
	ds_bpermute_b32 v0, v116, v241
	ds_bpermute_b32 v1, v116, v243
	ds_bpermute_b32 v2, v116, v245
	ds_bpermute_b32 v3, v116, v247
	ds_bpermute_b32 v4, v116, v242
	ds_bpermute_b32 v5, v116, v244
	ds_bpermute_b32 v6, v116, v246
	ds_bpermute_b32 v7, v116, v248
	s_waitcnt lgkmcnt(0)
	s_mov_b32 s88, 0xaaaa5555
	s_mov_b32 s89, 0xaaaa5555
	v_min_u32_e32 v104, v241, v0
	v_max_u32_e32 v105, v241, v0
	v_cndmask_b32_e64 v241, v105, v104, s[88:89]
	v_min_u32_e32 v106, v243, v1
	v_max_u32_e32 v107, v243, v1
	v_cndmask_b32_e64 v243, v107, v106, s[88:89]
	v_min_u32_e32 v104, v245, v2
	v_max_u32_e32 v105, v245, v2
	v_cndmask_b32_e64 v245, v105, v104, s[88:89]
	v_min_u32_e32 v106, v247, v3
	v_max_u32_e32 v107, v247, v3
	v_cndmask_b32_e64 v247, v107, v106, s[88:89]
	v_min_u32_e32 v104, v242, v4
	v_max_u32_e32 v105, v242, v4
	v_cndmask_b32_e64 v242, v105, v104, s[88:89]
	v_min_u32_e32 v106, v244, v5
	v_max_u32_e32 v107, v244, v5
	v_cndmask_b32_e64 v244, v107, v106, s[88:89]
	v_min_u32_e32 v104, v246, v6
	v_max_u32_e32 v105, v246, v6
	v_cndmask_b32_e64 v246, v105, v104, s[88:89]
	v_min_u32_e32 v106, v248, v7
	v_max_u32_e32 v107, v248, v7
	v_cndmask_b32_e64 v248, v107, v106, s[88:89]
	v_xor_b32_e32 v116, 64, v234
	ds_bpermute_b32 v0, v116, v241
	ds_bpermute_b32 v1, v116, v243
	ds_bpermute_b32 v2, v116, v245
	ds_bpermute_b32 v3, v116, v247
	ds_bpermute_b32 v4, v116, v242
	ds_bpermute_b32 v5, v116, v244
	ds_bpermute_b32 v6, v116, v246
	ds_bpermute_b32 v7, v116, v248
	s_waitcnt lgkmcnt(0)
	s_mov_b32 s88, 0xffff
	s_mov_b32 s89, 0xffff0000
	v_min_u32_e32 v104, v241, v0
	v_max_u32_e32 v105, v241, v0
	v_cndmask_b32_e64 v241, v105, v104, s[88:89]
	v_min_u32_e32 v106, v243, v1
	v_max_u32_e32 v107, v243, v1
	v_cndmask_b32_e64 v243, v107, v106, s[88:89]
	v_min_u32_e32 v104, v245, v2
	v_max_u32_e32 v105, v245, v2
	v_cndmask_b32_e64 v245, v105, v104, s[88:89]
	v_min_u32_e32 v106, v247, v3
	v_max_u32_e32 v107, v247, v3
	v_cndmask_b32_e64 v247, v107, v106, s[88:89]
	v_min_u32_e32 v104, v242, v4
	v_max_u32_e32 v105, v242, v4
	v_cndmask_b32_e64 v242, v105, v104, s[88:89]
	v_min_u32_e32 v106, v244, v5
	v_max_u32_e32 v107, v244, v5
	v_cndmask_b32_e64 v244, v107, v106, s[88:89]
	v_min_u32_e32 v104, v246, v6
	v_max_u32_e32 v105, v246, v6
	v_cndmask_b32_e64 v246, v105, v104, s[88:89]
	v_min_u32_e32 v106, v248, v7
	v_max_u32_e32 v107, v248, v7
	v_cndmask_b32_e64 v248, v107, v106, s[88:89]
	v_xor_b32_e32 v116, 32, v234
	ds_bpermute_b32 v0, v116, v241
	ds_bpermute_b32 v1, v116, v243
	ds_bpermute_b32 v2, v116, v245
	ds_bpermute_b32 v3, v116, v247
	ds_bpermute_b32 v4, v116, v242
	ds_bpermute_b32 v5, v116, v244
	ds_bpermute_b32 v6, v116, v246
	ds_bpermute_b32 v7, v116, v248
	s_waitcnt lgkmcnt(0)
	s_mov_b32 s88, 0xff00ff
	s_mov_b32 s89, 0xff00ff00
	v_min_u32_e32 v104, v241, v0
	v_max_u32_e32 v105, v241, v0
	v_cndmask_b32_e64 v241, v105, v104, s[88:89]
	v_min_u32_e32 v106, v243, v1
	v_max_u32_e32 v107, v243, v1
	v_cndmask_b32_e64 v243, v107, v106, s[88:89]
	v_min_u32_e32 v104, v245, v2
	v_max_u32_e32 v105, v245, v2
	v_cndmask_b32_e64 v245, v105, v104, s[88:89]
	v_min_u32_e32 v106, v247, v3
	v_max_u32_e32 v107, v247, v3
	v_cndmask_b32_e64 v247, v107, v106, s[88:89]
	v_min_u32_e32 v104, v242, v4
	v_max_u32_e32 v105, v242, v4
	v_cndmask_b32_e64 v242, v105, v104, s[88:89]
	v_min_u32_e32 v106, v244, v5
	v_max_u32_e32 v107, v244, v5
	v_cndmask_b32_e64 v244, v107, v106, s[88:89]
	v_min_u32_e32 v104, v246, v6
	v_max_u32_e32 v105, v246, v6
	v_cndmask_b32_e64 v246, v105, v104, s[88:89]
	v_min_u32_e32 v106, v248, v7
	v_max_u32_e32 v107, v248, v7
	v_cndmask_b32_e64 v248, v107, v106, s[88:89]
	v_xor_b32_e32 v116, 16, v234
	ds_bpermute_b32 v0, v116, v241
	ds_bpermute_b32 v1, v116, v243
	ds_bpermute_b32 v2, v116, v245
	ds_bpermute_b32 v3, v116, v247
	ds_bpermute_b32 v4, v116, v242
	ds_bpermute_b32 v5, v116, v244
	ds_bpermute_b32 v6, v116, v246
	ds_bpermute_b32 v7, v116, v248
	s_waitcnt lgkmcnt(0)
	s_mov_b32 s88, 0xf0f0f0f
	s_mov_b32 s89, 0xf0f0f0f0
	v_min_u32_e32 v104, v241, v0
	v_max_u32_e32 v105, v241, v0
	v_cndmask_b32_e64 v241, v105, v104, s[88:89]
	v_min_u32_e32 v106, v243, v1
	v_max_u32_e32 v107, v243, v1
	v_cndmask_b32_e64 v243, v107, v106, s[88:89]
	v_min_u32_e32 v104, v245, v2
	v_max_u32_e32 v105, v245, v2
	v_cndmask_b32_e64 v245, v105, v104, s[88:89]
	v_min_u32_e32 v106, v247, v3
	v_max_u32_e32 v107, v247, v3
	v_cndmask_b32_e64 v247, v107, v106, s[88:89]
	v_min_u32_e32 v104, v242, v4
	v_max_u32_e32 v105, v242, v4
	v_cndmask_b32_e64 v242, v105, v104, s[88:89]
	v_min_u32_e32 v106, v244, v5
	v_max_u32_e32 v107, v244, v5
	v_cndmask_b32_e64 v244, v107, v106, s[88:89]
	v_min_u32_e32 v104, v246, v6
	v_max_u32_e32 v105, v246, v6
	v_cndmask_b32_e64 v246, v105, v104, s[88:89]
	v_min_u32_e32 v106, v248, v7
	v_max_u32_e32 v107, v248, v7
	v_cndmask_b32_e64 v248, v107, v106, s[88:89]
	v_xor_b32_e32 v116, 8, v234
	ds_bpermute_b32 v0, v116, v241
	ds_bpermute_b32 v1, v116, v243
	ds_bpermute_b32 v2, v116, v245
	ds_bpermute_b32 v3, v116, v247
	ds_bpermute_b32 v4, v116, v242
	ds_bpermute_b32 v5, v116, v244
	ds_bpermute_b32 v6, v116, v246
	ds_bpermute_b32 v7, v116, v248
	s_waitcnt lgkmcnt(0)
; DEV void sort_lists(int lane, int& myi0, int& myi1, float& myg0, float& myg1) {
; #pragma unroll
;     for (int k = 2; k <= 128; k <<= 1) {
; #pragma unroll
;       for (int j = k >> 1; j >= 1; j >>= 1) {
;         if (j == 64) {
;           const bool sw_ = myi1 < myi0;
;           const int ti = sw_ ? myi1 : myi0, tj = sw_ ? myi0 : myi1; const float tg = sw_ ? myg1 : myg0, th = sw_ ? myg0 : myg1;
;           myi0 = ti; myi1 = tj; myg0 = tg; myg1 = th;
;         } else {
;           const bool lower = (lane & j) == 0;
;           {
;             const bool up = (k == 128) ? true : ((k == 64) ? true : ((lane & k) == 0));
;             const int oi = __shfl_xor(myi0, j); const float og = __shfl_xor(myg0, j);
;             const bool take = (lower == up) ? (oi < myi0) : (oi > myi0);
;             myi0 = take ? oi : myi0; myg0 = take ? og : myg0;
;           }
;           {
;             const bool up = (k == 128) ? true : ((k == 64) ? false : ((lane & k) == 0));
;             const int oi = __shfl_xor(myi1, j); const float og = __shfl_xor(myg1, j);
;             const bool take = (lower == up) ? (oi < myi1) : (oi > myi1);
;             myi1 = take ? oi : myi1; myg1 = take ? og : myg1;
;           }
;         }
;       }
;     }
; }
	s_mov_b32 s88, 0x33333333
	s_mov_b32 s89, 0xcccccccc
	v_min_u32_e32 v104, v241, v0
	v_max_u32_e32 v105, v241, v0
	v_cndmask_b32_e64 v241, v105, v104, s[88:89]
	v_min_u32_e32 v106, v243, v1
	v_max_u32_e32 v107, v243, v1
	v_cndmask_b32_e64 v243, v107, v106, s[88:89]
	v_min_u32_e32 v104, v245, v2
	v_max_u32_e32 v105, v245, v2
	v_cndmask_b32_e64 v245, v105, v104, s[88:89]
	v_min_u32_e32 v106, v247, v3
	v_max_u32_e32 v107, v247, v3
	v_cndmask_b32_e64 v247, v107, v106, s[88:89]
	v_min_u32_e32 v104, v242, v4
	v_max_u32_e32 v105, v242, v4
	v_cndmask_b32_e64 v242, v105, v104, s[88:89]
	v_min_u32_e32 v106, v244, v5
	v_max_u32_e32 v107, v244, v5
	v_cndmask_b32_e64 v244, v107, v106, s[88:89]
	v_min_u32_e32 v104, v246, v6
	v_max_u32_e32 v105, v246, v6
	v_cndmask_b32_e64 v246, v105, v104, s[88:89]
	v_min_u32_e32 v106, v248, v7
	v_max_u32_e32 v107, v248, v7
	v_cndmask_b32_e64 v248, v107, v106, s[88:89]
	v_xor_b32_e32 v116, 4, v234
	ds_bpermute_b32 v0, v116, v241
	ds_bpermute_b32 v1, v116, v243
	ds_bpermute_b32 v2, v116, v245
	ds_bpermute_b32 v3, v116, v247
	ds_bpermute_b32 v4, v116, v242
	ds_bpermute_b32 v5, v116, v244
	ds_bpermute_b32 v6, v116, v246
	ds_bpermute_b32 v7, v116, v248
	s_waitcnt lgkmcnt(0)
	s_mov_b32 s88, 0x55555555
	s_mov_b32 s89, 0xaaaaaaaa
	v_min_u32_e32 v104, v241, v0
	v_max_u32_e32 v105, v241, v0
	v_cndmask_b32_e64 v241, v105, v104, s[88:89]
	v_min_u32_e32 v106, v243, v1
	v_max_u32_e32 v107, v243, v1
	v_cndmask_b32_e64 v243, v107, v106, s[88:89]
	v_min_u32_e32 v104, v245, v2
	v_max_u32_e32 v105, v245, v2
	v_cndmask_b32_e64 v245, v105, v104, s[88:89]
	v_min_u32_e32 v106, v247, v3
	v_max_u32_e32 v107, v247, v3
	v_cndmask_b32_e64 v247, v107, v106, s[88:89]
	v_min_u32_e32 v104, v242, v4
	v_max_u32_e32 v105, v242, v4
	v_cndmask_b32_e64 v242, v105, v104, s[88:89]
	v_min_u32_e32 v106, v244, v5
	v_max_u32_e32 v107, v244, v5
	v_cndmask_b32_e64 v244, v107, v106, s[88:89]
	v_min_u32_e32 v104, v246, v6
	v_max_u32_e32 v105, v246, v6
	v_cndmask_b32_e64 v246, v105, v104, s[88:89]
	v_min_u32_e32 v106, v248, v7
	v_max_u32_e32 v107, v248, v7
	v_cndmask_b32_e64 v248, v107, v106, s[88:89]
	v_xor_b32_e32 v116, 128, v234
	ds_bpermute_b32 v0, v116, v241
	ds_bpermute_b32 v1, v116, v243
	ds_bpermute_b32 v2, v116, v245
	ds_bpermute_b32 v3, v116, v247
	ds_bpermute_b32 v4, v116, v242
	ds_bpermute_b32 v5, v116, v244
	ds_bpermute_b32 v6, v116, v246
	ds_bpermute_b32 v7, v116, v248
	s_waitcnt lgkmcnt(0)
	s_mov_b32 s88, 0xffffffff
	s_mov_b32 s89, 0x0
	v_min_u32_e32 v104, v241, v0
	v_max_u32_e32 v105, v241, v0
	v_cndmask_b32_e64 v241, v105, v104, s[88:89]
	v_min_u32_e32 v106, v243, v1
	v_max_u32_e32 v107, v243, v1
	v_cndmask_b32_e64 v243, v107, v106, s[88:89]
	v_min_u32_e32 v104, v245, v2
	v_max_u32_e32 v105, v245, v2
	v_cndmask_b32_e64 v245, v105, v104, s[88:89]
	v_min_u32_e32 v106, v247, v3
	v_max_u32_e32 v107, v247, v3
	v_cndmask_b32_e64 v247, v107, v106, s[88:89]
	s_mov_b32 s88, 0x0
	s_mov_b32 s89, 0xffffffff
	v_min_u32_e32 v104, v242, v4
	v_max_u32_e32 v105, v242, v4
	v_cndmask_b32_e64 v242, v105, v104, s[88:89]
	v_min_u32_e32 v106, v244, v5
	v_max_u32_e32 v107, v244, v5
	v_cndmask_b32_e64 v244, v107, v106, s[88:89]
	v_min_u32_e32 v104, v246, v6
	v_max_u32_e32 v105, v246, v6
	v_cndmask_b32_e64 v246, v105, v104, s[88:89]
	v_min_u32_e32 v106, v248, v7
	v_max_u32_e32 v107, v248, v7
	v_cndmask_b32_e64 v248, v107, v106, s[88:89]
	v_xor_b32_e32 v116, 64, v234
	ds_bpermute_b32 v0, v116, v241
	ds_bpermute_b32 v1, v116, v243
	ds_bpermute_b32 v2, v116, v245
	ds_bpermute_b32 v3, v116, v247
	ds_bpermute_b32 v4, v116, v242
	ds_bpermute_b32 v5, v116, v244
	ds_bpermute_b32 v6, v116, v246
	ds_bpermute_b32 v7, v116, v248
	s_waitcnt lgkmcnt(0)
	s_mov_b32 s88, 0xffff
	s_mov_b32 s89, 0xffff
	v_min_u32_e32 v104, v241, v0
	v_max_u32_e32 v105, v241, v0
	v_cndmask_b32_e64 v241, v105, v104, s[88:89]
	v_min_u32_e32 v106, v243, v1
	v_max_u32_e32 v107, v243, v1
	v_cndmask_b32_e64 v243, v107, v106, s[88:89]
	v_min_u32_e32 v104, v245, v2
	v_max_u32_e32 v105, v245, v2
	v_cndmask_b32_e64 v245, v105, v104, s[88:89]
	v_min_u32_e32 v106, v247, v3
	v_max_u32_e32 v107, v247, v3
	v_cndmask_b32_e64 v247, v107, v106, s[88:89]
	s_mov_b32 s88, 0xffff0000
	s_mov_b32 s89, 0xffff0000
	v_min_u32_e32 v104, v242, v4
	v_max_u32_e32 v105, v242, v4
	v_cndmask_b32_e64 v242, v105, v104, s[88:89]
	v_min_u32_e32 v106, v244, v5
	v_max_u32_e32 v107, v244, v5
	v_cndmask_b32_e64 v244, v107, v106, s[88:89]
	v_min_u32_e32 v104, v246, v6
	v_max_u32_e32 v105, v246, v6
	v_cndmask_b32_e64 v246, v105, v104, s[88:89]
	v_min_u32_e32 v106, v248, v7
	v_max_u32_e32 v107, v248, v7
	v_cndmask_b32_e64 v248, v107, v106, s[88:89]
	v_xor_b32_e32 v116, 32, v234
	ds_bpermute_b32 v0, v116, v241
	ds_bpermute_b32 v1, v116, v243
	ds_bpermute_b32 v2, v116, v245
	ds_bpermute_b32 v3, v116, v247
	ds_bpermute_b32 v4, v116, v242
	ds_bpermute_b32 v5, v116, v244
	ds_bpermute_b32 v6, v116, v246
	ds_bpermute_b32 v7, v116, v248
	s_waitcnt lgkmcnt(0)
	s_mov_b32 s88, 0xff00ff
	s_mov_b32 s89, 0xff00ff
	v_min_u32_e32 v104, v241, v0
	v_max_u32_e32 v105, v241, v0
	v_cndmask_b32_e64 v241, v105, v104, s[88:89]
	v_min_u32_e32 v106, v243, v1
	v_max_u32_e32 v107, v243, v1
	v_cndmask_b32_e64 v243, v107, v106, s[88:89]
	v_min_u32_e32 v104, v245, v2
	v_max_u32_e32 v105, v245, v2
	v_cndmask_b32_e64 v245, v105, v104, s[88:89]
	v_min_u32_e32 v106, v247, v3
	v_max_u32_e32 v107, v247, v3
	v_cndmask_b32_e64 v247, v107, v106, s[88:89]
	s_mov_b32 s88, 0xff00ff00
	s_mov_b32 s89, 0xff00ff00
	v_min_u32_e32 v104, v242, v4
	v_max_u32_e32 v105, v242, v4
	v_cndmask_b32_e64 v242, v105, v104, s[88:89]
	v_min_u32_e32 v106, v244, v5
	v_max_u32_e32 v107, v244, v5
	v_cndmask_b32_e64 v244, v107, v106, s[88:89]
	v_min_u32_e32 v104, v246, v6
	v_max_u32_e32 v105, v246, v6
	v_cndmask_b32_e64 v246, v105, v104, s[88:89]
	v_min_u32_e32 v106, v248, v7
	v_max_u32_e32 v107, v248, v7
	v_cndmask_b32_e64 v248, v107, v106, s[88:89]
	v_xor_b32_e32 v116, 16, v234
	ds_bpermute_b32 v0, v116, v241
	ds_bpermute_b32 v1, v116, v243
	ds_bpermute_b32 v2, v116, v245
	ds_bpermute_b32 v3, v116, v247
	ds_bpermute_b32 v4, v116, v242
	ds_bpermute_b32 v5, v116, v244
	ds_bpermute_b32 v6, v116, v246
	ds_bpermute_b32 v7, v116, v248
	s_waitcnt lgkmcnt(0)
; DEV void sort_lists(int lane, int& myi0, int& myi1, float& myg0, float& myg1) {
; #pragma unroll
;     for (int k = 2; k <= 128; k <<= 1) {
; #pragma unroll
;       for (int j = k >> 1; j >= 1; j >>= 1) {
;         if (j == 64) {
;           const bool sw_ = myi1 < myi0;
;           const int ti = sw_ ? myi1 : myi0, tj = sw_ ? myi0 : myi1; const float tg = sw_ ? myg1 : myg0, th = sw_ ? myg0 : myg1;
;           myi0 = ti; myi1 = tj; myg0 = tg; myg1 = th;
;         } else {
;           const bool lower = (lane & j) == 0;
;           {
;             const bool up = (k == 128) ? true : ((k == 64) ? true : ((lane & k) == 0));
;             const int oi = __shfl_xor(myi0, j); const float og = __shfl_xor(myg0, j);
;             const bool take = (lower == up) ? (oi < myi0) : (oi > myi0);
;             myi0 = take ? oi : myi0; myg0 = take ? og : myg0;
;           }
;           {
;             const bool up = (k == 128) ? true : ((k == 64) ? false : ((lane & k) == 0));
;             const int oi = __shfl_xor(myi1, j); const float og = __shfl_xor(myg1, j);
;             const bool take = (lower == up) ? (oi < myi1) : (oi > myi1);
;             myi1 = take ? oi : myi1; myg1 = take ? og : myg1;
;           }
;         }
;       }
;     }
; }
	s_mov_b32 s88, 0xf0f0f0f
	s_mov_b32 s89, 0xf0f0f0f
	v_min_u32_e32 v104, v241, v0
	v_max_u32_e32 v105, v241, v0
	v_cndmask_b32_e64 v241, v105, v104, s[88:89]
	v_min_u32_e32 v106, v243, v1
	v_max_u32_e32 v107, v243, v1
	v_cndmask_b32_e64 v243, v107, v106, s[88:89]
	v_min_u32_e32 v104, v245, v2
	v_max_u32_e32 v105, v245, v2
	v_cndmask_b32_e64 v245, v105, v104, s[88:89]
	v_min_u32_e32 v106, v247, v3
	v_max_u32_e32 v107, v247, v3
	v_cndmask_b32_e64 v247, v107, v106, s[88:89]
	s_mov_b32 s88, 0xf0f0f0f0
	s_mov_b32 s89, 0xf0f0f0f0
	v_min_u32_e32 v104, v242, v4
	v_max_u32_e32 v105, v242, v4
	v_cndmask_b32_e64 v242, v105, v104, s[88:89]
	v_min_u32_e32 v106, v244, v5
	v_max_u32_e32 v107, v244, v5
	v_cndmask_b32_e64 v244, v107, v106, s[88:89]
	v_min_u32_e32 v104, v246, v6
	v_max_u32_e32 v105, v246, v6
	v_cndmask_b32_e64 v246, v105, v104, s[88:89]
	v_min_u32_e32 v106, v248, v7
	v_max_u32_e32 v107, v248, v7
	v_cndmask_b32_e64 v248, v107, v106, s[88:89]
	v_xor_b32_e32 v116, 8, v234
	ds_bpermute_b32 v0, v116, v241
	ds_bpermute_b32 v1, v116, v243
	ds_bpermute_b32 v2, v116, v245
	ds_bpermute_b32 v3, v116, v247
	ds_bpermute_b32 v4, v116, v242
	ds_bpermute_b32 v5, v116, v244
	ds_bpermute_b32 v6, v116, v246
	ds_bpermute_b32 v7, v116, v248
	s_waitcnt lgkmcnt(0)
	s_mov_b32 s88, 0x33333333
	s_mov_b32 s89, 0x33333333
	v_min_u32_e32 v104, v241, v0
	v_max_u32_e32 v105, v241, v0
	v_cndmask_b32_e64 v241, v105, v104, s[88:89]
	v_min_u32_e32 v106, v243, v1
	v_max_u32_e32 v107, v243, v1
	v_cndmask_b32_e64 v243, v107, v106, s[88:89]
	v_min_u32_e32 v104, v245, v2
	v_max_u32_e32 v105, v245, v2
	v_cndmask_b32_e64 v245, v105, v104, s[88:89]
	v_min_u32_e32 v106, v247, v3
	v_max_u32_e32 v107, v247, v3
	v_cndmask_b32_e64 v247, v107, v106, s[88:89]
	s_mov_b32 s88, 0xcccccccc
	s_mov_b32 s89, 0xcccccccc
	v_min_u32_e32 v104, v242, v4
	v_max_u32_e32 v105, v242, v4
	v_cndmask_b32_e64 v242, v105, v104, s[88:89]
	v_min_u32_e32 v106, v244, v5
	v_max_u32_e32 v107, v244, v5
	v_cndmask_b32_e64 v244, v107, v106, s[88:89]
	v_min_u32_e32 v104, v246, v6
	v_max_u32_e32 v105, v246, v6
	v_cndmask_b32_e64 v246, v105, v104, s[88:89]
	v_min_u32_e32 v106, v248, v7
	v_max_u32_e32 v107, v248, v7
	v_cndmask_b32_e64 v248, v107, v106, s[88:89]
	v_xor_b32_e32 v116, 4, v234
	ds_bpermute_b32 v0, v116, v241
	ds_bpermute_b32 v1, v116, v243
	ds_bpermute_b32 v2, v116, v245
	ds_bpermute_b32 v3, v116, v247
	ds_bpermute_b32 v4, v116, v242
	ds_bpermute_b32 v5, v116, v244
	ds_bpermute_b32 v6, v116, v246
	ds_bpermute_b32 v7, v116, v248
	s_waitcnt lgkmcnt(0)
	s_mov_b32 s88, 0x55555555
	s_mov_b32 s89, 0x55555555
	v_min_u32_e32 v104, v241, v0
	v_max_u32_e32 v105, v241, v0
	v_cndmask_b32_e64 v241, v105, v104, s[88:89]
	v_min_u32_e32 v106, v243, v1
	v_max_u32_e32 v107, v243, v1
	v_cndmask_b32_e64 v243, v107, v106, s[88:89]
	v_min_u32_e32 v104, v245, v2
	v_max_u32_e32 v105, v245, v2
	v_cndmask_b32_e64 v245, v105, v104, s[88:89]
	v_min_u32_e32 v106, v247, v3
	v_max_u32_e32 v107, v247, v3
	v_cndmask_b32_e64 v247, v107, v106, s[88:89]
	s_mov_b32 s88, 0xaaaaaaaa
	s_mov_b32 s89, 0xaaaaaaaa
	v_min_u32_e32 v104, v242, v4
	v_max_u32_e32 v105, v242, v4
	v_cndmask_b32_e64 v242, v105, v104, s[88:89]
	v_min_u32_e32 v106, v244, v5
	v_max_u32_e32 v107, v244, v5
	v_cndmask_b32_e64 v244, v107, v106, s[88:89]
	v_min_u32_e32 v104, v246, v6
	v_max_u32_e32 v105, v246, v6
	v_cndmask_b32_e64 v246, v105, v104, s[88:89]
	v_min_u32_e32 v106, v248, v7
	v_max_u32_e32 v107, v248, v7
	v_cndmask_b32_e64 v248, v107, v106, s[88:89]
	v_min_u32_e32 v104, v241, v242
	v_max_u32_e32 v242, v241, v242
	v_mov_b32_e32 v241, v104
	v_min_u32_e32 v106, v243, v244
	v_max_u32_e32 v244, v243, v244
	v_mov_b32_e32 v243, v106
	v_min_u32_e32 v104, v245, v246
	v_max_u32_e32 v246, v245, v246
	v_mov_b32_e32 v245, v104
	v_min_u32_e32 v106, v247, v248
	v_max_u32_e32 v248, v247, v248
	v_mov_b32_e32 v247, v106
	v_xor_b32_e32 v116, 128, v234
	ds_bpermute_b32 v0, v116, v241
	ds_bpermute_b32 v1, v116, v243
	ds_bpermute_b32 v2, v116, v245
	ds_bpermute_b32 v3, v116, v247
	ds_bpermute_b32 v4, v116, v242
	ds_bpermute_b32 v5, v116, v244
	ds_bpermute_b32 v6, v116, v246
	ds_bpermute_b32 v7, v116, v248
	s_waitcnt lgkmcnt(0)
	s_mov_b32 s88, 0xffffffff
	s_mov_b32 s89, 0x0
	v_min_u32_e32 v104, v241, v0
	v_max_u32_e32 v105, v241, v0
	v_cndmask_b32_e64 v241, v105, v104, s[88:89]
	v_min_u32_e32 v106, v243, v1
	v_max_u32_e32 v107, v243, v1
	v_cndmask_b32_e64 v243, v107, v106, s[88:89]
	v_min_u32_e32 v104, v245, v2
	v_max_u32_e32 v105, v245, v2
	v_cndmask_b32_e64 v245, v105, v104, s[88:89]
	v_min_u32_e32 v106, v247, v3
	v_max_u32_e32 v107, v247, v3
	v_cndmask_b32_e64 v247, v107, v106, s[88:89]
	v_min_u32_e32 v104, v242, v4
	v_max_u32_e32 v105, v242, v4
	v_cndmask_b32_e64 v242, v105, v104, s[88:89]
	v_min_u32_e32 v106, v244, v5
	v_max_u32_e32 v107, v244, v5
	v_cndmask_b32_e64 v244, v107, v106, s[88:89]
	v_min_u32_e32 v104, v246, v6
	v_max_u32_e32 v105, v246, v6
	v_cndmask_b32_e64 v246, v105, v104, s[88:89]
	v_min_u32_e32 v106, v248, v7
	v_max_u32_e32 v107, v248, v7
	v_cndmask_b32_e64 v248, v107, v106, s[88:89]
	v_xor_b32_e32 v116, 64, v234
	ds_bpermute_b32 v0, v116, v241
	ds_bpermute_b32 v1, v116, v243
	ds_bpermute_b32 v2, v116, v245
	ds_bpermute_b32 v3, v116, v247
	ds_bpermute_b32 v4, v116, v242
	ds_bpermute_b32 v5, v116, v244
	ds_bpermute_b32 v6, v116, v246
	ds_bpermute_b32 v7, v116, v248
	s_waitcnt lgkmcnt(0)
; DEV void sort_lists(int lane, int& myi0, int& myi1, float& myg0, float& myg1) {
; #pragma unroll
;     for (int k = 2; k <= 128; k <<= 1) {
; #pragma unroll
;       for (int j = k >> 1; j >= 1; j >>= 1) {
;         if (j == 64) {
;           const bool sw_ = myi1 < myi0;
;           const int ti = sw_ ? myi1 : myi0, tj = sw_ ? myi0 : myi1; const float tg = sw_ ? myg1 : myg0, th = sw_ ? myg0 : myg1;
;           myi0 = ti; myi1 = tj; myg0 = tg; myg1 = th;
;         } else {
;           const bool lower = (lane & j) == 0;
;           {
;             const bool up = (k == 128) ? true : ((k == 64) ? true : ((lane & k) == 0));
;             const int oi = __shfl_xor(myi0, j); const float og = __shfl_xor(myg0, j);
;             const bool take = (lower == up) ? (oi < myi0) : (oi > myi0);
;             myi0 = take ? oi : myi0; myg0 = take ? og : myg0;
;           }
;           {
;             const bool up = (k == 128) ? true : ((k == 64) ? false : ((lane & k) == 0));
;             const int oi = __shfl_xor(myi1, j); const float og = __shfl_xor(myg1, j);
;             const bool take = (lower == up) ? (oi < myi1) : (oi > myi1);
;             myi1 = take ? oi : myi1; myg1 = take ? og : myg1;
;           }
;         }
;       }
;     }
; }
	s_mov_b32 s88, 0xffff
	s_mov_b32 s89, 0xffff
	v_min_u32_e32 v104, v241, v0
	v_max_u32_e32 v105, v241, v0
	v_cndmask_b32_e64 v241, v105, v104, s[88:89]
	v_min_u32_e32 v106, v243, v1
	v_max_u32_e32 v107, v243, v1
	v_cndmask_b32_e64 v243, v107, v106, s[88:89]
	v_min_u32_e32 v104, v245, v2
	v_max_u32_e32 v105, v245, v2
	v_cndmask_b32_e64 v245, v105, v104, s[88:89]
	v_min_u32_e32 v106, v247, v3
	v_max_u32_e32 v107, v247, v3
	v_cndmask_b32_e64 v247, v107, v106, s[88:89]
	v_min_u32_e32 v104, v242, v4
	v_max_u32_e32 v105, v242, v4
	v_cndmask_b32_e64 v242, v105, v104, s[88:89]
	v_min_u32_e32 v106, v244, v5
	v_max_u32_e32 v107, v244, v5
	v_cndmask_b32_e64 v244, v107, v106, s[88:89]
	v_min_u32_e32 v104, v246, v6
	v_max_u32_e32 v105, v246, v6
	v_cndmask_b32_e64 v246, v105, v104, s[88:89]
	v_min_u32_e32 v106, v248, v7
	v_max_u32_e32 v107, v248, v7
	v_cndmask_b32_e64 v248, v107, v106, s[88:89]
	v_xor_b32_e32 v116, 32, v234
	ds_bpermute_b32 v0, v116, v241
	ds_bpermute_b32 v1, v116, v243
	ds_bpermute_b32 v2, v116, v245
	ds_bpermute_b32 v3, v116, v247
	ds_bpermute_b32 v4, v116, v242
	ds_bpermute_b32 v5, v116, v244
	ds_bpermute_b32 v6, v116, v246
	ds_bpermute_b32 v7, v116, v248
	s_waitcnt lgkmcnt(0)
	s_mov_b32 s88, 0xff00ff
	s_mov_b32 s89, 0xff00ff
	v_min_u32_e32 v104, v241, v0
	v_max_u32_e32 v105, v241, v0
	v_cndmask_b32_e64 v241, v105, v104, s[88:89]
	v_min_u32_e32 v106, v243, v1
	v_max_u32_e32 v107, v243, v1
	v_cndmask_b32_e64 v243, v107, v106, s[88:89]
	v_min_u32_e32 v104, v245, v2
	v_max_u32_e32 v105, v245, v2
	v_cndmask_b32_e64 v245, v105, v104, s[88:89]
	v_min_u32_e32 v106, v247, v3
	v_max_u32_e32 v107, v247, v3
	v_cndmask_b32_e64 v247, v107, v106, s[88:89]
	v_min_u32_e32 v104, v242, v4
	v_max_u32_e32 v105, v242, v4
	v_cndmask_b32_e64 v242, v105, v104, s[88:89]
	v_min_u32_e32 v106, v244, v5
	v_max_u32_e32 v107, v244, v5
	v_cndmask_b32_e64 v244, v107, v106, s[88:89]
	v_min_u32_e32 v104, v246, v6
	v_max_u32_e32 v105, v246, v6
	v_cndmask_b32_e64 v246, v105, v104, s[88:89]
	v_min_u32_e32 v106, v248, v7
	v_max_u32_e32 v107, v248, v7
	v_cndmask_b32_e64 v248, v107, v106, s[88:89]
	v_xor_b32_e32 v116, 16, v234
	ds_bpermute_b32 v0, v116, v241
	ds_bpermute_b32 v1, v116, v243
	ds_bpermute_b32 v2, v116, v245
	ds_bpermute_b32 v3, v116, v247
	ds_bpermute_b32 v4, v116, v242
	ds_bpermute_b32 v5, v116, v244
	ds_bpermute_b32 v6, v116, v246
	ds_bpermute_b32 v7, v116, v248
	s_waitcnt lgkmcnt(0)
	s_mov_b32 s88, 0xf0f0f0f
	s_mov_b32 s89, 0xf0f0f0f
	v_min_u32_e32 v104, v241, v0
	v_max_u32_e32 v105, v241, v0
	v_cndmask_b32_e64 v241, v105, v104, s[88:89]
	v_min_u32_e32 v106, v243, v1
	v_max_u32_e32 v107, v243, v1
	v_cndmask_b32_e64 v243, v107, v106, s[88:89]
	v_min_u32_e32 v104, v245, v2
	v_max_u32_e32 v105, v245, v2
	v_cndmask_b32_e64 v245, v105, v104, s[88:89]
	v_min_u32_e32 v106, v247, v3
	v_max_u32_e32 v107, v247, v3
	v_cndmask_b32_e64 v247, v107, v106, s[88:89]
	v_min_u32_e32 v104, v242, v4
	v_max_u32_e32 v105, v242, v4
	v_cndmask_b32_e64 v242, v105, v104, s[88:89]
	v_min_u32_e32 v106, v244, v5
	v_max_u32_e32 v107, v244, v5
	v_cndmask_b32_e64 v244, v107, v106, s[88:89]
	v_min_u32_e32 v104, v246, v6
	v_max_u32_e32 v105, v246, v6
	v_cndmask_b32_e64 v246, v105, v104, s[88:89]
	v_min_u32_e32 v106, v248, v7
	v_max_u32_e32 v107, v248, v7
	v_cndmask_b32_e64 v248, v107, v106, s[88:89]
	v_xor_b32_e32 v116, 8, v234
	ds_bpermute_b32 v0, v116, v241
	ds_bpermute_b32 v1, v116, v243
	ds_bpermute_b32 v2, v116, v245
	ds_bpermute_b32 v3, v116, v247
	ds_bpermute_b32 v4, v116, v242
	ds_bpermute_b32 v5, v116, v244
	ds_bpermute_b32 v6, v116, v246
	ds_bpermute_b32 v7, v116, v248
	s_waitcnt lgkmcnt(0)
	s_mov_b32 s88, 0x33333333
	s_mov_b32 s89, 0x33333333
	v_min_u32_e32 v104, v241, v0
	v_max_u32_e32 v105, v241, v0
	v_cndmask_b32_e64 v241, v105, v104, s[88:89]
	v_min_u32_e32 v106, v243, v1
	v_max_u32_e32 v107, v243, v1
	v_cndmask_b32_e64 v243, v107, v106, s[88:89]
	v_min_u32_e32 v104, v245, v2
	v_max_u32_e32 v105, v245, v2
	v_cndmask_b32_e64 v245, v105, v104, s[88:89]
	v_min_u32_e32 v106, v247, v3
	v_max_u32_e32 v107, v247, v3
	v_cndmask_b32_e64 v247, v107, v106, s[88:89]
	v_min_u32_e32 v104, v242, v4
	v_max_u32_e32 v105, v242, v4
	v_cndmask_b32_e64 v242, v105, v104, s[88:89]
	v_min_u32_e32 v106, v244, v5
	v_max_u32_e32 v107, v244, v5
	v_cndmask_b32_e64 v244, v107, v106, s[88:89]
	v_min_u32_e32 v104, v246, v6
	v_max_u32_e32 v105, v246, v6
	v_cndmask_b32_e64 v246, v105, v104, s[88:89]
	v_min_u32_e32 v106, v248, v7
	v_max_u32_e32 v107, v248, v7
	v_cndmask_b32_e64 v248, v107, v106, s[88:89]
	v_xor_b32_e32 v116, 4, v234
	ds_bpermute_b32 v0, v116, v241
	ds_bpermute_b32 v1, v116, v243
	ds_bpermute_b32 v2, v116, v245
	ds_bpermute_b32 v3, v116, v247
	ds_bpermute_b32 v4, v116, v242
	ds_bpermute_b32 v5, v116, v244
	ds_bpermute_b32 v6, v116, v246
	ds_bpermute_b32 v7, v116, v248
	s_waitcnt lgkmcnt(0)
	s_mov_b32 s88, 0x55555555
	s_mov_b32 s89, 0x55555555
	v_min_u32_e32 v104, v241, v0
	v_max_u32_e32 v105, v241, v0
	v_cndmask_b32_e64 v241, v105, v104, s[88:89]
	v_min_u32_e32 v106, v243, v1
	v_max_u32_e32 v107, v243, v1
	v_cndmask_b32_e64 v243, v107, v106, s[88:89]
	v_min_u32_e32 v104, v245, v2
	v_max_u32_e32 v105, v245, v2
	v_cndmask_b32_e64 v245, v105, v104, s[88:89]
	v_min_u32_e32 v106, v247, v3
	v_max_u32_e32 v107, v247, v3
	v_cndmask_b32_e64 v247, v107, v106, s[88:89]
	v_min_u32_e32 v104, v242, v4
	v_max_u32_e32 v105, v242, v4
	v_cndmask_b32_e64 v242, v105, v104, s[88:89]
	v_min_u32_e32 v106, v244, v5
	v_max_u32_e32 v107, v244, v5
	v_cndmask_b32_e64 v244, v107, v106, s[88:89]
	v_min_u32_e32 v104, v246, v6
	v_max_u32_e32 v105, v246, v6
	v_cndmask_b32_e64 v246, v105, v104, s[88:89]
	v_min_u32_e32 v106, v248, v7
	v_max_u32_e32 v107, v248, v7
	v_cndmask_b32_e64 v248, v107, v106, s[88:89]
	v_mov_b32_e32 v117, 0
	s_lshl_b32 s98, s2, 11
	s_add_u32 s98, s98, s101
	v_add_u32_e32 v116, s98, v234
	ds_write_b32 v116, v241 offset:0
	ds_write_b32 v116, v242 offset:256
	ds_write_b32 v116, v243 offset:512
	ds_write_b32 v116, v244 offset:768
	ds_write_b32 v116, v245 offset:1024
	ds_write_b32 v116, v246 offset:1280
	ds_write_b32 v116, v247 offset:1536
	ds_write_b32 v116, v248 offset:1792
	v_add_u32_e32 v118, 0x10000, v116
	ds_write_b32 v118, v117 offset:0
	ds_write_b32 v118, v117 offset:256
	ds_write_b32 v118, v117 offset:512
	ds_write_b32 v118, v117 offset:768
	ds_write_b32 v118, v117 offset:1024
	ds_write_b32 v118, v117 offset:1280
	ds_write_b32 v118, v117 offset:1536
	ds_write_b32 v118, v117 offset:1792
	s_add_u32 s2, s2, 1
	s_cmp_lt_u32 s2, 4
	s_cbranch_scc1 .Lpg1_p0
; #define PG_ISSUE(BUF, TAB, e0_) do { const int isrc_ = ((e0_) < 64) ? myi0 : myi1; \
;       _Pragma("unroll") for (int e = 0; e < 8; ++e) { const int idx_ = __builtin_amdgcn_readlane(isrc_, ((e0_) + e) & 63); \
;         BUF[e] = *(const u32x4*)((TAB) + (size_t)idx_ * 1024 + lane * 16); } } while (0)
; DEV void peer_gather(const Params& P, int l, int m0, const int* idxs, const float* gs) {
;     ...
;     PG_ISSUE(b0, U, 0);
; #pragma nounroll
;     for (int e0 = 0; e0 < 128; e0 += 16) {
;       PG_ISSUE(b1, U, e0 + 8);
;       PG_U8(b0, 0, e0);
;       if (e0 + 16 < 128) PG_ISSUE(b0, U, e0 + 16); else PG_ISSUE(b0, V, 0);
;       PG_U8(b1, 0, e0 + 8);
;     }
	s_waitcnt lgkmcnt(0)
	v_lshrrev_b32_e32 v248, 3, v233
	v_readfirstlane_b32 s82, v122
	v_readfirstlane_b32 s83, v123
	s_nop 4
	v_readfirstlane_b32 s80, v126
	v_readfirstlane_b32 s81, v127
	s_nop 4
	s_mov_b32 s2, 0xffffff80
	s_mov_b32 s86, 0xcccccccc
	s_mov_b32 s87, 0xcccccccc
	s_mov_b32 s88, 0xaaaaaaaa
	s_mov_b32 s89, 0xaaaaaaaa
	s_mov_b32 s90, 0xf0f0f0f0
	s_mov_b32 s91, 0xf0f0f0f0
	s_lshl_b32 vcc_lo, s3, 11
	s_add_u32 s82, s82, vcc_lo
	s_addc_u32 s83, s83, 0
	v_add_u32_e32 v246, s101, v234
	v_add_u32_e32 v247, 0x10000, v246
	s_mov_b32 s100, 0
	s_mov_b32 s98, 0
	s_mov_b32 s99, 0
	s_lshl3_add_u32 vcc_lo, s98, s99
	v_lshl_add_u32 v119, vcc_lo, 8, v236
	global_load_dwordx4 v[80:83], v119, s[82:83]
	global_load_dwordx4 v[84:87], v119, s[82:83] offset:16
	v_lshl_add_u32 v116, s98, 9, v246
	ds_read_b32 v134, v116
	ds_read_b32 v135, v116 offset:256
	v_lshl_or_b32 v240, s99, 21, v235
	s_waitcnt lgkmcnt(0)
	ds_bpermute_b32 v142, v249, v134
	ds_bpermute_b32 v143, v250, v134
	s_waitcnt lgkmcnt(0)
	v_and_or_b32 v142, v142, s2, v240
	v_and_or_b32 v143, v143, s2, v240
	global_load_dwordx4 v[0:3], v142, s[80:81]
	global_load_dwordx4 v[4:7], v143, s[80:81]
	ds_bpermute_b32 v142, v251, v134
	ds_bpermute_b32 v143, v252, v134
	s_waitcnt lgkmcnt(0)
	v_and_or_b32 v142, v142, s2, v240
	v_and_or_b32 v143, v143, s2, v240
	global_load_dwordx4 v[8:11], v142, s[80:81]
	global_load_dwordx4 v[12:15], v143, s[80:81]
	ds_bpermute_b32 v142, v253, v134
	ds_bpermute_b32 v143, v254, v134
	s_waitcnt lgkmcnt(0)
	v_and_or_b32 v142, v142, s2, v240
	v_and_or_b32 v143, v143, s2, v240
	global_load_dwordx4 v[16:19], v142, s[80:81]
	global_load_dwordx4 v[20:23], v143, s[80:81]
	ds_bpermute_b32 v142, v255, v134
	ds_bpermute_b32 v143, v153, v134
	s_waitcnt lgkmcnt(0)
	v_and_or_b32 v142, v142, s2, v240
	v_and_or_b32 v143, v143, s2, v240
	global_load_dwordx4 v[24:27], v142, s[80:81]
	global_load_dwordx4 v[28:31], v143, s[80:81]
	ds_bpermute_b32 v142, v249, v135
	ds_bpermute_b32 v143, v250, v135
	s_waitcnt lgkmcnt(0)
	v_and_or_b32 v142, v142, s2, v240
	v_and_or_b32 v143, v143, s2, v240
	global_load_dwordx4 v[32:35], v142, s[80:81]
	global_load_dwordx4 v[36:39], v143, s[80:81]
	ds_bpermute_b32 v142, v251, v135
	ds_bpermute_b32 v143, v252, v135
	s_waitcnt lgkmcnt(0)
	v_and_or_b32 v142, v142, s2, v240
	v_and_or_b32 v143, v143, s2, v240
	global_load_dwordx4 v[40:43], v142, s[80:81]
	global_load_dwordx4 v[44:47], v143, s[80:81]
	ds_bpermute_b32 v142, v253, v135
	ds_bpermute_b32 v143, v254, v135
	s_waitcnt lgkmcnt(0)
	v_and_or_b32 v142, v142, s2, v240
	v_and_or_b32 v143, v143, s2, v240
	global_load_dwordx4 v[48:51], v142, s[80:81]
	global_load_dwordx4 v[52:55], v143, s[80:81]
	ds_bpermute_b32 v142, v255, v135
	ds_bpermute_b32 v143, v153, v135
	s_waitcnt lgkmcnt(0)
	v_and_or_b32 v142, v142, s2, v240
	v_and_or_b32 v143, v143, s2, v240
	global_load_dwordx4 v[56:59], v142, s[80:81]
	global_load_dwordx4 v[60:63], v143, s[80:81]
	s_mov_b32 s92, 1
	v_lshl_add_u32 v116, s92, 9, v246
	ds_read_b32 v134, v116
	ds_read_b32 v135, v116 offset:256

.Lpg1_act:
	v_readlane_b32 s82, v232, 1
	v_readlane_b32 s83, v232, 2
	s_nop 4
	s_lshl_b32 s98, s2, 11
	s_add_u32 s98, s98, s101
	v_add_u32_e32 v116, s98, v234
	v_add_u32_e32 v117, 0x10000, v116
	ds_read_b32 v0, v116 offset:0
	ds_read_b32 v8, v117 offset:0
	ds_read_b32 v1, v116 offset:256
	ds_read_b32 v9, v117 offset:256
	ds_read_b32 v2, v116 offset:512
	ds_read_b32 v10, v117 offset:512
	ds_read_b32 v3, v116 offset:768
	ds_read_b32 v11, v117 offset:768
	ds_read_b32 v4, v116 offset:1024
	ds_read_b32 v12, v117 offset:1024
	ds_read_b32 v5, v116 offset:1280
	ds_read_b32 v13, v117 offset:1280
	ds_read_b32 v6, v116 offset:1536
	ds_read_b32 v14, v117 offset:1536
	ds_read_b32 v7, v116 offset:1792
	ds_read_b32 v15, v117 offset:1792
	s_waitcnt lgkmcnt(0)
	s_lshl_b32 s99, s2, 2
	s_add_u32 s99, s99, s33
	s_add_u32 s99, s99, 0
	s_lshl_b32 s99, s99, 9
	v_and_b32_e32 v0, 0x7f, v0
	v_lshl_add_u32 v0, v0, 2, s99
	global_load_dword v16, v0, s[82:83]
	v_and_b32_e32 v1, 0x7f, v1
	v_lshl_add_u32 v1, v1, 2, s99
	global_load_dword v17, v1, s[82:83]
	s_lshl_b32 s99, s2, 2
	s_add_u32 s99, s99, s33
	s_add_u32 s99, s99, 1
	s_lshl_b32 s99, s99, 9
	v_and_b32_e32 v2, 0x7f, v2
	v_lshl_add_u32 v2, v2, 2, s99
	global_load_dword v18, v2, s[82:83]
	v_and_b32_e32 v3, 0x7f, v3
	v_lshl_add_u32 v3, v3, 2, s99
	global_load_dword v19, v3, s[82:83]
	s_lshl_b32 s99, s2, 2
	s_add_u32 s99, s99, s33
	s_add_u32 s99, s99, 2
	s_lshl_b32 s99, s99, 9
	v_and_b32_e32 v4, 0x7f, v4
	v_lshl_add_u32 v4, v4, 2, s99
	global_load_dword v20, v4, s[82:83]
	v_and_b32_e32 v5, 0x7f, v5
	v_lshl_add_u32 v5, v5, 2, s99
	global_load_dword v21, v5, s[82:83]
	s_lshl_b32 s99, s2, 2
	s_add_u32 s99, s99, s33
	s_add_u32 s99, s99, 3
	s_lshl_b32 s99, s99, 9
	v_and_b32_e32 v6, 0x7f, v6
	v_lshl_add_u32 v6, v6, 2, s99
	global_load_dword v22, v6, s[82:83]
	v_and_b32_e32 v7, 0x7f, v7
	v_lshl_add_u32 v7, v7, 2, s99
	global_load_dword v23, v7, s[82:83]
	v_mul_f32_e32 v8, 0x3c800000, v8
	v_mul_f32_e32 v9, 0x3c800000, v9
	v_mul_f32_e32 v10, 0x3c800000, v10
	v_mul_f32_e32 v11, 0x3c800000, v11
	v_mul_f32_e32 v12, 0x3c800000, v12
	v_mul_f32_e32 v13, 0x3c800000, v13
	v_mul_f32_e32 v14, 0x3c800000, v14
	v_mul_f32_e32 v15, 0x3c800000, v15
	v_mul_f32_e32 v24, 0x3d372713, v8
	v_mul_f32_e32 v25, 0x3d372713, v9
	v_mul_f32_e32 v26, 0x3d372713, v10
	v_mul_f32_e32 v27, 0x3d372713, v11
	v_mul_f32_e32 v28, 0x3d372713, v12
	v_mul_f32_e32 v29, 0x3d372713, v13
	v_mul_f32_e32 v30, 0x3d372713, v14
	v_mul_f32_e32 v31, 0x3d372713, v15
	v_mul_f32_e32 v24, v8, v24
	v_mul_f32_e32 v25, v9, v25
	v_mul_f32_e32 v26, v10, v26
	v_mul_f32_e32 v27, v11, v27
	v_mul_f32_e32 v28, v12, v28
	v_mul_f32_e32 v29, v13, v29
	v_mul_f32_e32 v30, v14, v30
	v_mul_f32_e32 v31, v15, v31
	v_fma_f32 v24, v8, v24, v8
	v_fma_f32 v25, v9, v25, v9
	v_fma_f32 v26, v10, v26, v10
	v_fma_f32 v27, v11, v27, v11
	v_fma_f32 v28, v12, v28, v12
	v_fma_f32 v29, v13, v29, v13
	v_fma_f32 v30, v14, v30, v14
	v_fma_f32 v31, v15, v31, v15
	v_mul_f32_e32 v24, 0xbfcc422a, v24
	v_mul_f32_e32 v25, 0xbfcc422a, v25
	v_mul_f32_e32 v26, 0xbfcc422a, v26
	v_mul_f32_e32 v27, 0xbfcc422a, v27
	v_mul_f32_e32 v28, 0xbfcc422a, v28
	v_mul_f32_e32 v29, 0xbfcc422a, v29
	v_mul_f32_e32 v30, 0xbfcc422a, v30
	v_mul_f32_e32 v31, 0xbfcc422a, v31
	v_mul_f32_e32 v24, 0x3fb8aa3b, v24
	v_mul_f32_e32 v25, 0x3fb8aa3b, v25
	v_mul_f32_e32 v26, 0x3fb8aa3b, v26
	v_mul_f32_e32 v27, 0x3fb8aa3b, v27
	v_mul_f32_e32 v28, 0x3fb8aa3b, v28
	v_mul_f32_e32 v29, 0x3fb8aa3b, v29
	v_mul_f32_e32 v30, 0x3fb8aa3b, v30
	v_mul_f32_e32 v31, 0x3fb8aa3b, v31
	v_exp_f32_e32 v24, v24
	v_exp_f32_e32 v25, v25
	v_exp_f32_e32 v26, v26
	v_exp_f32_e32 v27, v27
	v_exp_f32_e32 v28, v28
	v_exp_f32_e32 v29, v29
	v_exp_f32_e32 v30, v30
	v_exp_f32_e32 v31, v31
	s_nop 0
	v_add_f32_e32 v24, 1.0, v24
	v_add_f32_e32 v25, 1.0, v25
	v_add_f32_e32 v26, 1.0, v26
	v_add_f32_e32 v27, 1.0, v27
	v_add_f32_e32 v28, 1.0, v28
	v_add_f32_e32 v29, 1.0, v29
	v_add_f32_e32 v30, 1.0, v30
	v_add_f32_e32 v31, 1.0, v31
	v_rcp_f32_e32 v24, v24
	v_rcp_f32_e32 v25, v25
	v_rcp_f32_e32 v26, v26
	v_rcp_f32_e32 v27, v27
	v_rcp_f32_e32 v28, v28
	v_rcp_f32_e32 v29, v29
	v_rcp_f32_e32 v30, v30
	v_rcp_f32_e32 v31, v31
	s_nop 0
	v_mul_f32_e32 v24, v8, v24
	v_mul_f32_e32 v25, v9, v25
	v_mul_f32_e32 v26, v10, v26
	v_mul_f32_e32 v27, v11, v27
	v_mul_f32_e32 v28, v12, v28
	v_mul_f32_e32 v29, v13, v29
	v_mul_f32_e32 v30, v14, v30
	v_mul_f32_e32 v31, v15, v31
	s_waitcnt vmcnt(0)
	v_mul_f32_e32 v24, v24, v16
	ds_write_b32 v117, v24 offset:0
	v_mul_f32_e32 v25, v25, v17
	ds_write_b32 v117, v25 offset:256
	v_mul_f32_e32 v26, v26, v18
	ds_write_b32 v117, v26 offset:512
	v_mul_f32_e32 v27, v27, v19
	ds_write_b32 v117, v27 offset:768
	v_mul_f32_e32 v28, v28, v20
	ds_write_b32 v117, v28 offset:1024
	v_mul_f32_e32 v29, v29, v21
	ds_write_b32 v117, v29 offset:1280
	v_mul_f32_e32 v30, v30, v22
	ds_write_b32 v117, v30 offset:1536
	v_mul_f32_e32 v31, v31, v23
	ds_write_b32 v117, v31 offset:1792
	s_add_u32 s2, s2, 1
	s_cmp_lt_u32 s2, 4
	s_cbranch_scc1 .Lpg1_act
; #define PG_ISSUE(BUF, TAB, e0_) do { const int isrc_ = ((e0_) < 64) ? myi0 : myi1; \
;       _Pragma("unroll") for (int e = 0; e < 8; ++e) { const int idx_ = __builtin_amdgcn_readlane(isrc_, ((e0_) + e) & 63); \
;         BUF[e] = *(const u32x4*)((TAB) + (size_t)idx_ * 1024 + lane * 16); } } while (0)
; DEV void peer_gather(const Params& P, int l, int m0, const int* idxs, const float* gs) {
;     ...
;     PG_ISSUE(b0, U, 0);
; #pragma nounroll
;     for (int e0 = 0; e0 < 128; e0 += 16) {
;       PG_ISSUE(b1, U, e0 + 8);
;       PG_U8(b0, 0, e0);
;       if (e0 + 16 < 128) PG_ISSUE(b0, U, e0 + 16); else PG_ISSUE(b0, V, 0);
;       PG_U8(b1, 0, e0 + 8);
;     }
;     float* hrow = P.out + tok * DM + lane * 16;
;     f32x4 hv[4];
; #pragma unroll
;     for (int q = 0; q < 4; ++q) hv[q] = *(const f32x4*)(hrow + 4 * q);
;     if (i + 1 < 16) {
;       const int tn = tt + 1;
;       nxa = *(const u32x4*)(hn + (size_t)(m0 + tn) * DM + lane * 16); nxb = *(const u32x4*)(hn + (size_t)(m0 + tn) * DM + lane * 16 + 8);
;       ni0 = idxs[tn * 128 + lane]; ni1 = idxs[tn * 128 + 64 + lane]; ng0 = gs[tn * 128 + lane]; ng1 = gs[tn * 128 + 64 + lane];
;     }
; #pragma nounroll
;     for (int e0 = 0; e0 < 128; e0 += 16) {
;       PG_ISSUE(b1, V, e0 + 8);
;       if (e0 == 64 && i + 1 < 16) sort_lists(lane, ni0, ni1, ng0, ng1);
;       PG_V16(b0, e0);
;       if (e0 + 16 < 128) PG_ISSUE(b0, V, e0 + 16);
	s_waitcnt lgkmcnt(0)
	v_add_u32_e32 v249, 0, v237
	v_add_u32_e32 v250, 32, v237
	v_add_u32_e32 v251, 64, v237
	v_add_u32_e32 v252, 96, v237
	v_add_u32_e32 v253, 128, v237
	v_add_u32_e32 v254, 160, v237
	v_add_u32_e32 v255, 192, v237
	v_add_u32_e32 v153, 224, v237
	v_readfirstlane_b32 s80, v128
	v_readfirstlane_b32 s81, v129
	s_nop 4
	v_add_u32_e32 v246, s101, v234
	v_add_u32_e32 v247, 0x10000, v246
	v_readfirstlane_b32 s82, v132
	v_readfirstlane_b32 s83, v133
	s_nop 4
	s_mov_b32 s2, 0xffffff80
	s_lshl_b32 vcc_lo, s3, 12
	s_add_u32 s82, s82, vcc_lo
	s_addc_u32 s83, s83, 0
	s_mov_b32 s88, 0xff00ff00
	s_mov_b32 s89, 0xff00ff00
	s_mov_b32 s100, 0
	s_mov_b32 s98, 0
	s_mov_b32 s99, 0
	v_lshl_add_u32 v116, s98, 9, v246
	ds_read_b32 v134, v116
	ds_read_b32 v135, v116 offset:256
	v_lshl_or_b32 v240, s99, 21, v235
	s_waitcnt lgkmcnt(0)
	ds_bpermute_b32 v142, v249, v134
	ds_bpermute_b32 v143, v250, v134
	s_waitcnt lgkmcnt(0)
	v_and_or_b32 v142, v142, s2, v240
	v_and_or_b32 v143, v143, s2, v240
	global_load_dwordx4 v[0:3], v142, s[80:81]
	global_load_dwordx4 v[4:7], v143, s[80:81]
	ds_bpermute_b32 v142, v251, v134
	ds_bpermute_b32 v143, v252, v134
	s_waitcnt lgkmcnt(0)
	v_and_or_b32 v142, v142, s2, v240
	v_and_or_b32 v143, v143, s2, v240
	global_load_dwordx4 v[8:11], v142, s[80:81]
	global_load_dwordx4 v[12:15], v143, s[80:81]
	ds_bpermute_b32 v142, v253, v134
	ds_bpermute_b32 v143, v254, v134
	s_waitcnt lgkmcnt(0)
	v_and_or_b32 v142, v142, s2, v240
	v_and_or_b32 v143, v143, s2, v240
	global_load_dwordx4 v[16:19], v142, s[80:81]
	global_load_dwordx4 v[20:23], v143, s[80:81]
	ds_bpermute_b32 v142, v255, v134
	ds_bpermute_b32 v143, v153, v134
	s_waitcnt lgkmcnt(0)
	v_and_or_b32 v142, v142, s2, v240
	v_and_or_b32 v143, v143, s2, v240
	global_load_dwordx4 v[24:27], v142, s[80:81]
	global_load_dwordx4 v[28:31], v143, s[80:81]
	ds_bpermute_b32 v142, v249, v135
	ds_bpermute_b32 v143, v250, v135
	s_waitcnt lgkmcnt(0)
	v_and_or_b32 v142, v142, s2, v240
	v_and_or_b32 v143, v143, s2, v240
	global_load_dwordx4 v[32:35], v142, s[80:81]
	global_load_dwordx4 v[36:39], v143, s[80:81]
	ds_bpermute_b32 v142, v251, v135
	ds_bpermute_b32 v143, v252, v135
	s_waitcnt lgkmcnt(0)
	v_and_or_b32 v142, v142, s2, v240
	v_and_or_b32 v143, v143, s2, v240
	global_load_dwordx4 v[40:43], v142, s[80:81]
	global_load_dwordx4 v[44:47], v143, s[80:81]
	ds_bpermute_b32 v142, v253, v135
	ds_bpermute_b32 v143, v254, v135
	s_waitcnt lgkmcnt(0)
	v_and_or_b32 v142, v142, s2, v240
	v_and_or_b32 v143, v143, s2, v240
	global_load_dwordx4 v[48:51], v142, s[80:81]
	global_load_dwordx4 v[52:55], v143, s[80:81]
	ds_bpermute_b32 v142, v255, v135
	ds_bpermute_b32 v143, v153, v135
	s_waitcnt lgkmcnt(0)
	v_and_or_b32 v142, v142, s2, v240
	v_and_or_b32 v143, v143, s2, v240
	global_load_dwordx4 v[56:59], v142, s[80:81]
	global_load_dwordx4 v[60:63], v143, s[80:81]
	s_mov_b32 s92, 1
	v_lshl_add_u32 v116, s92, 9, v246
	ds_read_b32 v134, v116
	ds_read_b32 v135, v116 offset:256
	v_lshl_add_u32 v117, s98, 9, v247
	ds_read_b32 v136, v117
	ds_read_b32 v137, v117 offset:256
	s_waitcnt vmcnt(0)
